# v7 plus DPP quad_perm instead of ds_bpermute for the lane-pair exchange in the attention and gating store epilogues
# baseline (speedup 1.0000x reference)
; __device__ __forceinline__ float bf2f(unsigned short h) { return __uint_as_float(((unsigned)h) << 16); }
; __device__ __forceinline__ unsigned cvtpk(float lo, float hi) { unsigned r; asm volatile("v_cvt_pk_bf16_f32 %0, %1, %2" : "=v"(r) : "v"(lo), "v"(hi)); return r; }
; __device__ __forceinline__ int crow(int r, int hi) { return (r & 3) + 8 * (r >> 2) + 4 * hi; }
; __device__ __forceinline__ float gelu_tanh(float x) {
;     const float y = 0.7978845608028654f * (x + 0.044715f * x * x * x);
;     const float e = __builtin_amdgcn_exp2f(-2.0f * LOG2E * y);
;     return x * __builtin_amdgcn_rcpf(1.0f + e);
; }
; __device__ __forceinline__ void ph_misc(const Args& a, char* lds, int l) {
;     ...
;             for (int r = 0; r < 16; ++r) { const int t = 32 * tb + crow(r, hi), c = 32 * (cb0 + ci) + r32; const size_t row = row0 + t;
;                 const float uval = gelu_tanh(bf2f(P[row * NIN + PC_U + g * 128 + c])); const float val = uval * (acc[ci][r] + b_s[l * 512 + g * 128 + t]);
;                 const float vn = __shfl_xor(val, 1); if ((r32 & 1) == 0) *(unsigned*)(MIX + row * DM + 1024 + g * 128 + c) = cvtpk(val, vn); }
.LBB0_672:
	s_lshl_b64 s[0:1], s[34:35], 7
	v_or_b32_e32 v72, s0, v36
	v_mov_b64_e32 v[74:75], s[16:17]
	v_mad_u64_u32 v[74:75], s[6:7], v72, s83, v[74:75]
	v_mad_i32_i24 v75, s1, v244, v75
	s_lshl_b32 s86, s2, 1
	v_lshl_add_u64 v[74:75], v[74:75], 0, s[86:87]
	v_lshl_add_u64 v[74:75], v[38:39], 1, v[74:75]
	s_movk_i32 s2, 0x1000
	v_add_co_u32_e32 v76, vcc, s2, v74
	v_or_b32_e32 v0, s38, v36
	s_nop 0
	v_addc_co_u32_e32 v77, vcc, 0, v75, vcc
	flat_load_ushort v61, v[76:77] offset:512
	v_lshl_add_u64 v[78:79], v[0:1], 2, s[14:15]
	flat_load_dword v0, v[78:79]
	v_mov_b32_e32 v73, s1
	v_lshlrev_b64 v[72:73], 12, v[72:73]
	v_lshl_add_u64 v[76:77], s[22:23], 0, v[72:73]
	s_waitcnt vmcnt(0) lgkmcnt(0)
	v_lshlrev_b32_e32 v61, 16, v61
	v_mul_f32_e32 v63, 0x3d372713, v61
	v_mul_f32_e32 v63, v63, v61
	v_fma_f32 v63, v63, v61, v61
	v_mul_f32_e32 v63, 0x3f4c422a, v63
	v_mul_f32_e32 v63, 0xc038aa3b, v63
	v_exp_f32_e32 v63, v63
	v_add_f32_e32 v0, v18, v0
	v_add_f32_e32 v63, 1.0, v63
	v_rcp_f32_e32 v63, v63
	s_nop 0
	v_mul_f32_e32 v61, v63, v61
	v_mul_f32_e32 v0, v0, v61
	s_nop 1
	v_mov_b32_dpp v18, v0 quad_perm:[1,0,3,2] row_mask:0xf bank_mask:0xf
	s_and_saveexec_b64 s[6:7], s[4:5]
	s_cbranch_execz .LBB0_674
	v_lshl_add_u64 v[72:73], v[76:77], 0, s[86:87]
	v_lshl_add_u64 v[72:73], v[38:39], 1, v[72:73]
	v_add_co_u32_e32 v72, vcc, 0x271c0000, v72
	s_waitcnt lgkmcnt(0)
	v_cvt_pk_bf16_f32 v0, v0, v18
	s_nop 0
	v_addc_co_u32_e32 v73, vcc, 0, v73, vcc
	flat_store_dword v[72:73], v0 offset:2048
.LBB0_674:
	s_or_b64 exec, exec, s[6:7]
	s_waitcnt lgkmcnt(0)
	v_or_b32_e32 v18, s0, v40
	v_mov_b64_e32 v[72:73], s[16:17]
	v_mad_u64_u32 v[72:73], s[6:7], v18, s83, v[72:73]
	v_mad_i32_i24 v73, s1, v244, v73
	v_lshl_add_u64 v[72:73], v[72:73], 0, s[86:87]
	v_lshl_add_u64 v[80:81], v[38:39], 1, v[72:73]
	v_add_co_u32_e32 v72, vcc, s2, v80
	v_add_u32_e32 v0, s38, v36
	s_nop 0
	v_addc_co_u32_e32 v73, vcc, 0, v81, vcc
	flat_load_ushort v61, v[72:73] offset:512
	v_lshl_add_u64 v[72:73], v[0:1], 2, s[14:15]
	flat_load_dword v0, v[72:73] offset:4
	s_waitcnt vmcnt(0) lgkmcnt(0)
	v_lshlrev_b32_e32 v61, 16, v61
	v_mul_f32_e32 v63, 0x3d372713, v61
	v_mul_f32_e32 v63, v63, v61
	v_fma_f32 v63, v63, v61, v61
	v_mul_f32_e32 v63, 0x3f4c422a, v63
	v_mul_f32_e32 v63, 0xc038aa3b, v63
	v_exp_f32_e32 v63, v63
	v_add_f32_e32 v0, v19, v0
	v_mov_b32_e32 v19, s1
	v_lshlrev_b64 v[18:19], 12, v[18:19]
	v_add_f32_e32 v63, 1.0, v63
	v_rcp_f32_e32 v63, v63
	v_lshl_add_u64 v[18:19], s[22:23], 0, v[18:19]
	v_mul_f32_e32 v61, v63, v61
	v_mul_f32_e32 v0, v0, v61
	s_nop 1
	v_mov_b32_dpp v61, v0 quad_perm:[1,0,3,2] row_mask:0xf bank_mask:0xf
	s_and_saveexec_b64 s[6:7], s[4:5]
	s_cbranch_execz .LBB0_676
	v_lshl_add_u64 v[82:83], v[18:19], 0, s[86:87]
	v_lshl_add_u64 v[82:83], v[38:39], 1, v[82:83]
	v_add_co_u32_e32 v82, vcc, 0x271c0000, v82
	s_waitcnt lgkmcnt(0)
	v_cvt_pk_bf16_f32 v0, v0, v61
	s_nop 0
	v_addc_co_u32_e32 v83, vcc, 0, v83, vcc
	flat_store_dword v[82:83], v0 offset:2048
.LBB0_676:
	s_or_b64 exec, exec, s[6:7]
	v_or_b32_e32 v84, s0, v42
	v_mov_b64_e32 v[82:83], s[16:17]
	v_mad_u64_u32 v[82:83], s[6:7], v84, s83, v[82:83]
	v_mad_i32_i24 v83, s1, v244, v83
	v_lshl_add_u64 v[82:83], v[82:83], 0, s[86:87]
	v_lshl_add_u64 v[82:83], v[38:39], 1, v[82:83]
	v_add_co_u32_e32 v86, vcc, s2, v82
	v_mov_b32_e32 v85, s1
	s_nop 0
	v_addc_co_u32_e32 v87, vcc, 0, v83, vcc
	flat_load_ushort v0, v[86:87] offset:512
	s_waitcnt lgkmcnt(0)
	flat_load_dword v61, v[72:73] offset:8
	v_lshlrev_b64 v[84:85], 12, v[84:85]
	v_lshl_add_u64 v[84:85], s[22:23], 0, v[84:85]
	s_waitcnt vmcnt(0)
	v_lshlrev_b32_e32 v0, 16, v0
	v_mul_f32_e32 v63, 0x3d372713, v0
	v_mul_f32_e32 v63, v63, v0
	v_fma_f32 v63, v63, v0, v0
	v_mul_f32_e32 v63, 0x3f4c422a, v63
	v_mul_f32_e32 v63, 0xc038aa3b, v63
	v_exp_f32_e32 v63, v63
	s_waitcnt lgkmcnt(0)
	v_add_f32_e32 v20, v20, v61
	v_add_f32_e32 v63, 1.0, v63
	v_rcp_f32_e32 v63, v63
	s_nop 0
	v_mul_f32_e32 v0, v63, v0
	v_mul_f32_e32 v0, v20, v0
	s_nop 1
	v_mov_b32_dpp v20, v0 quad_perm:[1,0,3,2] row_mask:0xf bank_mask:0xf
	s_and_saveexec_b64 s[6:7], s[4:5]
	s_cbranch_execz .LBB0_678
	v_lshl_add_u64 v[86:87], v[84:85], 0, s[86:87]
	v_lshl_add_u64 v[86:87], v[38:39], 1, v[86:87]
	v_add_co_u32_e32 v86, vcc, 0x271c0000, v86
	s_waitcnt lgkmcnt(0)
	v_cvt_pk_bf16_f32 v0, v0, v20
	s_nop 0
	v_addc_co_u32_e32 v87, vcc, 0, v87, vcc
	flat_store_dword v[86:87], v0 offset:2048

; __device__ __forceinline__ float bf2f(unsigned short h) { return __uint_as_float(((unsigned)h) << 16); }
; __device__ __forceinline__ unsigned cvtpk(float lo, float hi) { unsigned r; asm volatile("v_cvt_pk_bf16_f32 %0, %1, %2" : "=v"(r) : "v"(lo), "v"(hi)); return r; }
; __device__ __forceinline__ int crow(int r, int hi) { return (r & 3) + 8 * (r >> 2) + 4 * hi; }
; __device__ __forceinline__ float gelu_tanh(float x) {
;     const float y = 0.7978845608028654f * (x + 0.044715f * x * x * x);
;     const float e = __builtin_amdgcn_exp2f(-2.0f * LOG2E * y);
;     return x * __builtin_amdgcn_rcpf(1.0f + e);
; }
; __device__ __forceinline__ void ph_misc(const Args& a, char* lds, int l) {
;     ...
;             for (int r = 0; r < 16; ++r) { const int t = 32 * tb + crow(r, hi), c = 32 * (cb0 + ci) + r32; const size_t row = row0 + t;
;                 const float uval = gelu_tanh(bf2f(P[row * NIN + PC_U + g * 128 + c])); const float val = uval * (acc[ci][r] + b_s[l * 512 + g * 128 + t]);
;                 const float vn = __shfl_xor(val, 1); if ((r32 & 1) == 0) *(unsigned*)(MIX + row * DM + 1024 + g * 128 + c) = cvtpk(val, vn); }
.LBB0_680:
	s_or_b64 exec, exec, s[6:7]
	v_or_b32_e32 v90, s0, v46
	v_mov_b64_e32 v[88:89], s[16:17]
	v_mad_u64_u32 v[88:89], s[6:7], v90, s83, v[88:89]
	v_mad_i32_i24 v89, s1, v244, v89
	v_lshl_add_u64 v[88:89], v[88:89], 0, s[86:87]
	v_lshl_add_u64 v[88:89], v[38:39], 1, v[88:89]
	v_add_co_u32_e32 v92, vcc, s2, v88
	v_mov_b32_e32 v91, s1
	s_nop 0
	v_addc_co_u32_e32 v93, vcc, 0, v89, vcc
	flat_load_ushort v0, v[92:93] offset:512
	s_waitcnt lgkmcnt(0)
	flat_load_dword v61, v[72:73] offset:32
	v_lshlrev_b64 v[90:91], 12, v[90:91]
	v_lshl_add_u64 v[90:91], s[22:23], 0, v[90:91]
	s_waitcnt vmcnt(0)
	v_lshlrev_b32_e32 v0, 16, v0
	v_mul_f32_e32 v63, 0x3d372713, v0
	v_mul_f32_e32 v63, v63, v0
	v_fma_f32 v63, v63, v0, v0
	v_mul_f32_e32 v63, 0x3f4c422a, v63
	v_mul_f32_e32 v63, 0xc038aa3b, v63
	v_exp_f32_e32 v63, v63
	s_waitcnt lgkmcnt(0)
	v_add_f32_e32 v22, v22, v61
	v_add_f32_e32 v63, 1.0, v63
	v_rcp_f32_e32 v63, v63
	s_nop 0
	v_mul_f32_e32 v0, v63, v0
	v_mul_f32_e32 v0, v22, v0
	s_nop 1
	v_mov_b32_dpp v22, v0 quad_perm:[1,0,3,2] row_mask:0xf bank_mask:0xf
	s_and_saveexec_b64 s[6:7], s[4:5]
	s_cbranch_execz .LBB0_682
	v_lshl_add_u64 v[92:93], v[90:91], 0, s[86:87]
	v_lshl_add_u64 v[92:93], v[38:39], 1, v[92:93]
	v_add_co_u32_e32 v92, vcc, 0x271c0000, v92
	s_waitcnt lgkmcnt(0)
	v_cvt_pk_bf16_f32 v0, v0, v22
	s_nop 0
	v_addc_co_u32_e32 v93, vcc, 0, v93, vcc
	flat_store_dword v[92:93], v0 offset:2048

; __device__ __forceinline__ float bf2f(unsigned short h) { return __uint_as_float(((unsigned)h) << 16); }
; __device__ __forceinline__ unsigned cvtpk(float lo, float hi) { unsigned r; asm volatile("v_cvt_pk_bf16_f32 %0, %1, %2" : "=v"(r) : "v"(lo), "v"(hi)); return r; }
; __device__ __forceinline__ int crow(int r, int hi) { return (r & 3) + 8 * (r >> 2) + 4 * hi; }
; __device__ __forceinline__ float gelu_tanh(float x) {
;     const float y = 0.7978845608028654f * (x + 0.044715f * x * x * x);
;     const float e = __builtin_amdgcn_exp2f(-2.0f * LOG2E * y);
;     return x * __builtin_amdgcn_rcpf(1.0f + e);
; }
; __device__ __forceinline__ void ph_misc(const Args& a, char* lds, int l) {
;     ...
;             for (int r = 0; r < 16; ++r) { const int t = 32 * tb + crow(r, hi), c = 32 * (cb0 + ci) + r32; const size_t row = row0 + t;
;                 const float uval = gelu_tanh(bf2f(P[row * NIN + PC_U + g * 128 + c])); const float val = uval * (acc[ci][r] + b_s[l * 512 + g * 128 + t]);
;                 const float vn = __shfl_xor(val, 1); if ((r32 & 1) == 0) *(unsigned*)(MIX + row * DM + 1024 + g * 128 + c) = cvtpk(val, vn); }
.LBB0_684:
	s_or_b64 exec, exec, s[6:7]
	v_or_b32_e32 v96, s0, v50
	v_mov_b64_e32 v[94:95], s[16:17]
	v_mad_u64_u32 v[94:95], s[6:7], v96, s83, v[94:95]
	v_mad_i32_i24 v95, s1, v244, v95
	v_lshl_add_u64 v[94:95], v[94:95], 0, s[86:87]
	v_lshl_add_u64 v[94:95], v[38:39], 1, v[94:95]
	v_add_co_u32_e32 v98, vcc, s2, v94
	v_mov_b32_e32 v97, s1
	s_nop 0
	v_addc_co_u32_e32 v99, vcc, 0, v95, vcc
	flat_load_ushort v0, v[98:99] offset:512
	s_waitcnt lgkmcnt(0)
	flat_load_dword v61, v[72:73] offset:40
	v_lshlrev_b64 v[96:97], 12, v[96:97]
	v_lshl_add_u64 v[96:97], s[22:23], 0, v[96:97]
	s_waitcnt vmcnt(0)
	v_lshlrev_b32_e32 v0, 16, v0
	v_mul_f32_e32 v63, 0x3d372713, v0
	v_mul_f32_e32 v63, v63, v0
	v_fma_f32 v63, v63, v0, v0
	v_mul_f32_e32 v63, 0x3f4c422a, v63
	v_mul_f32_e32 v63, 0xc038aa3b, v63
	v_exp_f32_e32 v63, v63
	s_waitcnt lgkmcnt(0)
	v_add_f32_e32 v24, v24, v61
	v_add_f32_e32 v63, 1.0, v63
	v_rcp_f32_e32 v63, v63
	s_nop 0
	v_mul_f32_e32 v0, v63, v0
	v_mul_f32_e32 v0, v24, v0
	s_nop 1
	v_mov_b32_dpp v24, v0 quad_perm:[1,0,3,2] row_mask:0xf bank_mask:0xf
	s_and_saveexec_b64 s[6:7], s[4:5]
	s_cbranch_execz .LBB0_686
	v_lshl_add_u64 v[98:99], v[96:97], 0, s[86:87]
	v_lshl_add_u64 v[98:99], v[38:39], 1, v[98:99]
	v_add_co_u32_e32 v98, vcc, 0x271c0000, v98
	s_waitcnt lgkmcnt(0)
	v_cvt_pk_bf16_f32 v0, v0, v24
	s_nop 0
	v_addc_co_u32_e32 v99, vcc, 0, v99, vcc
	flat_store_dword v[98:99], v0 offset:2048

; __device__ __forceinline__ float bf2f(unsigned short h) { return __uint_as_float(((unsigned)h) << 16); }
; __device__ __forceinline__ unsigned cvtpk(float lo, float hi) { unsigned r; asm volatile("v_cvt_pk_bf16_f32 %0, %1, %2" : "=v"(r) : "v"(lo), "v"(hi)); return r; }
; __device__ __forceinline__ int crow(int r, int hi) { return (r & 3) + 8 * (r >> 2) + 4 * hi; }
; __device__ __forceinline__ float gelu_tanh(float x) {
;     const float y = 0.7978845608028654f * (x + 0.044715f * x * x * x);
;     const float e = __builtin_amdgcn_exp2f(-2.0f * LOG2E * y);
;     return x * __builtin_amdgcn_rcpf(1.0f + e);
; }
; __device__ __forceinline__ void ph_misc(const Args& a, char* lds, int l) {
;     ...
;             for (int r = 0; r < 16; ++r) { const int t = 32 * tb + crow(r, hi), c = 32 * (cb0 + ci) + r32; const size_t row = row0 + t;
;                 const float uval = gelu_tanh(bf2f(P[row * NIN + PC_U + g * 128 + c])); const float val = uval * (acc[ci][r] + b_s[l * 512 + g * 128 + t]);
;                 const float vn = __shfl_xor(val, 1); if ((r32 & 1) == 0) *(unsigned*)(MIX + row * DM + 1024 + g * 128 + c) = cvtpk(val, vn); }
.LBB0_688:
	s_or_b64 exec, exec, s[6:7]
	v_or_b32_e32 v102, s0, v54
	v_mov_b64_e32 v[100:101], s[16:17]
	v_mad_u64_u32 v[100:101], s[6:7], v102, s83, v[100:101]
	v_mad_i32_i24 v101, s1, v244, v101
	v_lshl_add_u64 v[100:101], v[100:101], 0, s[86:87]
	v_lshl_add_u64 v[100:101], v[38:39], 1, v[100:101]
	v_add_co_u32_e32 v104, vcc, s2, v100
	v_mov_b32_e32 v103, s1
	s_nop 0
	v_addc_co_u32_e32 v105, vcc, 0, v101, vcc
	flat_load_ushort v0, v[104:105] offset:512
	s_waitcnt lgkmcnt(0)
	flat_load_dword v61, v[72:73] offset:64
	v_lshlrev_b64 v[102:103], 12, v[102:103]
	v_lshl_add_u64 v[102:103], s[22:23], 0, v[102:103]
	s_waitcnt vmcnt(0)
	v_lshlrev_b32_e32 v0, 16, v0
	v_mul_f32_e32 v63, 0x3d372713, v0
	v_mul_f32_e32 v63, v63, v0
	v_fma_f32 v63, v63, v0, v0
	v_mul_f32_e32 v63, 0x3f4c422a, v63
	v_mul_f32_e32 v63, 0xc038aa3b, v63
	v_exp_f32_e32 v63, v63
	s_waitcnt lgkmcnt(0)
	v_add_f32_e32 v26, v26, v61
	v_add_f32_e32 v63, 1.0, v63
	v_rcp_f32_e32 v63, v63
	s_nop 0
	v_mul_f32_e32 v0, v63, v0
	v_mul_f32_e32 v0, v26, v0
	s_nop 1
	v_mov_b32_dpp v26, v0 quad_perm:[1,0,3,2] row_mask:0xf bank_mask:0xf
	s_and_saveexec_b64 s[6:7], s[4:5]
	s_cbranch_execz .LBB0_690
	v_lshl_add_u64 v[104:105], v[102:103], 0, s[86:87]
	v_lshl_add_u64 v[104:105], v[38:39], 1, v[104:105]
	v_add_co_u32_e32 v104, vcc, 0x271c0000, v104
	s_waitcnt lgkmcnt(0)
	v_cvt_pk_bf16_f32 v0, v0, v26
	s_nop 0
	v_addc_co_u32_e32 v105, vcc, 0, v105, vcc
	flat_store_dword v[104:105], v0 offset:2048

; __device__ __forceinline__ float bf2f(unsigned short h) { return __uint_as_float(((unsigned)h) << 16); }
; __device__ __forceinline__ unsigned cvtpk(float lo, float hi) { unsigned r; asm volatile("v_cvt_pk_bf16_f32 %0, %1, %2" : "=v"(r) : "v"(lo), "v"(hi)); return r; }
; __device__ __forceinline__ int crow(int r, int hi) { return (r & 3) + 8 * (r >> 2) + 4 * hi; }
; __device__ __forceinline__ float gelu_tanh(float x) {
;     const float y = 0.7978845608028654f * (x + 0.044715f * x * x * x);
;     const float e = __builtin_amdgcn_exp2f(-2.0f * LOG2E * y);
;     return x * __builtin_amdgcn_rcpf(1.0f + e);
; }
; __device__ __forceinline__ void ph_misc(const Args& a, char* lds, int l) {
;     ...
;             for (int r = 0; r < 16; ++r) { const int t = 32 * tb + crow(r, hi), c = 32 * (cb0 + ci) + r32; const size_t row = row0 + t;
;                 const float uval = gelu_tanh(bf2f(P[row * NIN + PC_U + g * 128 + c])); const float val = uval * (acc[ci][r] + b_s[l * 512 + g * 128 + t]);
;                 const float vn = __shfl_xor(val, 1); if ((r32 & 1) == 0) *(unsigned*)(MIX + row * DM + 1024 + g * 128 + c) = cvtpk(val, vn); }
.LBB0_692:
	s_or_b64 exec, exec, s[6:7]
	v_or_b32_e32 v108, s0, v58
	v_mov_b64_e32 v[106:107], s[16:17]
	v_mad_u64_u32 v[106:107], s[6:7], v108, s83, v[106:107]
	v_mad_i32_i24 v107, s1, v244, v107
	v_lshl_add_u64 v[106:107], v[106:107], 0, s[86:87]
	v_lshl_add_u64 v[106:107], v[38:39], 1, v[106:107]
	v_add_co_u32_e32 v110, vcc, s2, v106
	v_mov_b32_e32 v109, s1
	s_nop 0
	v_addc_co_u32_e32 v111, vcc, 0, v107, vcc
	flat_load_ushort v0, v[110:111] offset:512
	s_waitcnt lgkmcnt(0)
	flat_load_dword v61, v[72:73] offset:72
	v_lshlrev_b64 v[108:109], 12, v[108:109]
	v_lshl_add_u64 v[108:109], s[22:23], 0, v[108:109]
	s_waitcnt vmcnt(0)
	v_lshlrev_b32_e32 v0, 16, v0
	v_mul_f32_e32 v63, 0x3d372713, v0
	v_mul_f32_e32 v63, v63, v0
	v_fma_f32 v63, v63, v0, v0
	v_mul_f32_e32 v63, 0x3f4c422a, v63
	v_mul_f32_e32 v63, 0xc038aa3b, v63
	v_exp_f32_e32 v63, v63
	s_waitcnt lgkmcnt(0)
	v_add_f32_e32 v28, v28, v61
	v_add_f32_e32 v63, 1.0, v63
	v_rcp_f32_e32 v63, v63
	s_nop 0
	v_mul_f32_e32 v0, v63, v0
	v_mul_f32_e32 v0, v28, v0
	s_nop 1
	v_mov_b32_dpp v28, v0 quad_perm:[1,0,3,2] row_mask:0xf bank_mask:0xf
	s_and_saveexec_b64 s[6:7], s[4:5]
	s_cbranch_execz .LBB0_694
	v_lshl_add_u64 v[110:111], v[108:109], 0, s[86:87]
	v_lshl_add_u64 v[110:111], v[38:39], 1, v[110:111]
	v_add_co_u32_e32 v110, vcc, 0x271c0000, v110
	s_waitcnt lgkmcnt(0)
	v_cvt_pk_bf16_f32 v0, v0, v28
	s_nop 0
	v_addc_co_u32_e32 v111, vcc, 0, v111, vcc
	flat_store_dword v[110:111], v0 offset:2048

; __device__ __forceinline__ float bf2f(unsigned short h) { return __uint_as_float(((unsigned)h) << 16); }
; __device__ __forceinline__ unsigned cvtpk(float lo, float hi) { unsigned r; asm volatile("v_cvt_pk_bf16_f32 %0, %1, %2" : "=v"(r) : "v"(lo), "v"(hi)); return r; }
; __device__ __forceinline__ int crow(int r, int hi) { return (r & 3) + 8 * (r >> 2) + 4 * hi; }
; __device__ __forceinline__ float gelu_tanh(float x) {
;     const float y = 0.7978845608028654f * (x + 0.044715f * x * x * x);
;     const float e = __builtin_amdgcn_exp2f(-2.0f * LOG2E * y);
;     return x * __builtin_amdgcn_rcpf(1.0f + e);
; }
; __device__ __forceinline__ void ph_misc(const Args& a, char* lds, int l) {
;     ...
;             for (int r = 0; r < 16; ++r) { const int t = 32 * tb + crow(r, hi), c = 32 * (cb0 + ci) + r32; const size_t row = row0 + t;
;                 const float uval = gelu_tanh(bf2f(P[row * NIN + PC_U + g * 128 + c])); const float val = uval * (acc[ci][r] + b_s[l * 512 + g * 128 + t]);
;                 const float vn = __shfl_xor(val, 1); if ((r32 & 1) == 0) *(unsigned*)(MIX + row * DM + 1024 + g * 128 + c) = cvtpk(val, vn); }
.LBB0_696:
	s_or_b64 exec, exec, s[6:7]
	v_or_b32_e32 v114, s0, v62
	v_mov_b64_e32 v[112:113], s[16:17]
	v_mad_u64_u32 v[112:113], s[6:7], v114, s83, v[112:113]
	v_mad_i32_i24 v113, s1, v244, v113
	v_lshl_add_u64 v[112:113], v[112:113], 0, s[86:87]
	v_lshl_add_u64 v[112:113], v[38:39], 1, v[112:113]
	v_add_co_u32_e32 v116, vcc, s2, v112
	v_mov_b32_e32 v115, s1
	s_nop 0
	v_addc_co_u32_e32 v117, vcc, 0, v113, vcc
	flat_load_ushort v0, v[116:117] offset:512
	s_waitcnt lgkmcnt(0)
	flat_load_dword v61, v[72:73] offset:96
	v_lshlrev_b64 v[114:115], 12, v[114:115]
	v_lshl_add_u64 v[114:115], s[22:23], 0, v[114:115]
	s_waitcnt vmcnt(0)
	v_lshlrev_b32_e32 v0, 16, v0
	v_mul_f32_e32 v63, 0x3d372713, v0
	v_mul_f32_e32 v63, v63, v0
	v_fma_f32 v63, v63, v0, v0
	v_mul_f32_e32 v63, 0x3f4c422a, v63
	v_mul_f32_e32 v63, 0xc038aa3b, v63
	v_exp_f32_e32 v63, v63
	s_waitcnt lgkmcnt(0)
	v_add_f32_e32 v30, v30, v61
	v_add_f32_e32 v63, 1.0, v63
	v_rcp_f32_e32 v63, v63
	s_nop 0
	v_mul_f32_e32 v0, v63, v0
	v_mul_f32_e32 v0, v30, v0
	s_nop 1
	v_mov_b32_dpp v30, v0 quad_perm:[1,0,3,2] row_mask:0xf bank_mask:0xf
	s_and_saveexec_b64 s[6:7], s[4:5]
	s_cbranch_execz .LBB0_698
	v_lshl_add_u64 v[116:117], v[114:115], 0, s[86:87]
	v_lshl_add_u64 v[116:117], v[38:39], 1, v[116:117]
	v_add_co_u32_e32 v116, vcc, 0x271c0000, v116
	s_waitcnt lgkmcnt(0)
	v_cvt_pk_bf16_f32 v0, v0, v30
	s_nop 0
	v_addc_co_u32_e32 v117, vcc, 0, v117, vcc
	flat_store_dword v[116:117], v0 offset:2048

; __device__ __forceinline__ float bf2f(unsigned short h) { return __uint_as_float(((unsigned)h) << 16); }
; __device__ __forceinline__ unsigned cvtpk(float lo, float hi) { unsigned r; asm volatile("v_cvt_pk_bf16_f32 %0, %1, %2" : "=v"(r) : "v"(lo), "v"(hi)); return r; }
; __device__ __forceinline__ int crow(int r, int hi) { return (r & 3) + 8 * (r >> 2) + 4 * hi; }
; __device__ __forceinline__ float gelu_tanh(float x) {
;     const float y = 0.7978845608028654f * (x + 0.044715f * x * x * x);
;     const float e = __builtin_amdgcn_exp2f(-2.0f * LOG2E * y);
;     return x * __builtin_amdgcn_rcpf(1.0f + e);
; }
; __device__ __forceinline__ void ph_misc(const Args& a, char* lds, int l) {
;     ...
;             for (int r = 0; r < 16; ++r) { const int t = 32 * tb + crow(r, hi), c = 32 * (cb0 + ci) + r32; const size_t row = row0 + t;
;                 const float uval = gelu_tanh(bf2f(P[row * NIN + PC_U + g * 128 + c])); const float val = uval * (acc[ci][r] + b_s[l * 512 + g * 128 + t]);
;                 const float vn = __shfl_xor(val, 1); if ((r32 & 1) == 0) *(unsigned*)(MIX + row * DM + 1024 + g * 128 + c) = cvtpk(val, vn); }
.LBB0_700:
	s_or_b64 exec, exec, s[6:7]
	v_or_b32_e32 v120, s0, v66
	v_mov_b64_e32 v[118:119], s[16:17]
	v_mad_u64_u32 v[118:119], s[6:7], v120, s83, v[118:119]
	v_mad_i32_i24 v119, s1, v244, v119
	v_lshl_add_u64 v[118:119], v[118:119], 0, s[86:87]
	v_lshl_add_u64 v[118:119], v[38:39], 1, v[118:119]
	v_add_co_u32_e32 v122, vcc, s2, v118
	v_mov_b32_e32 v121, s1
	s_nop 0
	v_addc_co_u32_e32 v123, vcc, 0, v119, vcc
	flat_load_ushort v0, v[122:123] offset:512
	s_waitcnt lgkmcnt(0)
	flat_load_dword v61, v[72:73] offset:104
	v_lshlrev_b64 v[120:121], 12, v[120:121]
	v_lshl_add_u64 v[120:121], s[22:23], 0, v[120:121]
	s_waitcnt vmcnt(0)
	v_lshlrev_b32_e32 v0, 16, v0
	v_mul_f32_e32 v63, 0x3d372713, v0
	v_mul_f32_e32 v63, v63, v0
	v_fma_f32 v63, v63, v0, v0
	v_mul_f32_e32 v63, 0x3f4c422a, v63
	v_mul_f32_e32 v63, 0xc038aa3b, v63
	v_exp_f32_e32 v63, v63
	s_waitcnt lgkmcnt(0)
	v_add_f32_e32 v32, v32, v61
	v_add_f32_e32 v63, 1.0, v63
	v_rcp_f32_e32 v63, v63
	s_nop 0
	v_mul_f32_e32 v0, v63, v0
	v_mul_f32_e32 v0, v32, v0
	s_nop 1
	v_mov_b32_dpp v32, v0 quad_perm:[1,0,3,2] row_mask:0xf bank_mask:0xf
	s_and_saveexec_b64 s[6:7], s[4:5]
	s_cbranch_execz .LBB0_702
	v_lshl_add_u64 v[122:123], v[120:121], 0, s[86:87]
	v_lshl_add_u64 v[122:123], v[38:39], 1, v[122:123]
	v_add_co_u32_e32 v122, vcc, 0x271c0000, v122
	s_waitcnt lgkmcnt(0)
	v_cvt_pk_bf16_f32 v0, v0, v32
	s_nop 0
	v_addc_co_u32_e32 v123, vcc, 0, v123, vcc
	flat_store_dword v[122:123], v0 offset:2048

; __device__ __forceinline__ float bf2f(unsigned short h) { return __uint_as_float(((unsigned)h) << 16); }
; __device__ __forceinline__ unsigned cvtpk(float lo, float hi) { unsigned r; asm volatile("v_cvt_pk_bf16_f32 %0, %1, %2" : "=v"(r) : "v"(lo), "v"(hi)); return r; }
; __device__ __forceinline__ int crow(int r, int hi) { return (r & 3) + 8 * (r >> 2) + 4 * hi; }
; __device__ __forceinline__ float gelu_tanh(float x) {
;     const float y = 0.7978845608028654f * (x + 0.044715f * x * x * x);
;     const float e = __builtin_amdgcn_exp2f(-2.0f * LOG2E * y);
;     return x * __builtin_amdgcn_rcpf(1.0f + e);
; }
; __device__ __forceinline__ void ph_misc(const Args& a, char* lds, int l) {
;     ...
;             for (int r = 0; r < 16; ++r) { const int t = 32 * tb + crow(r, hi), c = 32 * (cb0 + ci) + r32; const size_t row = row0 + t;
;                 const float uval = gelu_tanh(bf2f(P[row * NIN + PC_U + g * 128 + c])); const float val = uval * (acc[ci][r] + b_s[l * 512 + g * 128 + t]);
;                 const float vn = __shfl_xor(val, 1); if ((r32 & 1) == 0) *(unsigned*)(MIX + row * DM + 1024 + g * 128 + c) = cvtpk(val, vn); }
.LBB0_704:
	s_or_b64 exec, exec, s[0:1]
	s_mov_b64 s[0:1], 0x1200
	v_lshl_add_u64 v[74:75], v[74:75], 0, s[0:1]
	flat_load_ushort v0, v[74:75] offset:64
	s_waitcnt lgkmcnt(0)
	flat_load_dword v61, v[78:79]
	s_waitcnt vmcnt(0)
	v_lshlrev_b32_e32 v0, 16, v0
	v_mul_f32_e32 v63, 0x3d372713, v0
	v_mul_f32_e32 v63, v63, v0
	v_fma_f32 v63, v63, v0, v0
	v_mul_f32_e32 v63, 0x3f4c422a, v63
	v_mul_f32_e32 v63, 0xc038aa3b, v63
	v_exp_f32_e32 v63, v63
	s_waitcnt lgkmcnt(0)
	v_add_f32_e32 v2, v2, v61
	v_add_f32_e32 v63, 1.0, v63
	v_rcp_f32_e32 v63, v63
	s_nop 0
	v_mul_f32_e32 v0, v63, v0
	v_mul_f32_e32 v0, v2, v0
	s_nop 1
	v_mov_b32_dpp v2, v0 quad_perm:[1,0,3,2] row_mask:0xf bank_mask:0xf
	s_and_saveexec_b64 s[0:1], s[4:5]
	s_cbranch_execz .LBB0_706
	v_lshl_add_u64 v[74:75], v[76:77], 0, s[86:87]
	v_lshl_add_u64 v[74:75], v[38:39], 1, v[74:75]
	v_add_co_u32_e32 v74, vcc, 0x271c0000, v74
	s_waitcnt lgkmcnt(0)
	v_cvt_pk_bf16_f32 v0, v0, v2
	s_nop 0
	v_addc_co_u32_e32 v75, vcc, 0, v75, vcc
	flat_store_dword v[74:75], v0 offset:2112
.LBB0_706:
	s_or_b64 exec, exec, s[0:1]
	s_mov_b64 s[0:1], 0x1200
	v_lshl_add_u64 v[74:75], v[80:81], 0, s[0:1]
	flat_load_ushort v0, v[74:75] offset:64
	s_waitcnt lgkmcnt(0)
	flat_load_dword v2, v[72:73] offset:4
	s_waitcnt vmcnt(0)
	v_lshlrev_b32_e32 v0, 16, v0
	v_mul_f32_e32 v61, 0x3d372713, v0
	v_mul_f32_e32 v61, v61, v0
	v_fma_f32 v61, v61, v0, v0
	v_mul_f32_e32 v61, 0x3f4c422a, v61
	v_mul_f32_e32 v61, 0xc038aa3b, v61
	v_exp_f32_e32 v61, v61
	s_waitcnt lgkmcnt(0)
	v_add_f32_e32 v2, v3, v2
	v_add_f32_e32 v61, 1.0, v61
	v_rcp_f32_e32 v61, v61
	s_nop 0
	v_mul_f32_e32 v0, v61, v0
	v_mul_f32_e32 v0, v2, v0
	s_nop 1
	v_mov_b32_dpp v2, v0 quad_perm:[1,0,3,2] row_mask:0xf bank_mask:0xf
	s_and_saveexec_b64 s[0:1], s[4:5]
	s_cbranch_execz .LBB0_708
	v_lshl_add_u64 v[18:19], v[18:19], 0, s[86:87]
	v_lshl_add_u64 v[18:19], v[38:39], 1, v[18:19]
	s_waitcnt lgkmcnt(0)
	v_cvt_pk_bf16_f32 v0, v0, v2
	v_add_co_u32_e32 v2, vcc, 0x271c0000, v18
	s_nop 1
	v_addc_co_u32_e32 v3, vcc, 0, v19, vcc
	flat_store_dword v[2:3], v0 offset:2112
.LBB0_708:
	s_or_b64 exec, exec, s[0:1]
	s_mov_b64 s[0:1], 0x1200
	s_waitcnt lgkmcnt(0)
	v_lshl_add_u64 v[2:3], v[82:83], 0, s[0:1]
	flat_load_ushort v0, v[2:3] offset:64
	s_nop 0
	flat_load_dword v2, v[72:73] offset:8
	s_waitcnt vmcnt(0) lgkmcnt(0)
	v_lshlrev_b32_e32 v0, 16, v0
	v_mul_f32_e32 v3, 0x3d372713, v0
	v_mul_f32_e32 v3, v3, v0
	v_fma_f32 v3, v3, v0, v0
	v_mul_f32_e32 v3, 0x3f4c422a, v3
	v_mul_f32_e32 v3, 0xc038aa3b, v3
	v_exp_f32_e32 v3, v3
	v_add_f32_e32 v2, v4, v2
	v_add_f32_e32 v3, 1.0, v3
	v_rcp_f32_e32 v3, v3
	s_nop 0
	v_mul_f32_e32 v0, v3, v0
	v_mul_f32_e32 v0, v2, v0
	s_nop 1
	v_mov_b32_dpp v2, v0 quad_perm:[1,0,3,2] row_mask:0xf bank_mask:0xf
	s_and_saveexec_b64 s[0:1], s[4:5]
	s_cbranch_execz .LBB0_710
	v_lshl_add_u64 v[18:19], v[84:85], 0, s[86:87]
	v_lshl_add_u64 v[18:19], v[38:39], 1, v[18:19]
	s_waitcnt lgkmcnt(0)
	v_cvt_pk_bf16_f32 v0, v0, v2
	v_add_co_u32_e32 v2, vcc, 0x271c0000, v18
	s_nop 1
	v_addc_co_u32_e32 v3, vcc, 0, v19, vcc
	flat_store_dword v[2:3], v0 offset:2112
.LBB0_710:
	s_or_b64 exec, exec, s[0:1]
	s_mov_b64 s[0:1], 0x1200
	s_waitcnt lgkmcnt(0)
	v_lshl_add_u64 v[2:3], v[86:87], 0, s[0:1]
	flat_load_ushort v0, v[2:3] offset:64
	s_nop 0
	flat_load_dword v2, v[72:73] offset:12
	s_waitcnt vmcnt(0) lgkmcnt(0)
	v_lshlrev_b32_e32 v0, 16, v0
	v_mul_f32_e32 v3, 0x3d372713, v0
	v_mul_f32_e32 v3, v3, v0
	v_fma_f32 v3, v3, v0, v0
	v_mul_f32_e32 v3, 0x3f4c422a, v3
	v_mul_f32_e32 v3, 0xc038aa3b, v3
	v_exp_f32_e32 v3, v3
	v_add_f32_e32 v2, v5, v2
	v_add_f32_e32 v3, 1.0, v3
	v_rcp_f32_e32 v3, v3
	s_nop 0
	v_mul_f32_e32 v0, v3, v0
	v_mul_f32_e32 v0, v2, v0
	s_nop 1
	v_mov_b32_dpp v2, v0 quad_perm:[1,0,3,2] row_mask:0xf bank_mask:0xf
	s_and_saveexec_b64 s[0:1], s[4:5]
	s_cbranch_execz .LBB0_712
	v_lshl_add_u64 v[4:5], v[20:21], 0, s[86:87]
	v_lshl_add_u64 v[4:5], v[38:39], 1, v[4:5]
	s_waitcnt lgkmcnt(0)
	v_cvt_pk_bf16_f32 v0, v0, v2
	v_add_co_u32_e32 v2, vcc, 0x271c0000, v4
	s_nop 1
	v_addc_co_u32_e32 v3, vcc, 0, v5, vcc
	flat_store_dword v[2:3], v0 offset:2112
.LBB0_712:
	s_or_b64 exec, exec, s[0:1]
	s_mov_b64 s[0:1], 0x1200
	s_waitcnt lgkmcnt(0)
	v_lshl_add_u64 v[2:3], v[88:89], 0, s[0:1]
	flat_load_ushort v0, v[2:3] offset:64
	s_nop 0
	flat_load_dword v2, v[72:73] offset:32
	s_waitcnt vmcnt(0) lgkmcnt(0)
	v_lshlrev_b32_e32 v0, 16, v0
	v_mul_f32_e32 v3, 0x3d372713, v0
	v_mul_f32_e32 v3, v3, v0
	v_fma_f32 v3, v3, v0, v0
	v_mul_f32_e32 v3, 0x3f4c422a, v3
	v_mul_f32_e32 v3, 0xc038aa3b, v3
	v_exp_f32_e32 v3, v3
	v_add_f32_e32 v2, v6, v2
	v_add_f32_e32 v3, 1.0, v3
	v_rcp_f32_e32 v3, v3
	s_nop 0
	v_mul_f32_e32 v0, v3, v0
	v_mul_f32_e32 v0, v2, v0
	s_nop 1
	v_mov_b32_dpp v2, v0 quad_perm:[1,0,3,2] row_mask:0xf bank_mask:0xf
	s_and_saveexec_b64 s[0:1], s[4:5]
	s_cbranch_execz .LBB0_714
	v_lshl_add_u64 v[4:5], v[90:91], 0, s[86:87]
	v_lshl_add_u64 v[4:5], v[38:39], 1, v[4:5]
	s_waitcnt lgkmcnt(0)
	v_cvt_pk_bf16_f32 v0, v0, v2
	v_add_co_u32_e32 v2, vcc, 0x271c0000, v4
	s_nop 1
	v_addc_co_u32_e32 v3, vcc, 0, v5, vcc
	flat_store_dword v[2:3], v0 offset:2112
.LBB0_714:
	s_or_b64 exec, exec, s[0:1]
	s_mov_b64 s[0:1], 0x1200
	s_waitcnt lgkmcnt(0)
	v_lshl_add_u64 v[2:3], v[92:93], 0, s[0:1]
	flat_load_ushort v0, v[2:3] offset:64
	s_nop 0
	flat_load_dword v2, v[72:73] offset:36
	s_waitcnt vmcnt(0) lgkmcnt(0)
	v_lshlrev_b32_e32 v0, 16, v0
	v_mul_f32_e32 v3, 0x3d372713, v0
	v_mul_f32_e32 v3, v3, v0
	v_fma_f32 v3, v3, v0, v0
	v_mul_f32_e32 v3, 0x3f4c422a, v3
	v_mul_f32_e32 v3, 0xc038aa3b, v3
	v_exp_f32_e32 v3, v3
	v_add_f32_e32 v2, v7, v2
	v_add_f32_e32 v3, 1.0, v3
	v_rcp_f32_e32 v3, v3
	s_nop 0
	v_mul_f32_e32 v0, v3, v0
	v_mul_f32_e32 v0, v2, v0
	s_nop 1
	v_mov_b32_dpp v2, v0 quad_perm:[1,0,3,2] row_mask:0xf bank_mask:0xf
	s_and_saveexec_b64 s[0:1], s[4:5]
	s_cbranch_execz .LBB0_716
	v_lshl_add_u64 v[4:5], v[22:23], 0, s[86:87]
	v_lshl_add_u64 v[4:5], v[38:39], 1, v[4:5]
	s_waitcnt lgkmcnt(0)
	v_cvt_pk_bf16_f32 v0, v0, v2
	v_add_co_u32_e32 v2, vcc, 0x271c0000, v4
	s_nop 1
	v_addc_co_u32_e32 v3, vcc, 0, v5, vcc
	flat_store_dword v[2:3], v0 offset:2112
; __device__ __forceinline__ float bf2f(unsigned short h) { return __uint_as_float(((unsigned)h) << 16); }
; __device__ __forceinline__ unsigned cvtpk(float lo, float hi) { unsigned r; asm volatile("v_cvt_pk_bf16_f32 %0, %1, %2" : "=v"(r) : "v"(lo), "v"(hi)); return r; }
; __device__ __forceinline__ int crow(int r, int hi) { return (r & 3) + 8 * (r >> 2) + 4 * hi; }
; __device__ __forceinline__ float gelu_tanh(float x) {
;     const float y = 0.7978845608028654f * (x + 0.044715f * x * x * x);
;     const float e = __builtin_amdgcn_exp2f(-2.0f * LOG2E * y);
;     return x * __builtin_amdgcn_rcpf(1.0f + e);
; }
; __device__ __forceinline__ void ph_misc(const Args& a, char* lds, int l) {
;     ...
;             for (int r = 0; r < 16; ++r) { const int t = 32 * tb + crow(r, hi), c = 32 * (cb0 + ci) + r32; const size_t row = row0 + t;
;                 const float uval = gelu_tanh(bf2f(P[row * NIN + PC_U + g * 128 + c])); const float val = uval * (acc[ci][r] + b_s[l * 512 + g * 128 + t]);
;                 const float vn = __shfl_xor(val, 1); if ((r32 & 1) == 0) *(unsigned*)(MIX + row * DM + 1024 + g * 128 + c) = cvtpk(val, vn); }
.LBB0_716:
	s_or_b64 exec, exec, s[0:1]
	s_mov_b64 s[0:1], 0x1200
	s_waitcnt lgkmcnt(0)
	v_lshl_add_u64 v[2:3], v[94:95], 0, s[0:1]
	flat_load_ushort v0, v[2:3] offset:64
	s_nop 0
	flat_load_dword v2, v[72:73] offset:40
	s_waitcnt vmcnt(0) lgkmcnt(0)
	v_lshlrev_b32_e32 v0, 16, v0
	v_mul_f32_e32 v3, 0x3d372713, v0
	v_mul_f32_e32 v3, v3, v0
	v_fma_f32 v3, v3, v0, v0
	v_mul_f32_e32 v3, 0x3f4c422a, v3
	v_mul_f32_e32 v3, 0xc038aa3b, v3
	v_exp_f32_e32 v3, v3
	v_add_f32_e32 v2, v8, v2
	v_add_f32_e32 v3, 1.0, v3
	v_rcp_f32_e32 v3, v3
	s_nop 0
	v_mul_f32_e32 v0, v3, v0
	v_mul_f32_e32 v0, v2, v0
	s_nop 1
	v_mov_b32_dpp v2, v0 quad_perm:[1,0,3,2] row_mask:0xf bank_mask:0xf
	s_and_saveexec_b64 s[0:1], s[4:5]
	s_cbranch_execz .LBB0_718
	v_lshl_add_u64 v[4:5], v[96:97], 0, s[86:87]
	v_lshl_add_u64 v[4:5], v[38:39], 1, v[4:5]
	s_waitcnt lgkmcnt(0)
	v_cvt_pk_bf16_f32 v0, v0, v2
	v_add_co_u32_e32 v2, vcc, 0x271c0000, v4
	s_nop 1
	v_addc_co_u32_e32 v3, vcc, 0, v5, vcc
	flat_store_dword v[2:3], v0 offset:2112
.LBB0_718:
	s_or_b64 exec, exec, s[0:1]
	s_mov_b64 s[0:1], 0x1200
	s_waitcnt lgkmcnt(0)
	v_lshl_add_u64 v[2:3], v[98:99], 0, s[0:1]
	flat_load_ushort v0, v[2:3] offset:64
	s_nop 0
	flat_load_dword v2, v[72:73] offset:44
	s_waitcnt vmcnt(0) lgkmcnt(0)
	v_lshlrev_b32_e32 v0, 16, v0
	v_mul_f32_e32 v3, 0x3d372713, v0
	v_mul_f32_e32 v3, v3, v0
	v_fma_f32 v3, v3, v0, v0
	v_mul_f32_e32 v3, 0x3f4c422a, v3
	v_mul_f32_e32 v3, 0xc038aa3b, v3
	v_exp_f32_e32 v3, v3
	v_add_f32_e32 v2, v9, v2
	v_add_f32_e32 v3, 1.0, v3
	v_rcp_f32_e32 v3, v3
	s_nop 0
	v_mul_f32_e32 v0, v3, v0
	v_mul_f32_e32 v0, v2, v0
	s_nop 1
	v_mov_b32_dpp v2, v0 quad_perm:[1,0,3,2] row_mask:0xf bank_mask:0xf
	s_and_saveexec_b64 s[0:1], s[4:5]
	s_cbranch_execz .LBB0_720
	v_lshl_add_u64 v[4:5], v[24:25], 0, s[86:87]
	v_lshl_add_u64 v[4:5], v[38:39], 1, v[4:5]
	s_waitcnt lgkmcnt(0)
	v_cvt_pk_bf16_f32 v0, v0, v2
	v_add_co_u32_e32 v2, vcc, 0x271c0000, v4
	s_nop 1
	v_addc_co_u32_e32 v3, vcc, 0, v5, vcc
	flat_store_dword v[2:3], v0 offset:2112
.LBB0_720:
	s_or_b64 exec, exec, s[0:1]
	s_mov_b64 s[0:1], 0x1200
	s_waitcnt lgkmcnt(0)
	v_lshl_add_u64 v[2:3], v[100:101], 0, s[0:1]
	flat_load_ushort v0, v[2:3] offset:64
	s_nop 0
	flat_load_dword v2, v[72:73] offset:64
	s_waitcnt vmcnt(0) lgkmcnt(0)
	v_lshlrev_b32_e32 v0, 16, v0
	v_mul_f32_e32 v3, 0x3d372713, v0
	v_mul_f32_e32 v3, v3, v0
	v_fma_f32 v3, v3, v0, v0
	v_mul_f32_e32 v3, 0x3f4c422a, v3
	v_mul_f32_e32 v3, 0xc038aa3b, v3
	v_exp_f32_e32 v3, v3
	v_add_f32_e32 v2, v10, v2
	v_add_f32_e32 v3, 1.0, v3
	v_rcp_f32_e32 v3, v3
	s_nop 0
	v_mul_f32_e32 v0, v3, v0
	v_mul_f32_e32 v0, v2, v0
	s_nop 1
	v_mov_b32_dpp v2, v0 quad_perm:[1,0,3,2] row_mask:0xf bank_mask:0xf
	s_and_saveexec_b64 s[0:1], s[4:5]
	s_cbranch_execz .LBB0_722
	v_lshl_add_u64 v[4:5], v[102:103], 0, s[86:87]
	v_lshl_add_u64 v[4:5], v[38:39], 1, v[4:5]
	s_waitcnt lgkmcnt(0)
	v_cvt_pk_bf16_f32 v0, v0, v2
	v_add_co_u32_e32 v2, vcc, 0x271c0000, v4
	s_nop 1
	v_addc_co_u32_e32 v3, vcc, 0, v5, vcc
	flat_store_dword v[2:3], v0 offset:2112
.LBB0_722:
	s_or_b64 exec, exec, s[0:1]
	s_mov_b64 s[0:1], 0x1200
	s_waitcnt lgkmcnt(0)
	v_lshl_add_u64 v[2:3], v[104:105], 0, s[0:1]
	flat_load_ushort v0, v[2:3] offset:64
	s_nop 0
	flat_load_dword v2, v[72:73] offset:68
	s_waitcnt vmcnt(0) lgkmcnt(0)
	v_lshlrev_b32_e32 v0, 16, v0
	v_mul_f32_e32 v3, 0x3d372713, v0
	v_mul_f32_e32 v3, v3, v0
	v_fma_f32 v3, v3, v0, v0
	v_mul_f32_e32 v3, 0x3f4c422a, v3
	v_mul_f32_e32 v3, 0xc038aa3b, v3
	v_exp_f32_e32 v3, v3
	v_add_f32_e32 v2, v11, v2
	v_add_f32_e32 v3, 1.0, v3
	v_rcp_f32_e32 v3, v3
	s_nop 0
	v_mul_f32_e32 v0, v3, v0
	v_mul_f32_e32 v0, v2, v0
	s_nop 1
	v_mov_b32_dpp v2, v0 quad_perm:[1,0,3,2] row_mask:0xf bank_mask:0xf
	s_and_saveexec_b64 s[0:1], s[4:5]
	s_cbranch_execz .LBB0_724
	v_lshl_add_u64 v[4:5], v[26:27], 0, s[86:87]
	v_lshl_add_u64 v[4:5], v[38:39], 1, v[4:5]
	s_waitcnt lgkmcnt(0)
	v_cvt_pk_bf16_f32 v0, v0, v2
	v_add_co_u32_e32 v2, vcc, 0x271c0000, v4
	s_nop 1
	v_addc_co_u32_e32 v3, vcc, 0, v5, vcc
	flat_store_dword v[2:3], v0 offset:2112
.LBB0_724:
	s_or_b64 exec, exec, s[0:1]
	s_mov_b64 s[0:1], 0x1200
	s_waitcnt lgkmcnt(0)
	v_lshl_add_u64 v[2:3], v[106:107], 0, s[0:1]
	flat_load_ushort v0, v[2:3] offset:64
	s_nop 0
	flat_load_dword v2, v[72:73] offset:72
	s_waitcnt vmcnt(0) lgkmcnt(0)
	v_lshlrev_b32_e32 v0, 16, v0
	v_mul_f32_e32 v3, 0x3d372713, v0
	v_mul_f32_e32 v3, v3, v0
	v_fma_f32 v3, v3, v0, v0
	v_mul_f32_e32 v3, 0x3f4c422a, v3
	v_mul_f32_e32 v3, 0xc038aa3b, v3
	v_exp_f32_e32 v3, v3
	v_add_f32_e32 v2, v12, v2
	v_add_f32_e32 v3, 1.0, v3
	v_rcp_f32_e32 v3, v3
	s_nop 0
	v_mul_f32_e32 v0, v3, v0
	v_mul_f32_e32 v0, v2, v0
	s_nop 1
	v_mov_b32_dpp v2, v0 quad_perm:[1,0,3,2] row_mask:0xf bank_mask:0xf
	s_and_saveexec_b64 s[0:1], s[4:5]
	s_cbranch_execz .LBB0_726
	v_lshl_add_u64 v[4:5], v[108:109], 0, s[86:87]
	v_lshl_add_u64 v[4:5], v[38:39], 1, v[4:5]
	s_waitcnt lgkmcnt(0)
	v_cvt_pk_bf16_f32 v0, v0, v2
	v_add_co_u32_e32 v2, vcc, 0x271c0000, v4
	s_nop 1
	v_addc_co_u32_e32 v3, vcc, 0, v5, vcc
	flat_store_dword v[2:3], v0 offset:2112
; __device__ __forceinline__ float bf2f(unsigned short h) { return __uint_as_float(((unsigned)h) << 16); }
; __device__ __forceinline__ unsigned cvtpk(float lo, float hi) { unsigned r; asm volatile("v_cvt_pk_bf16_f32 %0, %1, %2" : "=v"(r) : "v"(lo), "v"(hi)); return r; }
; __device__ __forceinline__ int crow(int r, int hi) { return (r & 3) + 8 * (r >> 2) + 4 * hi; }
; __device__ __forceinline__ float gelu_tanh(float x) {
;     const float y = 0.7978845608028654f * (x + 0.044715f * x * x * x);
;     const float e = __builtin_amdgcn_exp2f(-2.0f * LOG2E * y);
;     return x * __builtin_amdgcn_rcpf(1.0f + e);
; }
; __device__ __forceinline__ void ph_misc(const Args& a, char* lds, int l) {
;     ...
;             for (int r = 0; r < 16; ++r) { const int t = 32 * tb + crow(r, hi), c = 32 * (cb0 + ci) + r32; const size_t row = row0 + t;
;                 const float uval = gelu_tanh(bf2f(P[row * NIN + PC_U + g * 128 + c])); const float val = uval * (acc[ci][r] + b_s[l * 512 + g * 128 + t]);
;                 const float vn = __shfl_xor(val, 1); if ((r32 & 1) == 0) *(unsigned*)(MIX + row * DM + 1024 + g * 128 + c) = cvtpk(val, vn); }
.LBB0_726:
	s_or_b64 exec, exec, s[0:1]
	s_mov_b64 s[0:1], 0x1200
	s_waitcnt lgkmcnt(0)
	v_lshl_add_u64 v[2:3], v[110:111], 0, s[0:1]
	flat_load_ushort v0, v[2:3] offset:64
	s_nop 0
	flat_load_dword v2, v[72:73] offset:76
	s_waitcnt vmcnt(0) lgkmcnt(0)
	v_lshlrev_b32_e32 v0, 16, v0
	v_mul_f32_e32 v3, 0x3d372713, v0
	v_mul_f32_e32 v3, v3, v0
	v_fma_f32 v3, v3, v0, v0
	v_mul_f32_e32 v3, 0x3f4c422a, v3
	v_mul_f32_e32 v3, 0xc038aa3b, v3
	v_exp_f32_e32 v3, v3
	v_add_f32_e32 v2, v13, v2
	v_add_f32_e32 v3, 1.0, v3
	v_rcp_f32_e32 v3, v3
	s_nop 0
	v_mul_f32_e32 v0, v3, v0
	v_mul_f32_e32 v0, v2, v0
	s_nop 1
	v_mov_b32_dpp v2, v0 quad_perm:[1,0,3,2] row_mask:0xf bank_mask:0xf
	s_and_saveexec_b64 s[0:1], s[4:5]
	s_cbranch_execz .LBB0_728
	v_lshl_add_u64 v[4:5], v[28:29], 0, s[86:87]
	v_lshl_add_u64 v[4:5], v[38:39], 1, v[4:5]
	s_waitcnt lgkmcnt(0)
	v_cvt_pk_bf16_f32 v0, v0, v2
	v_add_co_u32_e32 v2, vcc, 0x271c0000, v4
	s_nop 1
	v_addc_co_u32_e32 v3, vcc, 0, v5, vcc
	flat_store_dword v[2:3], v0 offset:2112
.LBB0_728:
	s_or_b64 exec, exec, s[0:1]
	s_mov_b64 s[0:1], 0x1200
	s_waitcnt lgkmcnt(0)
	v_lshl_add_u64 v[2:3], v[112:113], 0, s[0:1]
	flat_load_ushort v0, v[2:3] offset:64
	s_nop 0
	flat_load_dword v2, v[72:73] offset:96
	s_waitcnt vmcnt(0) lgkmcnt(0)
	v_lshlrev_b32_e32 v0, 16, v0
	v_mul_f32_e32 v3, 0x3d372713, v0
	v_mul_f32_e32 v3, v3, v0
	v_fma_f32 v3, v3, v0, v0
	v_mul_f32_e32 v3, 0x3f4c422a, v3
	v_mul_f32_e32 v3, 0xc038aa3b, v3
	v_exp_f32_e32 v3, v3
	v_add_f32_e32 v2, v14, v2
	v_add_f32_e32 v3, 1.0, v3
	v_rcp_f32_e32 v3, v3
	s_nop 0
	v_mul_f32_e32 v0, v3, v0
	v_mul_f32_e32 v0, v2, v0
	s_nop 1
	v_mov_b32_dpp v2, v0 quad_perm:[1,0,3,2] row_mask:0xf bank_mask:0xf
	s_and_saveexec_b64 s[0:1], s[4:5]
	s_cbranch_execz .LBB0_730
	v_lshl_add_u64 v[4:5], v[114:115], 0, s[86:87]
	v_lshl_add_u64 v[4:5], v[38:39], 1, v[4:5]
	s_waitcnt lgkmcnt(0)
	v_cvt_pk_bf16_f32 v0, v0, v2
	v_add_co_u32_e32 v2, vcc, 0x271c0000, v4
	s_nop 1
	v_addc_co_u32_e32 v3, vcc, 0, v5, vcc
	flat_store_dword v[2:3], v0 offset:2112
.LBB0_730:
	s_or_b64 exec, exec, s[0:1]
	s_mov_b64 s[0:1], 0x1200
	s_waitcnt lgkmcnt(0)
	v_lshl_add_u64 v[2:3], v[116:117], 0, s[0:1]
	flat_load_ushort v0, v[2:3] offset:64
	s_nop 0
	flat_load_dword v2, v[72:73] offset:100
	s_waitcnt vmcnt(0) lgkmcnt(0)
	v_lshlrev_b32_e32 v0, 16, v0
	v_mul_f32_e32 v3, 0x3d372713, v0
	v_mul_f32_e32 v3, v3, v0
	v_fma_f32 v3, v3, v0, v0
	v_mul_f32_e32 v3, 0x3f4c422a, v3
	v_mul_f32_e32 v3, 0xc038aa3b, v3
	v_exp_f32_e32 v3, v3
	v_add_f32_e32 v2, v15, v2
	v_add_f32_e32 v3, 1.0, v3
	v_rcp_f32_e32 v3, v3
	s_nop 0
	v_mul_f32_e32 v0, v3, v0
	v_mul_f32_e32 v0, v2, v0
	s_nop 1
	v_mov_b32_dpp v2, v0 quad_perm:[1,0,3,2] row_mask:0xf bank_mask:0xf
	s_and_saveexec_b64 s[0:1], s[4:5]
	s_cbranch_execz .LBB0_732
	v_lshl_add_u64 v[4:5], v[30:31], 0, s[86:87]
	v_lshl_add_u64 v[4:5], v[38:39], 1, v[4:5]
	s_waitcnt lgkmcnt(0)
	v_cvt_pk_bf16_f32 v0, v0, v2
	v_add_co_u32_e32 v2, vcc, 0x271c0000, v4
	s_nop 1
	v_addc_co_u32_e32 v3, vcc, 0, v5, vcc
	flat_store_dword v[2:3], v0 offset:2112
.LBB0_732:
	s_or_b64 exec, exec, s[0:1]
	s_mov_b64 s[0:1], 0x1200
	s_waitcnt lgkmcnt(0)
	v_lshl_add_u64 v[2:3], v[118:119], 0, s[0:1]
	flat_load_ushort v0, v[2:3] offset:64
	s_nop 0
	flat_load_dword v2, v[72:73] offset:104
	s_waitcnt vmcnt(0) lgkmcnt(0)
	v_lshlrev_b32_e32 v0, 16, v0
	v_mul_f32_e32 v3, 0x3d372713, v0
	v_mul_f32_e32 v3, v3, v0
	v_fma_f32 v3, v3, v0, v0
	v_mul_f32_e32 v3, 0x3f4c422a, v3
	v_mul_f32_e32 v3, 0xc038aa3b, v3
	v_exp_f32_e32 v3, v3
	v_add_f32_e32 v2, v16, v2
	v_add_f32_e32 v3, 1.0, v3
	v_rcp_f32_e32 v3, v3
	s_nop 0
	v_mul_f32_e32 v0, v3, v0
	v_mul_f32_e32 v0, v2, v0
	s_nop 1
	v_mov_b32_dpp v2, v0 quad_perm:[1,0,3,2] row_mask:0xf bank_mask:0xf
	s_and_saveexec_b64 s[0:1], s[4:5]
	s_cbranch_execz .LBB0_734
	v_lshl_add_u64 v[4:5], v[120:121], 0, s[86:87]
	v_lshl_add_u64 v[4:5], v[38:39], 1, v[4:5]
	s_waitcnt lgkmcnt(0)
	v_cvt_pk_bf16_f32 v0, v0, v2
	v_add_co_u32_e32 v2, vcc, 0x271c0000, v4
	s_nop 1
	v_addc_co_u32_e32 v3, vcc, 0, v5, vcc
	flat_store_dword v[2:3], v0 offset:2112
.LBB0_734:
	s_or_b64 exec, exec, s[0:1]
	s_mov_b64 s[0:1], 0x1200
	s_waitcnt lgkmcnt(0)
	v_lshl_add_u64 v[2:3], v[122:123], 0, s[0:1]
	flat_load_ushort v0, v[2:3] offset:64
	s_nop 0
	flat_load_dword v2, v[72:73] offset:108
	s_waitcnt vmcnt(0) lgkmcnt(0)
	v_lshlrev_b32_e32 v0, 16, v0
	v_mul_f32_e32 v3, 0x3d372713, v0
	v_mul_f32_e32 v3, v3, v0
	v_fma_f32 v3, v3, v0, v0
	v_mul_f32_e32 v3, 0x3f4c422a, v3
	v_mul_f32_e32 v3, 0xc038aa3b, v3
	v_exp_f32_e32 v3, v3
	v_add_f32_e32 v2, v17, v2
	v_add_f32_e32 v3, 1.0, v3
	v_rcp_f32_e32 v3, v3
	s_nop 0
	v_mul_f32_e32 v0, v3, v0
	v_mul_f32_e32 v0, v2, v0
	s_nop 1
	v_mov_b32_dpp v2, v0 quad_perm:[1,0,3,2] row_mask:0xf bank_mask:0xf
	s_and_saveexec_b64 s[0:1], s[4:5]
	s_cbranch_execz .LBB0_659
	v_lshl_add_u64 v[4:5], v[32:33], 0, s[86:87]
	v_lshl_add_u64 v[4:5], v[38:39], 1, v[4:5]
	s_waitcnt lgkmcnt(0)
	v_cvt_pk_bf16_f32 v0, v0, v2
	v_add_co_u32_e32 v2, vcc, 0x271c0000, v4
	s_nop 1
	v_addc_co_u32_e32 v3, vcc, 0, v5, vcc
	flat_store_dword v[2:3], v0 offset:2112
	s_branch .LBB0_659

; #define GAS __attribute__((address_space(1)))
; __device__ __forceinline__ unsigned cvtpk(float lo, float hi) { unsigned r; asm volatile("v_cvt_pk_bf16_f32 %0, %1, %2" : "=v"(r) : "v"(lo), "v"(hi)); return r; }
; __device__ __forceinline__ int crow(int r, int hi) { return (r & 3) + 8 * (r >> 2) + 4 * hi; }
; template <int DK, int MODE> ...
;     ...
;     if (hi == 0) ws[32 + r32] = l_reg; asm volatile("s_waitcnt lgkmcnt(0)" ::: "memory");
; #pragma unroll
;     for (int r = 0; r < 16; ++r) { const float rl = __builtin_amdgcn_rcpf(ws[32 + crow(r, hi)]);
; #pragma unroll
;         for (int d = 0; d < 4; ++d) o[d][r] *= rl; }
; __device__ __forceinline__ void store_o(const f32x16 (&o)[4], bf16_t* Ow, int pitch, int r32, int hi) {
;     ...
;     for (int r = 0; r < 16; ++r) { const int orow = crow(r, hi);
; #pragma unroll
;         for (int d0 = 0; d0 < 4; ++d0) { const float v = o[d0][r]; const float vn = __shfl_xor(v, 1);
;             if ((r32 & 1) == 0) *(GAS unsigned*)(Ow + (size_t)orow * pitch + d0 * 32 + r32) = cvtpk(v, vn); } }
.LBB0_879:
	s_and_saveexec_b64 s[0:1], s[10:11]
	ds_write_b32 v164, v177 offset:128
	s_or_b64 exec, exec, s[0:1]
	s_waitcnt lgkmcnt(0)
	v_add_u32_e32 v0, s89, v0
	ds_read_b128 v[78:81], v0 offset:128
	ds_read_b128 v[74:77], v0 offset:160
	s_lshl_b64 s[0:1], s[76:77], 12
	v_readlane_b32 s2, v255, 38
	ds_read_b128 v[70:73], v0 offset:192
	ds_read_b128 v[66:69], v0 offset:224
	s_waitcnt lgkmcnt(0)
	v_rcp_f32_e32 v78, v78
	s_add_u32 s0, s2, s0
	v_readlane_b32 s2, v255, 39
	v_xor_b32_e32 v0, 1, v243
	v_mul_f32_e32 v84, v34, v78
	v_and_b32_e32 v34, 64, v243
	v_add_u32_e32 v34, 64, v34
	s_addc_u32 s1, s2, s1
	s_lshl_b32 s2, s85, 1
	v_cmp_lt_i32_e32 vcc, v0, v34
	s_add_u32 s0, s0, s2
	s_addc_u32 s1, s1, 0
	v_cndmask_b32_e32 v0, v243, v0, vcc
	v_lshlrev_b32_e32 v34, 2, v0
	v_lshlrev_b32_e32 v0, 1, v146
	v_lshl_add_u64 v[82:83], s[0:1], 0, v[0:1]
	v_lshlrev_b32_e32 v0, 1, v148
	v_lshl_add_u64 v[82:83], v[82:83], 0, v[0:1]
	s_nop 1
	v_mov_b32_dpp v0, v84 quad_perm:[1,0,3,2] row_mask:0xf bank_mask:0xf
	s_waitcnt lgkmcnt(0)
	s_and_saveexec_b64 s[0:1], s[8:9]
	s_movk_i32 s83, 0x2600
	s_mov_b32 s86, s43
	s_mov_b32 s16, s93
	v_readlane_b32 s85, v255, 28
	s_cbranch_execz .LBB0_883
	s_waitcnt lgkmcnt(0)
	v_cvt_pk_bf16_f32 v0, v84, v0
	global_store_dword v[82:83], v0, off
.LBB0_883:
	s_or_b64 exec, exec, s[0:1]
	s_waitcnt lgkmcnt(0)
	v_mul_f32_e32 v0, v50, v78
	s_nop 1
	v_mov_b32_dpp v50, v0 quad_perm:[1,0,3,2] row_mask:0xf bank_mask:0xf
	s_and_saveexec_b64 s[0:1], s[8:9]
	s_cbranch_execz .LBB0_885
	s_waitcnt lgkmcnt(0)
	v_cvt_pk_bf16_f32 v0, v0, v50
	global_store_dword v[82:83], v0, off offset:64
.LBB0_885:
	s_or_b64 exec, exec, s[0:1]
	v_mul_f32_e32 v0, v18, v78
	s_nop 1
	v_mov_b32_dpp v18, v0 quad_perm:[1,0,3,2] row_mask:0xf bank_mask:0xf
	s_and_saveexec_b64 s[0:1], s[8:9]
	s_cbranch_execz .LBB0_887
	s_waitcnt lgkmcnt(0)
	v_cvt_pk_bf16_f32 v0, v0, v18
	global_store_dword v[82:83], v0, off offset:128
.LBB0_887:
	s_or_b64 exec, exec, s[0:1]
	v_mul_f32_e32 v0, v2, v78
	s_nop 1
	v_mov_b32_dpp v2, v0 quad_perm:[1,0,3,2] row_mask:0xf bank_mask:0xf
	s_and_saveexec_b64 s[0:1], s[8:9]
	s_cbranch_execz .LBB0_889
	s_waitcnt lgkmcnt(0)
	v_cvt_pk_bf16_f32 v0, v0, v2
	global_store_dword v[82:83], v0, off offset:192
.LBB0_889:
	s_or_b64 exec, exec, s[0:1]
	v_rcp_f32_e32 v0, v79
	s_waitcnt lgkmcnt(0)
	v_mul_f32_e32 v2, v35, v0
	s_nop 1
	v_mov_b32_dpp v18, v2 quad_perm:[1,0,3,2] row_mask:0xf bank_mask:0xf
	s_and_saveexec_b64 s[0:1], s[8:9]
	s_cbranch_execz .LBB0_891
	v_add_co_u32_e32 v78, vcc, 0x1000, v82
	s_waitcnt lgkmcnt(0)
	v_cvt_pk_bf16_f32 v2, v2, v18
	s_nop 0
	v_addc_co_u32_e32 v79, vcc, 0, v83, vcc
	global_store_dword v[78:79], v2, off
.LBB0_891:
	s_or_b64 exec, exec, s[0:1]
	v_mul_f32_e32 v2, v51, v0
	s_waitcnt lgkmcnt(0)
	s_nop 1
	v_mov_b32_dpp v18, v2 quad_perm:[1,0,3,2] row_mask:0xf bank_mask:0xf
	s_and_saveexec_b64 s[0:1], s[8:9]
	s_cbranch_execz .LBB0_893
	v_add_co_u32_e32 v50, vcc, 0x1000, v82
	s_waitcnt lgkmcnt(0)
	v_cvt_pk_bf16_f32 v2, v2, v18
	s_nop 0
	v_addc_co_u32_e32 v51, vcc, 0, v83, vcc
	global_store_dword v[50:51], v2, off offset:64
.LBB0_893:
	s_or_b64 exec, exec, s[0:1]
	v_mul_f32_e32 v2, v19, v0
	s_waitcnt lgkmcnt(0)
	s_nop 1
	v_mov_b32_dpp v18, v2 quad_perm:[1,0,3,2] row_mask:0xf bank_mask:0xf
	s_and_saveexec_b64 s[0:1], s[8:9]
	s_cbranch_execz .LBB0_895
	s_waitcnt lgkmcnt(0)
	v_cvt_pk_bf16_f32 v2, v2, v18
	v_add_co_u32_e32 v18, vcc, 0x1000, v82
	s_nop 1
	v_addc_co_u32_e32 v19, vcc, 0, v83, vcc
	global_store_dword v[18:19], v2, off offset:128
.LBB0_895:
	s_or_b64 exec, exec, s[0:1]
	v_mul_f32_e32 v0, v3, v0
	s_nop 1
	v_mov_b32_dpp v2, v0 quad_perm:[1,0,3,2] row_mask:0xf bank_mask:0xf
	s_and_saveexec_b64 s[0:1], s[8:9]
	s_cbranch_execz .LBB0_897
	s_waitcnt lgkmcnt(0)
	v_cvt_pk_bf16_f32 v0, v0, v2
	v_add_co_u32_e32 v2, vcc, 0x1000, v82
	s_nop 1
	v_addc_co_u32_e32 v3, vcc, 0, v83, vcc
	global_store_dword v[2:3], v0, off offset:192
.LBB0_897:
	s_or_b64 exec, exec, s[0:1]
	v_rcp_f32_e32 v0, v80
	s_waitcnt lgkmcnt(0)
	v_mul_f32_e32 v2, v36, v0
	s_nop 1
	v_mov_b32_dpp v3, v2 quad_perm:[1,0,3,2] row_mask:0xf bank_mask:0xf
	s_and_saveexec_b64 s[0:1], s[8:9]
	s_cbranch_execz .LBB0_899
	s_waitcnt lgkmcnt(0)
	v_cvt_pk_bf16_f32 v18, v2, v3
	v_add_co_u32_e32 v2, vcc, 0x2000, v82
	s_nop 1
	v_addc_co_u32_e32 v3, vcc, 0, v83, vcc
	global_store_dword v[2:3], v18, off
.LBB0_899:
	s_or_b64 exec, exec, s[0:1]
	v_mul_f32_e32 v2, v52, v0
	s_waitcnt lgkmcnt(0)
	s_nop 1
	v_mov_b32_dpp v3, v2 quad_perm:[1,0,3,2] row_mask:0xf bank_mask:0xf
	s_and_saveexec_b64 s[0:1], s[8:9]
	s_cbranch_execz .LBB0_901
	s_waitcnt lgkmcnt(0)
	v_cvt_pk_bf16_f32 v18, v2, v3
	v_add_co_u32_e32 v2, vcc, 0x2000, v82
	s_nop 1
	v_addc_co_u32_e32 v3, vcc, 0, v83, vcc
	global_store_dword v[2:3], v18, off offset:64
.LBB0_901:
	s_or_b64 exec, exec, s[0:1]
	v_mul_f32_e32 v2, v20, v0
	s_waitcnt lgkmcnt(0)
	s_nop 1
	v_mov_b32_dpp v3, v2 quad_perm:[1,0,3,2] row_mask:0xf bank_mask:0xf
	s_and_saveexec_b64 s[0:1], s[8:9]
	s_cbranch_execz .LBB0_903
	s_waitcnt lgkmcnt(0)
	v_cvt_pk_bf16_f32 v18, v2, v3
	v_add_co_u32_e32 v2, vcc, 0x2000, v82
	s_nop 1
	v_addc_co_u32_e32 v3, vcc, 0, v83, vcc
	global_store_dword v[2:3], v18, off offset:128
.LBB0_903:
	s_or_b64 exec, exec, s[0:1]
	v_mul_f32_e32 v0, v4, v0
	s_nop 1
	v_mov_b32_dpp v2, v0 quad_perm:[1,0,3,2] row_mask:0xf bank_mask:0xf
	s_and_saveexec_b64 s[0:1], s[8:9]
	s_cbranch_execz .LBB0_905
	s_waitcnt lgkmcnt(0)
	v_cvt_pk_bf16_f32 v0, v0, v2
	v_add_co_u32_e32 v2, vcc, 0x2000, v82
	s_nop 1
	v_addc_co_u32_e32 v3, vcc, 0, v83, vcc
	global_store_dword v[2:3], v0, off offset:192
; #define GAS __attribute__((address_space(1)))
; __device__ __forceinline__ unsigned cvtpk(float lo, float hi) { unsigned r; asm volatile("v_cvt_pk_bf16_f32 %0, %1, %2" : "=v"(r) : "v"(lo), "v"(hi)); return r; }
; __device__ __forceinline__ int crow(int r, int hi) { return (r & 3) + 8 * (r >> 2) + 4 * hi; }
; template <int DK, int MODE> ...
;     ...
;     if (hi == 0) ws[32 + r32] = l_reg; asm volatile("s_waitcnt lgkmcnt(0)" ::: "memory");
; #pragma unroll
;     for (int r = 0; r < 16; ++r) { const float rl = __builtin_amdgcn_rcpf(ws[32 + crow(r, hi)]);
; #pragma unroll
;         for (int d = 0; d < 4; ++d) o[d][r] *= rl; }
; __device__ __forceinline__ void store_o(const f32x16 (&o)[4], bf16_t* Ow, int pitch, int r32, int hi) {
;     ...
;     for (int r = 0; r < 16; ++r) { const int orow = crow(r, hi);
; #pragma unroll
;         for (int d0 = 0; d0 < 4; ++d0) { const float v = o[d0][r]; const float vn = __shfl_xor(v, 1);
;             if ((r32 & 1) == 0) *(GAS unsigned*)(Ow + (size_t)orow * pitch + d0 * 32 + r32) = cvtpk(v, vn); } }
.LBB0_905:
	s_or_b64 exec, exec, s[0:1]
	v_rcp_f32_e32 v0, v81
	s_waitcnt lgkmcnt(0)
	v_mul_f32_e32 v2, v37, v0
	s_nop 1
	v_mov_b32_dpp v3, v2 quad_perm:[1,0,3,2] row_mask:0xf bank_mask:0xf
	s_and_saveexec_b64 s[0:1], s[8:9]
	s_cbranch_execz .LBB0_907
	s_waitcnt lgkmcnt(0)
	v_cvt_pk_bf16_f32 v4, v2, v3
	v_add_co_u32_e32 v2, vcc, 0x3000, v82
	s_nop 1
	v_addc_co_u32_e32 v3, vcc, 0, v83, vcc
	global_store_dword v[2:3], v4, off
.LBB0_907:
	s_or_b64 exec, exec, s[0:1]
	v_mul_f32_e32 v2, v53, v0
	s_waitcnt lgkmcnt(0)
	s_nop 1
	v_mov_b32_dpp v3, v2 quad_perm:[1,0,3,2] row_mask:0xf bank_mask:0xf
	s_and_saveexec_b64 s[0:1], s[8:9]
	s_cbranch_execz .LBB0_909
	s_waitcnt lgkmcnt(0)
	v_cvt_pk_bf16_f32 v4, v2, v3
	v_add_co_u32_e32 v2, vcc, 0x3000, v82
	s_nop 1
	v_addc_co_u32_e32 v3, vcc, 0, v83, vcc
	global_store_dword v[2:3], v4, off offset:64
.LBB0_909:
	s_or_b64 exec, exec, s[0:1]
	v_mul_f32_e32 v2, v21, v0
	s_waitcnt lgkmcnt(0)
	s_nop 1
	v_mov_b32_dpp v3, v2 quad_perm:[1,0,3,2] row_mask:0xf bank_mask:0xf
	s_and_saveexec_b64 s[0:1], s[8:9]
	s_cbranch_execz .LBB0_911
	s_waitcnt lgkmcnt(0)
	v_cvt_pk_bf16_f32 v4, v2, v3
	v_add_co_u32_e32 v2, vcc, 0x3000, v82
	s_nop 1
	v_addc_co_u32_e32 v3, vcc, 0, v83, vcc
	global_store_dword v[2:3], v4, off offset:128
.LBB0_911:
	s_or_b64 exec, exec, s[0:1]
	v_mul_f32_e32 v0, v5, v0
	s_nop 1
	v_mov_b32_dpp v2, v0 quad_perm:[1,0,3,2] row_mask:0xf bank_mask:0xf
	s_and_saveexec_b64 s[0:1], s[8:9]
	s_cbranch_execz .LBB0_913
	s_waitcnt lgkmcnt(0)
	v_cvt_pk_bf16_f32 v0, v0, v2
	v_add_co_u32_e32 v2, vcc, 0x3000, v82
	s_nop 1
	v_addc_co_u32_e32 v3, vcc, 0, v83, vcc
	global_store_dword v[2:3], v0, off offset:192
.LBB0_913:
	s_or_b64 exec, exec, s[0:1]
	v_rcp_f32_e32 v0, v74
	s_waitcnt lgkmcnt(0)
	v_mul_f32_e32 v2, v38, v0
	s_nop 1
	v_mov_b32_dpp v3, v2 quad_perm:[1,0,3,2] row_mask:0xf bank_mask:0xf
	s_and_saveexec_b64 s[0:1], s[8:9]
	s_cbranch_execz .LBB0_915
	s_waitcnt lgkmcnt(0)
	v_cvt_pk_bf16_f32 v4, v2, v3
	v_add_co_u32_e32 v2, vcc, 0x8000, v82
	s_nop 1
	v_addc_co_u32_e32 v3, vcc, 0, v83, vcc
	global_store_dword v[2:3], v4, off
.LBB0_915:
	s_or_b64 exec, exec, s[0:1]
	v_mul_f32_e32 v2, v54, v0
	s_waitcnt lgkmcnt(0)
	s_nop 1
	v_mov_b32_dpp v3, v2 quad_perm:[1,0,3,2] row_mask:0xf bank_mask:0xf
	s_and_saveexec_b64 s[0:1], s[8:9]
	s_cbranch_execz .LBB0_917
	s_waitcnt lgkmcnt(0)
	v_cvt_pk_bf16_f32 v4, v2, v3
	v_add_co_u32_e32 v2, vcc, 0x8000, v82
	s_nop 1
	v_addc_co_u32_e32 v3, vcc, 0, v83, vcc
	global_store_dword v[2:3], v4, off offset:64
.LBB0_917:
	s_or_b64 exec, exec, s[0:1]
	v_mul_f32_e32 v2, v22, v0
	s_waitcnt lgkmcnt(0)
	s_nop 1
	v_mov_b32_dpp v3, v2 quad_perm:[1,0,3,2] row_mask:0xf bank_mask:0xf
	s_and_saveexec_b64 s[0:1], s[8:9]
	s_cbranch_execz .LBB0_919
	s_waitcnt lgkmcnt(0)
	v_cvt_pk_bf16_f32 v4, v2, v3
	v_add_co_u32_e32 v2, vcc, 0x8000, v82
	s_nop 1
	v_addc_co_u32_e32 v3, vcc, 0, v83, vcc
	global_store_dword v[2:3], v4, off offset:128
.LBB0_919:
	s_or_b64 exec, exec, s[0:1]
	v_mul_f32_e32 v0, v6, v0
	s_nop 1
	v_mov_b32_dpp v2, v0 quad_perm:[1,0,3,2] row_mask:0xf bank_mask:0xf
	s_and_saveexec_b64 s[0:1], s[8:9]
	s_cbranch_execz .LBB0_921
	s_waitcnt lgkmcnt(0)
	v_cvt_pk_bf16_f32 v0, v0, v2
	v_add_co_u32_e32 v2, vcc, 0x8000, v82
	s_nop 1
	v_addc_co_u32_e32 v3, vcc, 0, v83, vcc
	global_store_dword v[2:3], v0, off offset:192
.LBB0_921:
	s_or_b64 exec, exec, s[0:1]
	v_rcp_f32_e32 v0, v75
	s_waitcnt lgkmcnt(0)
	v_mul_f32_e32 v2, v39, v0
	s_nop 1
	v_mov_b32_dpp v3, v2 quad_perm:[1,0,3,2] row_mask:0xf bank_mask:0xf
	s_and_saveexec_b64 s[0:1], s[8:9]
	s_cbranch_execz .LBB0_923
	s_waitcnt lgkmcnt(0)
	v_cvt_pk_bf16_f32 v4, v2, v3
	v_add_co_u32_e32 v2, vcc, 0x9000, v82
	s_nop 1
	v_addc_co_u32_e32 v3, vcc, 0, v83, vcc
	global_store_dword v[2:3], v4, off
.LBB0_923:
	s_or_b64 exec, exec, s[0:1]
	v_mul_f32_e32 v2, v55, v0
	s_waitcnt lgkmcnt(0)
	s_nop 1
	v_mov_b32_dpp v3, v2 quad_perm:[1,0,3,2] row_mask:0xf bank_mask:0xf
	s_and_saveexec_b64 s[0:1], s[8:9]
	s_cbranch_execz .LBB0_925
	s_waitcnt lgkmcnt(0)
	v_cvt_pk_bf16_f32 v4, v2, v3
	v_add_co_u32_e32 v2, vcc, 0x9000, v82
	s_nop 1
	v_addc_co_u32_e32 v3, vcc, 0, v83, vcc
	global_store_dword v[2:3], v4, off offset:64
.LBB0_925:
	s_or_b64 exec, exec, s[0:1]
	v_mul_f32_e32 v2, v23, v0
	s_waitcnt lgkmcnt(0)
	s_nop 1
	v_mov_b32_dpp v3, v2 quad_perm:[1,0,3,2] row_mask:0xf bank_mask:0xf
	s_and_saveexec_b64 s[0:1], s[8:9]
	s_cbranch_execz .LBB0_927
	s_waitcnt lgkmcnt(0)
	v_cvt_pk_bf16_f32 v4, v2, v3
	v_add_co_u32_e32 v2, vcc, 0x9000, v82
	s_nop 1
	v_addc_co_u32_e32 v3, vcc, 0, v83, vcc
	global_store_dword v[2:3], v4, off offset:128
.LBB0_927:
	s_or_b64 exec, exec, s[0:1]
	v_mul_f32_e32 v0, v7, v0
	s_nop 1
	v_mov_b32_dpp v2, v0 quad_perm:[1,0,3,2] row_mask:0xf bank_mask:0xf
	s_and_saveexec_b64 s[0:1], s[8:9]
	s_cbranch_execz .LBB0_929
	s_waitcnt lgkmcnt(0)
	v_cvt_pk_bf16_f32 v0, v0, v2
	v_add_co_u32_e32 v2, vcc, 0x9000, v82
	s_nop 1
	v_addc_co_u32_e32 v3, vcc, 0, v83, vcc
	global_store_dword v[2:3], v0, off offset:192
.LBB0_929:
	s_or_b64 exec, exec, s[0:1]
	v_rcp_f32_e32 v0, v76
	s_waitcnt lgkmcnt(0)
	v_mul_f32_e32 v2, v40, v0
	s_nop 1
	v_mov_b32_dpp v3, v2 quad_perm:[1,0,3,2] row_mask:0xf bank_mask:0xf
	s_and_saveexec_b64 s[0:1], s[8:9]
	s_cbranch_execz .LBB0_931
	s_waitcnt lgkmcnt(0)
	v_cvt_pk_bf16_f32 v4, v2, v3
	v_add_co_u32_e32 v2, vcc, 0xa000, v82
	s_nop 1
	v_addc_co_u32_e32 v3, vcc, 0, v83, vcc
	global_store_dword v[2:3], v4, off
.LBB0_931:
	s_or_b64 exec, exec, s[0:1]
	v_mul_f32_e32 v2, v56, v0
	s_waitcnt lgkmcnt(0)
	s_nop 1
	v_mov_b32_dpp v3, v2 quad_perm:[1,0,3,2] row_mask:0xf bank_mask:0xf
	s_and_saveexec_b64 s[0:1], s[8:9]
	s_cbranch_execz .LBB0_933
	s_waitcnt lgkmcnt(0)
	v_cvt_pk_bf16_f32 v4, v2, v3
	v_add_co_u32_e32 v2, vcc, 0xa000, v82
	s_nop 1
	v_addc_co_u32_e32 v3, vcc, 0, v83, vcc
	global_store_dword v[2:3], v4, off offset:64
; #define GAS __attribute__((address_space(1)))
; __device__ __forceinline__ unsigned cvtpk(float lo, float hi) { unsigned r; asm volatile("v_cvt_pk_bf16_f32 %0, %1, %2" : "=v"(r) : "v"(lo), "v"(hi)); return r; }
; __device__ __forceinline__ int crow(int r, int hi) { return (r & 3) + 8 * (r >> 2) + 4 * hi; }
; template <int DK, int MODE> ...
;     ...
;     if (hi == 0) ws[32 + r32] = l_reg; asm volatile("s_waitcnt lgkmcnt(0)" ::: "memory");
; #pragma unroll
;     for (int r = 0; r < 16; ++r) { const float rl = __builtin_amdgcn_rcpf(ws[32 + crow(r, hi)]);
; #pragma unroll
;         for (int d = 0; d < 4; ++d) o[d][r] *= rl; }
; __device__ __forceinline__ void store_o(const f32x16 (&o)[4], bf16_t* Ow, int pitch, int r32, int hi) {
;     ...
;     for (int r = 0; r < 16; ++r) { const int orow = crow(r, hi);
; #pragma unroll
;         for (int d0 = 0; d0 < 4; ++d0) { const float v = o[d0][r]; const float vn = __shfl_xor(v, 1);
;             if ((r32 & 1) == 0) *(GAS unsigned*)(Ow + (size_t)orow * pitch + d0 * 32 + r32) = cvtpk(v, vn); } }
.LBB0_933:
	s_or_b64 exec, exec, s[0:1]
	v_mul_f32_e32 v2, v24, v0
	s_waitcnt lgkmcnt(0)
	s_nop 1
	v_mov_b32_dpp v3, v2 quad_perm:[1,0,3,2] row_mask:0xf bank_mask:0xf
	s_and_saveexec_b64 s[0:1], s[8:9]
	s_cbranch_execz .LBB0_935
	s_waitcnt lgkmcnt(0)
	v_cvt_pk_bf16_f32 v4, v2, v3
	v_add_co_u32_e32 v2, vcc, 0xa000, v82
	s_nop 1
	v_addc_co_u32_e32 v3, vcc, 0, v83, vcc
	global_store_dword v[2:3], v4, off offset:128
.LBB0_935:
	s_or_b64 exec, exec, s[0:1]
	v_mul_f32_e32 v0, v8, v0
	s_nop 1
	v_mov_b32_dpp v2, v0 quad_perm:[1,0,3,2] row_mask:0xf bank_mask:0xf
	s_and_saveexec_b64 s[0:1], s[8:9]
	s_cbranch_execz .LBB0_937
	s_waitcnt lgkmcnt(0)
	v_cvt_pk_bf16_f32 v0, v0, v2
	v_add_co_u32_e32 v2, vcc, 0xa000, v82
	s_nop 1
	v_addc_co_u32_e32 v3, vcc, 0, v83, vcc
	global_store_dword v[2:3], v0, off offset:192
.LBB0_937:
	s_or_b64 exec, exec, s[0:1]
	v_rcp_f32_e32 v0, v77
	s_waitcnt lgkmcnt(0)
	v_mul_f32_e32 v2, v41, v0
	s_nop 1
	v_mov_b32_dpp v3, v2 quad_perm:[1,0,3,2] row_mask:0xf bank_mask:0xf
	s_and_saveexec_b64 s[0:1], s[8:9]
	s_cbranch_execz .LBB0_939
	s_waitcnt lgkmcnt(0)
	v_cvt_pk_bf16_f32 v4, v2, v3
	v_add_co_u32_e32 v2, vcc, 0xb000, v82
	s_nop 1
	v_addc_co_u32_e32 v3, vcc, 0, v83, vcc
	global_store_dword v[2:3], v4, off
.LBB0_939:
	s_or_b64 exec, exec, s[0:1]
	v_mul_f32_e32 v2, v57, v0
	s_waitcnt lgkmcnt(0)
	s_nop 1
	v_mov_b32_dpp v3, v2 quad_perm:[1,0,3,2] row_mask:0xf bank_mask:0xf
	s_and_saveexec_b64 s[0:1], s[8:9]
	s_cbranch_execz .LBB0_941
	s_waitcnt lgkmcnt(0)
	v_cvt_pk_bf16_f32 v4, v2, v3
	v_add_co_u32_e32 v2, vcc, 0xb000, v82
	s_nop 1
	v_addc_co_u32_e32 v3, vcc, 0, v83, vcc
	global_store_dword v[2:3], v4, off offset:64
.LBB0_941:
	s_or_b64 exec, exec, s[0:1]
	v_mul_f32_e32 v2, v25, v0
	s_waitcnt lgkmcnt(0)
	s_nop 1
	v_mov_b32_dpp v3, v2 quad_perm:[1,0,3,2] row_mask:0xf bank_mask:0xf
	s_and_saveexec_b64 s[0:1], s[8:9]
	s_cbranch_execz .LBB0_943
	s_waitcnt lgkmcnt(0)
	v_cvt_pk_bf16_f32 v4, v2, v3
	v_add_co_u32_e32 v2, vcc, 0xb000, v82
	s_nop 1
	v_addc_co_u32_e32 v3, vcc, 0, v83, vcc
	global_store_dword v[2:3], v4, off offset:128
.LBB0_943:
	s_or_b64 exec, exec, s[0:1]
	v_mul_f32_e32 v0, v9, v0
	s_nop 1
	v_mov_b32_dpp v2, v0 quad_perm:[1,0,3,2] row_mask:0xf bank_mask:0xf
	s_and_saveexec_b64 s[0:1], s[8:9]
	s_cbranch_execz .LBB0_945
	s_waitcnt lgkmcnt(0)
	v_cvt_pk_bf16_f32 v0, v0, v2
	v_add_co_u32_e32 v2, vcc, 0xb000, v82
	s_nop 1
	v_addc_co_u32_e32 v3, vcc, 0, v83, vcc
	global_store_dword v[2:3], v0, off offset:192
.LBB0_945:
	s_or_b64 exec, exec, s[0:1]
	v_rcp_f32_e32 v0, v70
	s_waitcnt lgkmcnt(0)
	v_mul_f32_e32 v2, v42, v0
	s_nop 1
	v_mov_b32_dpp v3, v2 quad_perm:[1,0,3,2] row_mask:0xf bank_mask:0xf
	s_and_saveexec_b64 s[0:1], s[8:9]
	s_cbranch_execz .LBB0_947
	s_waitcnt lgkmcnt(0)
	v_cvt_pk_bf16_f32 v4, v2, v3
	v_add_co_u32_e32 v2, vcc, 0x10000, v82
	s_nop 1
	v_addc_co_u32_e32 v3, vcc, 0, v83, vcc
	global_store_dword v[2:3], v4, off
.LBB0_947:
	s_or_b64 exec, exec, s[0:1]
	v_mul_f32_e32 v2, v58, v0
	s_waitcnt lgkmcnt(0)
	s_nop 1
	v_mov_b32_dpp v3, v2 quad_perm:[1,0,3,2] row_mask:0xf bank_mask:0xf
	s_and_saveexec_b64 s[0:1], s[8:9]
	s_cbranch_execz .LBB0_949
	s_waitcnt lgkmcnt(0)
	v_cvt_pk_bf16_f32 v4, v2, v3
	v_add_co_u32_e32 v2, vcc, 0x10000, v82
	s_nop 1
	v_addc_co_u32_e32 v3, vcc, 0, v83, vcc
	global_store_dword v[2:3], v4, off offset:64
.LBB0_949:
	s_or_b64 exec, exec, s[0:1]
	v_mul_f32_e32 v2, v26, v0
	s_waitcnt lgkmcnt(0)
	s_nop 1
	v_mov_b32_dpp v3, v2 quad_perm:[1,0,3,2] row_mask:0xf bank_mask:0xf
	s_and_saveexec_b64 s[0:1], s[8:9]
	s_cbranch_execz .LBB0_951
	s_waitcnt lgkmcnt(0)
	v_cvt_pk_bf16_f32 v4, v2, v3
	v_add_co_u32_e32 v2, vcc, 0x10000, v82
	s_nop 1
	v_addc_co_u32_e32 v3, vcc, 0, v83, vcc
	global_store_dword v[2:3], v4, off offset:128
.LBB0_951:
	s_or_b64 exec, exec, s[0:1]
	v_mul_f32_e32 v0, v10, v0
	s_nop 1
	v_mov_b32_dpp v2, v0 quad_perm:[1,0,3,2] row_mask:0xf bank_mask:0xf
	s_and_saveexec_b64 s[0:1], s[8:9]
	s_cbranch_execz .LBB0_953
	s_waitcnt lgkmcnt(0)
	v_cvt_pk_bf16_f32 v0, v0, v2
	v_add_co_u32_e32 v2, vcc, 0x10000, v82
	s_nop 1
	v_addc_co_u32_e32 v3, vcc, 0, v83, vcc
	global_store_dword v[2:3], v0, off offset:192
.LBB0_953:
	s_or_b64 exec, exec, s[0:1]
	v_rcp_f32_e32 v0, v71
	s_waitcnt lgkmcnt(0)
	v_mul_f32_e32 v2, v43, v0
	s_nop 1
	v_mov_b32_dpp v3, v2 quad_perm:[1,0,3,2] row_mask:0xf bank_mask:0xf
	s_and_saveexec_b64 s[0:1], s[8:9]
	s_cbranch_execz .LBB0_955
	s_waitcnt lgkmcnt(0)
	v_cvt_pk_bf16_f32 v4, v2, v3
	v_add_co_u32_e32 v2, vcc, 0x11000, v82
	s_nop 1
	v_addc_co_u32_e32 v3, vcc, 0, v83, vcc
	global_store_dword v[2:3], v4, off
.LBB0_955:
	s_or_b64 exec, exec, s[0:1]
	v_mul_f32_e32 v2, v59, v0
	s_waitcnt lgkmcnt(0)
	s_nop 1
	v_mov_b32_dpp v3, v2 quad_perm:[1,0,3,2] row_mask:0xf bank_mask:0xf
	s_and_saveexec_b64 s[0:1], s[8:9]
	s_cbranch_execz .LBB0_957
	s_waitcnt lgkmcnt(0)
	v_cvt_pk_bf16_f32 v4, v2, v3
	v_add_co_u32_e32 v2, vcc, 0x11000, v82
	s_nop 1
	v_addc_co_u32_e32 v3, vcc, 0, v83, vcc
	global_store_dword v[2:3], v4, off offset:64
.LBB0_957:
	s_or_b64 exec, exec, s[0:1]
	v_mul_f32_e32 v2, v27, v0
	s_waitcnt lgkmcnt(0)
	s_nop 1
	v_mov_b32_dpp v3, v2 quad_perm:[1,0,3,2] row_mask:0xf bank_mask:0xf
	s_and_saveexec_b64 s[0:1], s[8:9]
	s_cbranch_execz .LBB0_959
	s_waitcnt lgkmcnt(0)
	v_cvt_pk_bf16_f32 v4, v2, v3
	v_add_co_u32_e32 v2, vcc, 0x11000, v82
	s_nop 1
	v_addc_co_u32_e32 v3, vcc, 0, v83, vcc
	global_store_dword v[2:3], v4, off offset:128
.LBB0_959:
	s_or_b64 exec, exec, s[0:1]
	v_mul_f32_e32 v0, v11, v0
	s_nop 1
	v_mov_b32_dpp v2, v0 quad_perm:[1,0,3,2] row_mask:0xf bank_mask:0xf
	s_and_saveexec_b64 s[0:1], s[8:9]
	s_cbranch_execz .LBB0_961
	s_waitcnt lgkmcnt(0)
	v_cvt_pk_bf16_f32 v0, v0, v2
	v_add_co_u32_e32 v2, vcc, 0x11000, v82
	s_nop 1
	v_addc_co_u32_e32 v3, vcc, 0, v83, vcc
	global_store_dword v[2:3], v0, off offset:192
; #define GAS __attribute__((address_space(1)))
; __device__ __forceinline__ unsigned cvtpk(float lo, float hi) { unsigned r; asm volatile("v_cvt_pk_bf16_f32 %0, %1, %2" : "=v"(r) : "v"(lo), "v"(hi)); return r; }
; __device__ __forceinline__ int crow(int r, int hi) { return (r & 3) + 8 * (r >> 2) + 4 * hi; }
; template <int DK, int MODE> ...
;     ...
;     if (hi == 0) ws[32 + r32] = l_reg; asm volatile("s_waitcnt lgkmcnt(0)" ::: "memory");
; #pragma unroll
;     for (int r = 0; r < 16; ++r) { const float rl = __builtin_amdgcn_rcpf(ws[32 + crow(r, hi)]);
; #pragma unroll
;         for (int d = 0; d < 4; ++d) o[d][r] *= rl; }
; __device__ __forceinline__ void store_o(const f32x16 (&o)[4], bf16_t* Ow, int pitch, int r32, int hi) {
;     ...
;     for (int r = 0; r < 16; ++r) { const int orow = crow(r, hi);
; #pragma unroll
;         for (int d0 = 0; d0 < 4; ++d0) { const float v = o[d0][r]; const float vn = __shfl_xor(v, 1);
;             if ((r32 & 1) == 0) *(GAS unsigned*)(Ow + (size_t)orow * pitch + d0 * 32 + r32) = cvtpk(v, vn); } }
.LBB0_961:
	s_or_b64 exec, exec, s[0:1]
	v_rcp_f32_e32 v0, v72
	s_waitcnt lgkmcnt(0)
	v_mul_f32_e32 v2, v44, v0
	s_nop 1
	v_mov_b32_dpp v3, v2 quad_perm:[1,0,3,2] row_mask:0xf bank_mask:0xf
	s_and_saveexec_b64 s[0:1], s[8:9]
	s_cbranch_execz .LBB0_963
	s_waitcnt lgkmcnt(0)
	v_cvt_pk_bf16_f32 v4, v2, v3
	v_add_co_u32_e32 v2, vcc, 0x12000, v82
	s_nop 1
	v_addc_co_u32_e32 v3, vcc, 0, v83, vcc
	global_store_dword v[2:3], v4, off
.LBB0_963:
	s_or_b64 exec, exec, s[0:1]
	v_mul_f32_e32 v2, v60, v0
	s_waitcnt lgkmcnt(0)
	s_nop 1
	v_mov_b32_dpp v3, v2 quad_perm:[1,0,3,2] row_mask:0xf bank_mask:0xf
	s_and_saveexec_b64 s[0:1], s[8:9]
	s_cbranch_execz .LBB0_965
	s_waitcnt lgkmcnt(0)
	v_cvt_pk_bf16_f32 v4, v2, v3
	v_add_co_u32_e32 v2, vcc, 0x12000, v82
	s_nop 1
	v_addc_co_u32_e32 v3, vcc, 0, v83, vcc
	global_store_dword v[2:3], v4, off offset:64
.LBB0_965:
	s_or_b64 exec, exec, s[0:1]
	v_mul_f32_e32 v2, v28, v0
	s_waitcnt lgkmcnt(0)
	s_nop 1
	v_mov_b32_dpp v3, v2 quad_perm:[1,0,3,2] row_mask:0xf bank_mask:0xf
	s_and_saveexec_b64 s[0:1], s[8:9]
	s_cbranch_execz .LBB0_967
	s_waitcnt lgkmcnt(0)
	v_cvt_pk_bf16_f32 v4, v2, v3
	v_add_co_u32_e32 v2, vcc, 0x12000, v82
	s_nop 1
	v_addc_co_u32_e32 v3, vcc, 0, v83, vcc
	global_store_dword v[2:3], v4, off offset:128
.LBB0_967:
	s_or_b64 exec, exec, s[0:1]
	v_mul_f32_e32 v0, v12, v0
	s_nop 1
	v_mov_b32_dpp v2, v0 quad_perm:[1,0,3,2] row_mask:0xf bank_mask:0xf
	s_and_saveexec_b64 s[0:1], s[8:9]
	s_cbranch_execz .LBB0_969
	s_waitcnt lgkmcnt(0)
	v_cvt_pk_bf16_f32 v0, v0, v2
	v_add_co_u32_e32 v2, vcc, 0x12000, v82
	s_nop 1
	v_addc_co_u32_e32 v3, vcc, 0, v83, vcc
	global_store_dword v[2:3], v0, off offset:192
.LBB0_969:
	s_or_b64 exec, exec, s[0:1]
	v_rcp_f32_e32 v0, v73
	s_waitcnt lgkmcnt(0)
	v_mul_f32_e32 v2, v45, v0
	s_nop 1
	v_mov_b32_dpp v3, v2 quad_perm:[1,0,3,2] row_mask:0xf bank_mask:0xf
	s_and_saveexec_b64 s[0:1], s[8:9]
	s_cbranch_execz .LBB0_971
	s_waitcnt lgkmcnt(0)
	v_cvt_pk_bf16_f32 v4, v2, v3
	v_add_co_u32_e32 v2, vcc, 0x13000, v82
	s_nop 1
	v_addc_co_u32_e32 v3, vcc, 0, v83, vcc
	global_store_dword v[2:3], v4, off
.LBB0_971:
	s_or_b64 exec, exec, s[0:1]
	v_mul_f32_e32 v2, v61, v0
	s_waitcnt lgkmcnt(0)
	s_nop 1
	v_mov_b32_dpp v3, v2 quad_perm:[1,0,3,2] row_mask:0xf bank_mask:0xf
	s_and_saveexec_b64 s[0:1], s[8:9]
	s_cbranch_execz .LBB0_973
	s_waitcnt lgkmcnt(0)
	v_cvt_pk_bf16_f32 v4, v2, v3
	v_add_co_u32_e32 v2, vcc, 0x13000, v82
	s_nop 1
	v_addc_co_u32_e32 v3, vcc, 0, v83, vcc
	global_store_dword v[2:3], v4, off offset:64
.LBB0_973:
	s_or_b64 exec, exec, s[0:1]
	v_mul_f32_e32 v2, v29, v0
	s_waitcnt lgkmcnt(0)
	s_nop 1
	v_mov_b32_dpp v3, v2 quad_perm:[1,0,3,2] row_mask:0xf bank_mask:0xf
	s_and_saveexec_b64 s[0:1], s[8:9]
	s_cbranch_execz .LBB0_975
	s_waitcnt lgkmcnt(0)
	v_cvt_pk_bf16_f32 v4, v2, v3
	v_add_co_u32_e32 v2, vcc, 0x13000, v82
	s_nop 1
	v_addc_co_u32_e32 v3, vcc, 0, v83, vcc
	global_store_dword v[2:3], v4, off offset:128
.LBB0_975:
	s_or_b64 exec, exec, s[0:1]
	v_mul_f32_e32 v0, v13, v0
	s_nop 1
	v_mov_b32_dpp v2, v0 quad_perm:[1,0,3,2] row_mask:0xf bank_mask:0xf
	s_and_saveexec_b64 s[0:1], s[8:9]
	s_cbranch_execz .LBB0_977
	s_waitcnt lgkmcnt(0)
	v_cvt_pk_bf16_f32 v0, v0, v2
	v_add_co_u32_e32 v2, vcc, 0x13000, v82
	s_nop 1
	v_addc_co_u32_e32 v3, vcc, 0, v83, vcc
	global_store_dword v[2:3], v0, off offset:192
.LBB0_977:
	s_or_b64 exec, exec, s[0:1]
	v_rcp_f32_e32 v0, v66
	s_waitcnt lgkmcnt(0)
	v_mul_f32_e32 v2, v46, v0
	s_nop 1
	v_mov_b32_dpp v3, v2 quad_perm:[1,0,3,2] row_mask:0xf bank_mask:0xf
	s_and_saveexec_b64 s[0:1], s[8:9]
	s_cbranch_execz .LBB0_979
	s_waitcnt lgkmcnt(0)
	v_cvt_pk_bf16_f32 v4, v2, v3
	v_add_co_u32_e32 v2, vcc, 0x18000, v82
	s_nop 1
	v_addc_co_u32_e32 v3, vcc, 0, v83, vcc
	global_store_dword v[2:3], v4, off
.LBB0_979:
	s_or_b64 exec, exec, s[0:1]
	v_mul_f32_e32 v2, v62, v0
	s_waitcnt lgkmcnt(0)
	s_nop 1
	v_mov_b32_dpp v3, v2 quad_perm:[1,0,3,2] row_mask:0xf bank_mask:0xf
	s_and_saveexec_b64 s[0:1], s[8:9]
	s_cbranch_execz .LBB0_981
	s_waitcnt lgkmcnt(0)
	v_cvt_pk_bf16_f32 v4, v2, v3
	v_add_co_u32_e32 v2, vcc, 0x18000, v82
	s_nop 1
	v_addc_co_u32_e32 v3, vcc, 0, v83, vcc
	global_store_dword v[2:3], v4, off offset:64
.LBB0_981:
	s_or_b64 exec, exec, s[0:1]
	v_mul_f32_e32 v2, v30, v0
	s_waitcnt lgkmcnt(0)
	s_nop 1
	v_mov_b32_dpp v3, v2 quad_perm:[1,0,3,2] row_mask:0xf bank_mask:0xf
	s_and_saveexec_b64 s[0:1], s[8:9]
	s_cbranch_execz .LBB0_983
	s_waitcnt lgkmcnt(0)
	v_cvt_pk_bf16_f32 v4, v2, v3
	v_add_co_u32_e32 v2, vcc, 0x18000, v82
	s_nop 1
	v_addc_co_u32_e32 v3, vcc, 0, v83, vcc
	global_store_dword v[2:3], v4, off offset:128
.LBB0_983:
	s_or_b64 exec, exec, s[0:1]
	v_mul_f32_e32 v0, v14, v0
	s_nop 1
	v_mov_b32_dpp v2, v0 quad_perm:[1,0,3,2] row_mask:0xf bank_mask:0xf
	s_and_saveexec_b64 s[0:1], s[8:9]
	s_cbranch_execz .LBB0_985
	s_waitcnt lgkmcnt(0)
	v_cvt_pk_bf16_f32 v0, v0, v2
	v_add_co_u32_e32 v2, vcc, 0x18000, v82
	s_nop 1
	v_addc_co_u32_e32 v3, vcc, 0, v83, vcc
	global_store_dword v[2:3], v0, off offset:192
; #define GAS __attribute__((address_space(1)))
; __device__ __forceinline__ unsigned cvtpk(float lo, float hi) { unsigned r; asm volatile("v_cvt_pk_bf16_f32 %0, %1, %2" : "=v"(r) : "v"(lo), "v"(hi)); return r; }
; __device__ __forceinline__ int crow(int r, int hi) { return (r & 3) + 8 * (r >> 2) + 4 * hi; }
; template <int DK, int MODE> ...
;     ...
;     if (hi == 0) ws[32 + r32] = l_reg; asm volatile("s_waitcnt lgkmcnt(0)" ::: "memory");
; #pragma unroll
;     for (int r = 0; r < 16; ++r) { const float rl = __builtin_amdgcn_rcpf(ws[32 + crow(r, hi)]);
; #pragma unroll
;         for (int d = 0; d < 4; ++d) o[d][r] *= rl; }
; __device__ __forceinline__ void store_o(const f32x16 (&o)[4], bf16_t* Ow, int pitch, int r32, int hi) {
;     ...
;     for (int r = 0; r < 16; ++r) { const int orow = crow(r, hi);
; #pragma unroll
;         for (int d0 = 0; d0 < 4; ++d0) { const float v = o[d0][r]; const float vn = __shfl_xor(v, 1);
;             if ((r32 & 1) == 0) *(GAS unsigned*)(Ow + (size_t)orow * pitch + d0 * 32 + r32) = cvtpk(v, vn); } }
.LBB0_985:
	s_or_b64 exec, exec, s[0:1]
	v_rcp_f32_e32 v0, v67
	s_waitcnt lgkmcnt(0)
	v_mul_f32_e32 v2, v47, v0
	s_nop 1
	v_mov_b32_dpp v3, v2 quad_perm:[1,0,3,2] row_mask:0xf bank_mask:0xf
	s_and_saveexec_b64 s[0:1], s[8:9]
	s_cbranch_execz .LBB0_987
	s_waitcnt lgkmcnt(0)
	v_cvt_pk_bf16_f32 v4, v2, v3
	v_add_co_u32_e32 v2, vcc, 0x19000, v82
	s_nop 1
	v_addc_co_u32_e32 v3, vcc, 0, v83, vcc
	global_store_dword v[2:3], v4, off
.LBB0_987:
	s_or_b64 exec, exec, s[0:1]
	v_mul_f32_e32 v2, v63, v0
	s_waitcnt lgkmcnt(0)
	s_nop 1
	v_mov_b32_dpp v3, v2 quad_perm:[1,0,3,2] row_mask:0xf bank_mask:0xf
	s_and_saveexec_b64 s[0:1], s[8:9]
	s_cbranch_execz .LBB0_989
	s_waitcnt lgkmcnt(0)
	v_cvt_pk_bf16_f32 v4, v2, v3
	v_add_co_u32_e32 v2, vcc, 0x19000, v82
	s_nop 1
	v_addc_co_u32_e32 v3, vcc, 0, v83, vcc
	global_store_dword v[2:3], v4, off offset:64
.LBB0_989:
	s_or_b64 exec, exec, s[0:1]
	v_mul_f32_e32 v2, v31, v0
	s_waitcnt lgkmcnt(0)
	s_nop 1
	v_mov_b32_dpp v3, v2 quad_perm:[1,0,3,2] row_mask:0xf bank_mask:0xf
	s_and_saveexec_b64 s[0:1], s[8:9]
	s_cbranch_execz .LBB0_991
	s_waitcnt lgkmcnt(0)
	v_cvt_pk_bf16_f32 v4, v2, v3
	v_add_co_u32_e32 v2, vcc, 0x19000, v82
	s_nop 1
	v_addc_co_u32_e32 v3, vcc, 0, v83, vcc
	global_store_dword v[2:3], v4, off offset:128
.LBB0_991:
	s_or_b64 exec, exec, s[0:1]
	v_mul_f32_e32 v0, v15, v0
	s_nop 1
	v_mov_b32_dpp v2, v0 quad_perm:[1,0,3,2] row_mask:0xf bank_mask:0xf
	s_and_saveexec_b64 s[0:1], s[8:9]
	s_cbranch_execz .LBB0_993
	s_waitcnt lgkmcnt(0)
	v_cvt_pk_bf16_f32 v0, v0, v2
	v_add_co_u32_e32 v2, vcc, 0x19000, v82
	s_nop 1
	v_addc_co_u32_e32 v3, vcc, 0, v83, vcc
	global_store_dword v[2:3], v0, off offset:192
.LBB0_993:
	s_or_b64 exec, exec, s[0:1]
	v_rcp_f32_e32 v0, v68
	s_waitcnt lgkmcnt(0)
	v_mul_f32_e32 v2, v48, v0
	s_nop 1
	v_mov_b32_dpp v3, v2 quad_perm:[1,0,3,2] row_mask:0xf bank_mask:0xf
	s_and_saveexec_b64 s[0:1], s[8:9]
	s_cbranch_execz .LBB0_995
	s_waitcnt lgkmcnt(0)
	v_cvt_pk_bf16_f32 v4, v2, v3
	v_add_co_u32_e32 v2, vcc, 0x1a000, v82
	s_nop 1
	v_addc_co_u32_e32 v3, vcc, 0, v83, vcc
	global_store_dword v[2:3], v4, off
.LBB0_995:
	s_or_b64 exec, exec, s[0:1]
	v_mul_f32_e32 v2, v64, v0
	s_waitcnt lgkmcnt(0)
	s_nop 1
	v_mov_b32_dpp v3, v2 quad_perm:[1,0,3,2] row_mask:0xf bank_mask:0xf
	s_and_saveexec_b64 s[0:1], s[8:9]
	s_cbranch_execz .LBB0_997
	s_waitcnt lgkmcnt(0)
	v_cvt_pk_bf16_f32 v4, v2, v3
	v_add_co_u32_e32 v2, vcc, 0x1a000, v82
	s_nop 1
	v_addc_co_u32_e32 v3, vcc, 0, v83, vcc
	global_store_dword v[2:3], v4, off offset:64
.LBB0_997:
	s_or_b64 exec, exec, s[0:1]
	v_mul_f32_e32 v2, v32, v0
	s_waitcnt lgkmcnt(0)
	s_nop 1
	v_mov_b32_dpp v3, v2 quad_perm:[1,0,3,2] row_mask:0xf bank_mask:0xf
	s_and_saveexec_b64 s[0:1], s[8:9]
	s_cbranch_execz .LBB0_999
	s_waitcnt lgkmcnt(0)
	v_cvt_pk_bf16_f32 v4, v2, v3
	v_add_co_u32_e32 v2, vcc, 0x1a000, v82
	s_nop 1
	v_addc_co_u32_e32 v3, vcc, 0, v83, vcc
	global_store_dword v[2:3], v4, off offset:128
.LBB0_999:
	s_or_b64 exec, exec, s[0:1]
	v_mul_f32_e32 v0, v16, v0
	s_nop 1
	v_mov_b32_dpp v2, v0 quad_perm:[1,0,3,2] row_mask:0xf bank_mask:0xf
	s_and_saveexec_b64 s[0:1], s[8:9]
	s_cbranch_execz .LBB0_1001
	s_waitcnt lgkmcnt(0)
	v_cvt_pk_bf16_f32 v0, v0, v2
	v_add_co_u32_e32 v2, vcc, 0x1a000, v82
	s_nop 1
	v_addc_co_u32_e32 v3, vcc, 0, v83, vcc
	global_store_dword v[2:3], v0, off offset:192
.LBB0_1001:
	s_or_b64 exec, exec, s[0:1]
	v_rcp_f32_e32 v0, v69
	s_waitcnt lgkmcnt(0)
	v_mul_f32_e32 v2, v49, v0
	s_nop 1
	v_mov_b32_dpp v3, v2 quad_perm:[1,0,3,2] row_mask:0xf bank_mask:0xf
	s_and_saveexec_b64 s[0:1], s[8:9]
	s_cbranch_execz .LBB0_1003
	s_waitcnt lgkmcnt(0)
	v_cvt_pk_bf16_f32 v4, v2, v3
	v_add_co_u32_e32 v2, vcc, 0x1b000, v82
	s_nop 1
	v_addc_co_u32_e32 v3, vcc, 0, v83, vcc
	global_store_dword v[2:3], v4, off
.LBB0_1003:
	s_or_b64 exec, exec, s[0:1]
	v_mul_f32_e32 v2, v65, v0
	s_waitcnt lgkmcnt(0)
	s_nop 1
	v_mov_b32_dpp v3, v2 quad_perm:[1,0,3,2] row_mask:0xf bank_mask:0xf
	s_and_saveexec_b64 s[0:1], s[8:9]
	s_cbranch_execz .LBB0_1005
	s_waitcnt lgkmcnt(0)
	v_cvt_pk_bf16_f32 v4, v2, v3
	v_add_co_u32_e32 v2, vcc, 0x1b000, v82
	s_nop 1
	v_addc_co_u32_e32 v3, vcc, 0, v83, vcc
	global_store_dword v[2:3], v4, off offset:64
.LBB0_1005:
	s_or_b64 exec, exec, s[0:1]
	v_mul_f32_e32 v2, v33, v0
	s_waitcnt lgkmcnt(0)
	s_nop 1
	v_mov_b32_dpp v3, v2 quad_perm:[1,0,3,2] row_mask:0xf bank_mask:0xf
	s_and_saveexec_b64 s[0:1], s[8:9]
	s_cbranch_execz .LBB0_1007
	s_waitcnt lgkmcnt(0)
	v_cvt_pk_bf16_f32 v4, v2, v3
	v_add_co_u32_e32 v2, vcc, 0x1b000, v82
	s_nop 1
	v_addc_co_u32_e32 v3, vcc, 0, v83, vcc
	global_store_dword v[2:3], v4, off offset:128
.LBB0_1007:
	s_or_b64 exec, exec, s[0:1]
	v_mul_f32_e32 v0, v17, v0
	s_nop 1
	v_mov_b32_dpp v2, v0 quad_perm:[1,0,3,2] row_mask:0xf bank_mask:0xf
	s_and_saveexec_b64 s[0:1], s[8:9]
	s_xor_b64 s[0:1], exec, s[0:1]
	s_cbranch_execz .LBB0_1009
	s_waitcnt lgkmcnt(0)
	v_cvt_pk_bf16_f32 v0, v0, v2
	v_add_co_u32_e32 v2, vcc, 0x1b000, v82
	s_nop 1
	v_addc_co_u32_e32 v3, vcc, 0, v83, vcc
	global_store_dword v[2:3], v0, off offset:192

; #define GAS __attribute__((address_space(1)))
; __device__ __forceinline__ unsigned cvtpk(float lo, float hi) { unsigned r; asm volatile("v_cvt_pk_bf16_f32 %0, %1, %2" : "=v"(r) : "v"(lo), "v"(hi)); return r; }
; __device__ __forceinline__ int crow(int r, int hi) { return (r & 3) + 8 * (r >> 2) + 4 * hi; }
; __device__ __forceinline__ void store_o(const f32x16 (&o)[4], bf16_t* Ow, int pitch, int r32, int hi) {
;     ...
;     for (int r = 0; r < 16; ++r) { const int orow = crow(r, hi);
; #pragma unroll
;         for (int d0 = 0; d0 < 4; ++d0) { const float v = o[d0][r]; const float vn = __shfl_xor(v, 1);
;             if ((r32 & 1) == 0) *(GAS unsigned*)(Ow + (size_t)orow * pitch + d0 * 32 + r32) = cvtpk(v, vn); } }
; __device__ __forceinline__ void ph_attn(const Args& a, char* lds, int l, int rep) {
;     ...
;             for (int r = 0; r < 16; ++r) { float ss = 0.f;
; #pragma unroll
;                 for (int d = 0; d < 4; ++d) { const unsigned pw = o1p[d][r >> 1]; const float o1v = __uint_as_float((r & 1) ? (pw & 0xffff0000u) : (pw << 16)); const float v = o1v - lam * o[d][r]; o[d][r] = v; ss += v * v; }
;                 ss += __shfl_xor(ss, 1); ss += __shfl_xor(ss, 2); ss += __shfl_xor(ss, 4); ss += __shfl_xor(ss, 8); ss += __shfl_xor(ss, 16);
;                 const float rs = 1.0f / sqrtf(ss * (1.0f / 128.0f) + EPSN);
; #pragma unroll
;                 for (int d = 0; d < 4; ++d) o[d][r] *= rs * gd[d]; }
;             att::store_o(o, MIX + qrow * DM + 1536 + h * 128, DM, r32, hi);
.LBB0_1044:
	s_or_b64 exec, exec, s[0:1]
	v_mul_f32_e32 v14, v149, v14
	v_mul_f32_e32 v0, v14, v101
	v_mul_f32_e32 v0, v12, v0
	s_nop 1
	v_mov_b32_dpp v12, v0 quad_perm:[1,0,3,2] row_mask:0xf bank_mask:0xf
	s_and_saveexec_b64 s[0:1], s[8:9]
	s_cbranch_execz .LBB0_1046
	s_waitcnt lgkmcnt(0)
	v_cvt_pk_bf16_f32 v0, v0, v12
	global_store_dword v[4:5], v0, off offset:3136
.LBB0_1046:
	s_or_b64 exec, exec, s[0:1]
	s_waitcnt lgkmcnt(0)
	v_mul_f32_e32 v12, v149, v102
	v_mul_f32_e32 v0, v12, v101
	v_mul_f32_e32 v0, v98, v0
	s_nop 1
	v_mov_b32_dpp v98, v0 quad_perm:[1,0,3,2] row_mask:0xf bank_mask:0xf
	s_and_saveexec_b64 s[0:1], s[8:9]
	s_cbranch_execz .LBB0_1048
	s_waitcnt lgkmcnt(0)
	v_cvt_pk_bf16_f32 v0, v0, v98
	global_store_dword v[4:5], v0, off offset:3200
.LBB0_1048:
	s_or_b64 exec, exec, s[0:1]
	v_mul_f32_e32 v0, v149, v100
	s_waitcnt lgkmcnt(0)
	v_mul_f32_e32 v98, v0, v101
	v_mul_f32_e32 v95, v95, v98
	s_nop 1
	v_mov_b32_dpp v98, v95 quad_perm:[1,0,3,2] row_mask:0xf bank_mask:0xf
	s_and_saveexec_b64 s[0:1], s[8:9]
	s_cbranch_execz .LBB0_1050
	s_waitcnt lgkmcnt(0)
	v_cvt_pk_bf16_f32 v95, v95, v98
	global_store_dword v[4:5], v95, off offset:3264
.LBB0_1050:
	s_or_b64 exec, exec, s[0:1]
	v_add_f32_e32 v4, v104, v105
	v_fmamk_f32 v4, v4, 0x3c000000, v241
	s_mov_b32 s0, 0xf800000
	v_mul_f32_e32 v5, 0x4f800000, v4
	v_cmp_gt_f32_e32 vcc, s0, v4
	s_nop 1
	v_cndmask_b32_e32 v4, v4, v5, vcc
	v_sqrt_f32_e32 v5, v4
	s_nop 0
	v_add_u32_e32 v95, -1, v5
	v_fma_f32 v100, -v95, v5, v4
	s_waitcnt lgkmcnt(0)
	v_add_u32_e32 v98, 1, v5
	v_cmp_ge_f32_e64 s[10:11], 0, v100
	s_nop 1
	v_cndmask_b32_e64 v95, v5, v95, s[10:11]
	v_fma_f32 v5, -v98, v5, v4
	v_cmp_lt_f32_e64 s[10:11], 0, v5
	s_nop 1
	v_cndmask_b32_e64 v5, v95, v98, s[10:11]
	v_mul_f32_e32 v95, 0x37800000, v5
	v_cndmask_b32_e32 v5, v5, v95, vcc
	v_cmp_class_f32_e32 vcc, v4, v247
	s_nop 1
	v_cndmask_b32_e32 v4, v5, v4, vcc
	v_div_scale_f32 v5, s[0:1], v4, v4, 1.0
	v_rcp_f32_e32 v95, v5
	s_nop 0
	v_fma_f32 v98, -v5, v95, 1.0
	v_fmac_f32_e32 v95, v98, v95
	v_div_scale_f32 v98, vcc, 1.0, v4, 1.0
	v_mul_f32_e32 v100, v98, v95
	v_fma_f32 v101, -v5, v100, v98
	v_fmac_f32_e32 v100, v101, v95
	v_fma_f32 v5, -v5, v100, v98
	v_div_fmas_f32 v5, v5, v95, v100
	v_div_fixup_f32 v4, v5, v4, 1.0
	v_mul_f32_e32 v5, v7, v4
	v_mul_f32_e32 v5, v99, v5
	s_nop 1
	v_mov_b32_dpp v95, v5 quad_perm:[1,0,3,2] row_mask:0xf bank_mask:0xf
	s_and_saveexec_b64 s[0:1], s[8:9]
	s_cbranch_execz .LBB0_1052
	v_add_co_u32_e32 v98, vcc, 0x1000, v2
	s_waitcnt lgkmcnt(0)
	v_cvt_pk_bf16_f32 v5, v5, v95
	s_nop 0
	v_addc_co_u32_e32 v99, vcc, 0, v3, vcc
	global_store_dword v[98:99], v5, off
.LBB0_1052:
	s_or_b64 exec, exec, s[0:1]
	v_mul_f32_e32 v5, v14, v4
	v_mul_f32_e32 v5, v94, v5
	s_nop 1
	v_mov_b32_dpp v94, v5 quad_perm:[1,0,3,2] row_mask:0xf bank_mask:0xf
	s_and_saveexec_b64 s[0:1], s[8:9]
	s_cbranch_execz .LBB0_1054
	s_waitcnt lgkmcnt(0)
	v_cvt_pk_bf16_f32 v5, v5, v94
	v_add_co_u32_e32 v94, vcc, 0x1000, v2
	s_nop 1
	v_addc_co_u32_e32 v95, vcc, 0, v3, vcc
	global_store_dword v[94:95], v5, off offset:64
.LBB0_1054:
	s_or_b64 exec, exec, s[0:1]
	v_mul_f32_e32 v5, v12, v4
	v_mul_f32_e32 v5, v93, v5
	s_nop 1
	v_mov_b32_dpp v93, v5 quad_perm:[1,0,3,2] row_mask:0xf bank_mask:0xf
	s_and_saveexec_b64 s[0:1], s[8:9]
	s_cbranch_execz .LBB0_1056
	s_waitcnt lgkmcnt(1)
	v_add_co_u32_e32 v94, vcc, 0x1000, v2
	s_waitcnt lgkmcnt(0)
	v_cvt_pk_bf16_f32 v5, v5, v93
	s_nop 0
	v_addc_co_u32_e32 v95, vcc, 0, v3, vcc
	global_store_dword v[94:95], v5, off offset:128
.LBB0_1056:
	s_or_b64 exec, exec, s[0:1]
	v_mul_f32_e32 v4, v0, v4
	v_mul_f32_e32 v4, v92, v4
	s_nop 1
	v_mov_b32_dpp v5, v4 quad_perm:[1,0,3,2] row_mask:0xf bank_mask:0xf
	s_and_saveexec_b64 s[0:1], s[8:9]
	s_cbranch_execz .LBB0_1058
	s_waitcnt lgkmcnt(0)
	v_cvt_pk_bf16_f32 v92, v4, v5
	v_add_co_u32_e32 v4, vcc, 0x1000, v2
	s_nop 1
	v_addc_co_u32_e32 v5, vcc, 0, v3, vcc
	global_store_dword v[4:5], v92, off offset:192
.LBB0_1058:
	s_or_b64 exec, exec, s[0:1]
	v_add_f32_e32 v4, v96, v97
	v_fmamk_f32 v4, v4, 0x3c000000, v241
	s_mov_b32 s0, 0xf800000
	s_waitcnt lgkmcnt(0)
	v_mul_f32_e32 v5, 0x4f800000, v4
	v_cmp_gt_f32_e32 vcc, s0, v4
	s_nop 1
	v_cndmask_b32_e32 v4, v4, v5, vcc
	v_sqrt_f32_e32 v5, v4
	s_nop 0
	v_add_u32_e32 v92, -1, v5
	v_fma_f32 v94, -v92, v5, v4
	v_add_u32_e32 v93, 1, v5
	v_cmp_ge_f32_e64 s[10:11], 0, v94
	s_nop 1
	v_cndmask_b32_e64 v92, v5, v92, s[10:11]
	v_fma_f32 v5, -v93, v5, v4
	v_cmp_lt_f32_e64 s[10:11], 0, v5
	s_nop 1
	v_cndmask_b32_e64 v5, v92, v93, s[10:11]
	v_mul_f32_e32 v92, 0x37800000, v5
	v_cndmask_b32_e32 v5, v5, v92, vcc
	v_cmp_class_f32_e32 vcc, v4, v247
	s_nop 1
	v_cndmask_b32_e32 v4, v5, v4, vcc
	v_div_scale_f32 v5, s[0:1], v4, v4, 1.0
	v_rcp_f32_e32 v92, v5
	s_nop 0
	v_fma_f32 v93, -v5, v92, 1.0
	v_fmac_f32_e32 v92, v93, v92
	v_div_scale_f32 v93, vcc, 1.0, v4, 1.0
	v_mul_f32_e32 v94, v93, v92
	v_fma_f32 v95, -v5, v94, v93
	v_fmac_f32_e32 v94, v95, v92
	v_fma_f32 v5, -v5, v94, v93
	v_div_fmas_f32 v5, v5, v92, v94
	v_div_fixup_f32 v4, v5, v4, 1.0
	v_mul_f32_e32 v5, v7, v4
	v_mul_f32_e32 v5, v91, v5
	s_nop 1
	v_mov_b32_dpp v91, v5 quad_perm:[1,0,3,2] row_mask:0xf bank_mask:0xf
	s_and_saveexec_b64 s[0:1], s[8:9]
	s_cbranch_execz .LBB0_1060
	v_add_co_u32_e32 v92, vcc, 0x2000, v2
	s_waitcnt lgkmcnt(0)
	v_cvt_pk_bf16_f32 v5, v5, v91
	s_nop 0
	v_addc_co_u32_e32 v93, vcc, 0, v3, vcc
	global_store_dword v[92:93], v5, off
.LBB0_1060:
	s_or_b64 exec, exec, s[0:1]
	v_mul_f32_e32 v5, v14, v4
	v_mul_f32_e32 v5, v90, v5
	s_nop 1
	v_mov_b32_dpp v90, v5 quad_perm:[1,0,3,2] row_mask:0xf bank_mask:0xf
	s_and_saveexec_b64 s[0:1], s[8:9]
	s_cbranch_execz .LBB0_1062
	s_waitcnt lgkmcnt(0)
	v_cvt_pk_bf16_f32 v5, v5, v90
	v_add_co_u32_e32 v90, vcc, 0x2000, v2
	s_nop 1
	v_addc_co_u32_e32 v91, vcc, 0, v3, vcc
	global_store_dword v[90:91], v5, off offset:64
; #define GAS __attribute__((address_space(1)))
; __device__ __forceinline__ unsigned cvtpk(float lo, float hi) { unsigned r; asm volatile("v_cvt_pk_bf16_f32 %0, %1, %2" : "=v"(r) : "v"(lo), "v"(hi)); return r; }
; __device__ __forceinline__ int crow(int r, int hi) { return (r & 3) + 8 * (r >> 2) + 4 * hi; }
; __device__ __forceinline__ void store_o(const f32x16 (&o)[4], bf16_t* Ow, int pitch, int r32, int hi) {
;     ...
;     for (int r = 0; r < 16; ++r) { const int orow = crow(r, hi);
; #pragma unroll
;         for (int d0 = 0; d0 < 4; ++d0) { const float v = o[d0][r]; const float vn = __shfl_xor(v, 1);
;             if ((r32 & 1) == 0) *(GAS unsigned*)(Ow + (size_t)orow * pitch + d0 * 32 + r32) = cvtpk(v, vn); } }
; __device__ __forceinline__ void ph_attn(const Args& a, char* lds, int l, int rep) {
;     ...
;             for (int r = 0; r < 16; ++r) { float ss = 0.f;
; #pragma unroll
;                 for (int d = 0; d < 4; ++d) { const unsigned pw = o1p[d][r >> 1]; const float o1v = __uint_as_float((r & 1) ? (pw & 0xffff0000u) : (pw << 16)); const float v = o1v - lam * o[d][r]; o[d][r] = v; ss += v * v; }
;                 ss += __shfl_xor(ss, 1); ss += __shfl_xor(ss, 2); ss += __shfl_xor(ss, 4); ss += __shfl_xor(ss, 8); ss += __shfl_xor(ss, 16);
;                 const float rs = 1.0f / sqrtf(ss * (1.0f / 128.0f) + EPSN);
; #pragma unroll
;                 for (int d = 0; d < 4; ++d) o[d][r] *= rs * gd[d]; }
;             att::store_o(o, MIX + qrow * DM + 1536 + h * 128, DM, r32, hi);
.LBB0_1062:
	s_or_b64 exec, exec, s[0:1]
	v_mul_f32_e32 v5, v12, v4
	v_mul_f32_e32 v5, v87, v5
	s_nop 1
	v_mov_b32_dpp v87, v5 quad_perm:[1,0,3,2] row_mask:0xf bank_mask:0xf
	s_and_saveexec_b64 s[0:1], s[8:9]
	s_cbranch_execz .LBB0_1064
	s_waitcnt lgkmcnt(1)
	v_add_co_u32_e32 v90, vcc, 0x2000, v2
	s_waitcnt lgkmcnt(0)
	v_cvt_pk_bf16_f32 v5, v5, v87
	s_nop 0
	v_addc_co_u32_e32 v91, vcc, 0, v3, vcc
	global_store_dword v[90:91], v5, off offset:128
.LBB0_1064:
	s_or_b64 exec, exec, s[0:1]
	v_mul_f32_e32 v4, v0, v4
	v_mul_f32_e32 v4, v86, v4
	s_nop 1
	v_mov_b32_dpp v5, v4 quad_perm:[1,0,3,2] row_mask:0xf bank_mask:0xf
	s_and_saveexec_b64 s[0:1], s[8:9]
	s_cbranch_execz .LBB0_1066
	s_waitcnt lgkmcnt(0)
	v_cvt_pk_bf16_f32 v86, v4, v5
	v_add_co_u32_e32 v4, vcc, 0x2000, v2
	s_nop 1
	v_addc_co_u32_e32 v5, vcc, 0, v3, vcc
	global_store_dword v[4:5], v86, off offset:192
.LBB0_1066:
	s_or_b64 exec, exec, s[0:1]
	v_add_f32_e32 v4, v88, v89
	v_fmamk_f32 v4, v4, 0x3c000000, v241
	s_mov_b32 s0, 0xf800000
	s_waitcnt lgkmcnt(0)
	v_mul_f32_e32 v5, 0x4f800000, v4
	v_cmp_gt_f32_e32 vcc, s0, v4
	s_nop 1
	v_cndmask_b32_e32 v4, v4, v5, vcc
	v_sqrt_f32_e32 v5, v4
	s_nop 0
	v_add_u32_e32 v86, -1, v5
	v_fma_f32 v88, -v86, v5, v4
	v_add_u32_e32 v87, 1, v5
	v_cmp_ge_f32_e64 s[10:11], 0, v88
	s_nop 1
	v_cndmask_b32_e64 v86, v5, v86, s[10:11]
	v_fma_f32 v5, -v87, v5, v4
	v_cmp_lt_f32_e64 s[10:11], 0, v5
	s_nop 1
	v_cndmask_b32_e64 v5, v86, v87, s[10:11]
	v_mul_f32_e32 v86, 0x37800000, v5
	v_cndmask_b32_e32 v5, v5, v86, vcc
	v_cmp_class_f32_e32 vcc, v4, v247
	s_nop 1
	v_cndmask_b32_e32 v4, v5, v4, vcc
	v_div_scale_f32 v5, s[0:1], v4, v4, 1.0
	v_rcp_f32_e32 v86, v5
	s_nop 0
	v_fma_f32 v87, -v5, v86, 1.0
	v_fmac_f32_e32 v86, v87, v86
	v_div_scale_f32 v87, vcc, 1.0, v4, 1.0
	v_mul_f32_e32 v88, v87, v86
	v_fma_f32 v89, -v5, v88, v87
	v_fmac_f32_e32 v88, v89, v86
	v_fma_f32 v5, -v5, v88, v87
	v_div_fmas_f32 v5, v5, v86, v88
	v_div_fixup_f32 v4, v5, v4, 1.0
	v_mul_f32_e32 v5, v7, v4
	v_mul_f32_e32 v5, v83, v5
	s_nop 1
	v_mov_b32_dpp v83, v5 quad_perm:[1,0,3,2] row_mask:0xf bank_mask:0xf
	s_and_saveexec_b64 s[0:1], s[8:9]
	s_cbranch_execz .LBB0_1068
	v_add_co_u32_e32 v86, vcc, 0x3000, v2
	s_waitcnt lgkmcnt(0)
	v_cvt_pk_bf16_f32 v5, v5, v83
	s_nop 0
	v_addc_co_u32_e32 v87, vcc, 0, v3, vcc
	global_store_dword v[86:87], v5, off
.LBB0_1068:
	s_or_b64 exec, exec, s[0:1]
	v_mul_f32_e32 v5, v14, v4
	v_mul_f32_e32 v5, v82, v5
	s_nop 1
	v_mov_b32_dpp v82, v5 quad_perm:[1,0,3,2] row_mask:0xf bank_mask:0xf
	s_and_saveexec_b64 s[0:1], s[8:9]
	s_cbranch_execz .LBB0_1070
	s_waitcnt lgkmcnt(0)
	v_cvt_pk_bf16_f32 v5, v5, v82
	v_add_co_u32_e32 v82, vcc, 0x3000, v2
	s_nop 1
	v_addc_co_u32_e32 v83, vcc, 0, v3, vcc
	global_store_dword v[82:83], v5, off offset:64
.LBB0_1070:
	s_or_b64 exec, exec, s[0:1]
	v_mul_f32_e32 v5, v12, v4
	v_mul_f32_e32 v5, v81, v5
	s_nop 1
	v_mov_b32_dpp v81, v5 quad_perm:[1,0,3,2] row_mask:0xf bank_mask:0xf
	s_and_saveexec_b64 s[0:1], s[8:9]
	s_cbranch_execz .LBB0_1072
	s_waitcnt lgkmcnt(1)
	v_add_co_u32_e32 v82, vcc, 0x3000, v2
	s_waitcnt lgkmcnt(0)
	v_cvt_pk_bf16_f32 v5, v5, v81
	s_nop 0
	v_addc_co_u32_e32 v83, vcc, 0, v3, vcc
	global_store_dword v[82:83], v5, off offset:128
.LBB0_1072:
	s_or_b64 exec, exec, s[0:1]
	v_mul_f32_e32 v4, v0, v4
	v_mul_f32_e32 v4, v80, v4
	s_nop 1
	v_mov_b32_dpp v5, v4 quad_perm:[1,0,3,2] row_mask:0xf bank_mask:0xf
	s_and_saveexec_b64 s[0:1], s[8:9]
	s_cbranch_execz .LBB0_1074
	s_waitcnt lgkmcnt(0)
	v_cvt_pk_bf16_f32 v80, v4, v5
	v_add_co_u32_e32 v4, vcc, 0x3000, v2
	s_nop 1
	v_addc_co_u32_e32 v5, vcc, 0, v3, vcc
	global_store_dword v[4:5], v80, off offset:192
.LBB0_1074:
	s_or_b64 exec, exec, s[0:1]
	v_add_f32_e32 v4, v84, v85
	v_fmamk_f32 v4, v4, 0x3c000000, v241
	s_mov_b32 s0, 0xf800000
	s_waitcnt lgkmcnt(0)
	v_mul_f32_e32 v5, 0x4f800000, v4
	v_cmp_gt_f32_e32 vcc, s0, v4
	s_nop 1
	v_cndmask_b32_e32 v4, v4, v5, vcc
	v_sqrt_f32_e32 v5, v4
	s_nop 0
	v_add_u32_e32 v80, -1, v5
	v_fma_f32 v82, -v80, v5, v4
	v_add_u32_e32 v81, 1, v5
	v_cmp_ge_f32_e64 s[10:11], 0, v82
	s_nop 1
	v_cndmask_b32_e64 v80, v5, v80, s[10:11]
	v_fma_f32 v5, -v81, v5, v4
	v_cmp_lt_f32_e64 s[10:11], 0, v5
	s_nop 1
	v_cndmask_b32_e64 v5, v80, v81, s[10:11]
	v_mul_f32_e32 v80, 0x37800000, v5
	v_cndmask_b32_e32 v5, v5, v80, vcc
	v_cmp_class_f32_e32 vcc, v4, v247
	s_nop 1
	v_cndmask_b32_e32 v4, v5, v4, vcc
	v_div_scale_f32 v5, s[0:1], v4, v4, 1.0
	v_rcp_f32_e32 v80, v5
	s_nop 0
	v_fma_f32 v81, -v5, v80, 1.0
	v_fmac_f32_e32 v80, v81, v80
	v_div_scale_f32 v81, vcc, 1.0, v4, 1.0
	v_mul_f32_e32 v82, v81, v80
	v_fma_f32 v83, -v5, v82, v81
	v_fmac_f32_e32 v82, v83, v80
	v_fma_f32 v5, -v5, v82, v81
	v_div_fmas_f32 v5, v5, v80, v82
	v_div_fixup_f32 v4, v5, v4, 1.0
	v_mul_f32_e32 v5, v7, v4
	v_mul_f32_e32 v5, v79, v5
	s_nop 1
	v_mov_b32_dpp v79, v5 quad_perm:[1,0,3,2] row_mask:0xf bank_mask:0xf
	s_and_saveexec_b64 s[0:1], s[8:9]
	s_cbranch_execz .LBB0_1076
	v_add_co_u32_e32 v80, vcc, 0x8000, v2
	s_waitcnt lgkmcnt(0)
	v_cvt_pk_bf16_f32 v5, v5, v79
	s_nop 0
	v_addc_co_u32_e32 v81, vcc, 0, v3, vcc
	global_store_dword v[80:81], v5, off
.LBB0_1076:
	s_or_b64 exec, exec, s[0:1]
	v_mul_f32_e32 v5, v14, v4
	v_mul_f32_e32 v5, v76, v5
	s_nop 1
	v_mov_b32_dpp v76, v5 quad_perm:[1,0,3,2] row_mask:0xf bank_mask:0xf
	s_and_saveexec_b64 s[0:1], s[8:9]
	s_cbranch_execz .LBB0_1078
	v_add_co_u32_e32 v80, vcc, 0x8000, v2
	s_waitcnt lgkmcnt(0)
	v_cvt_pk_bf16_f32 v5, v5, v76
	s_nop 0
	v_addc_co_u32_e32 v81, vcc, 0, v3, vcc
	global_store_dword v[80:81], v5, off offset:64
; #define GAS __attribute__((address_space(1)))
; __device__ __forceinline__ unsigned cvtpk(float lo, float hi) { unsigned r; asm volatile("v_cvt_pk_bf16_f32 %0, %1, %2" : "=v"(r) : "v"(lo), "v"(hi)); return r; }
; __device__ __forceinline__ int crow(int r, int hi) { return (r & 3) + 8 * (r >> 2) + 4 * hi; }
; __device__ __forceinline__ void store_o(const f32x16 (&o)[4], bf16_t* Ow, int pitch, int r32, int hi) {
; #pragma unroll
;     for (int r = 0; r < 16; ++r) { const int orow = crow(r, hi);
; #pragma unroll
;         for (int d0 = 0; d0 < 4; ++d0) { const float v = o[d0][r]; const float vn = __shfl_xor(v, 1);
;             if ((r32 & 1) == 0) *(GAS unsigned*)(Ow + (size_t)orow * pitch + d0 * 32 + r32) = cvtpk(v, vn); } }
; __device__ __forceinline__ void ph_attn(const Args& a, char* lds, int l, int rep) {
;     ...
;             for (int r = 0; r < 16; ++r) { float ss = 0.f;
; #pragma unroll
;                 for (int d = 0; d < 4; ++d) { const unsigned pw = o1p[d][r >> 1]; const float o1v = __uint_as_float((r & 1) ? (pw & 0xffff0000u) : (pw << 16)); const float v = o1v - lam * o[d][r]; o[d][r] = v; ss += v * v; }
;                 ss += __shfl_xor(ss, 1); ss += __shfl_xor(ss, 2); ss += __shfl_xor(ss, 4); ss += __shfl_xor(ss, 8); ss += __shfl_xor(ss, 16);
;                 const float rs = 1.0f / sqrtf(ss * (1.0f / 128.0f) + EPSN);
; #pragma unroll
;                 for (int d = 0; d < 4; ++d) o[d][r] *= rs * gd[d]; }
.LBB0_1078:
	s_or_b64 exec, exec, s[0:1]
	v_mul_f32_e32 v5, v12, v4
	v_mul_f32_e32 v5, v75, v5
	s_nop 1
	v_mov_b32_dpp v75, v5 quad_perm:[1,0,3,2] row_mask:0xf bank_mask:0xf
	s_and_saveexec_b64 s[0:1], s[8:9]
	s_cbranch_execz .LBB0_1080
	v_add_co_u32_e32 v80, vcc, 0x8000, v2
	s_waitcnt lgkmcnt(0)
	v_cvt_pk_bf16_f32 v5, v5, v75
	s_nop 0
	v_addc_co_u32_e32 v81, vcc, 0, v3, vcc
	global_store_dword v[80:81], v5, off offset:128
.LBB0_1080:
	s_or_b64 exec, exec, s[0:1]
	v_mul_f32_e32 v4, v0, v4
	v_mul_f32_e32 v4, v74, v4
	s_nop 1
	v_mov_b32_dpp v5, v4 quad_perm:[1,0,3,2] row_mask:0xf bank_mask:0xf
	s_and_saveexec_b64 s[0:1], s[8:9]
	s_cbranch_execz .LBB0_1082
	s_waitcnt lgkmcnt(0)
	v_cvt_pk_bf16_f32 v74, v4, v5
	v_add_co_u32_e32 v4, vcc, 0x8000, v2
	s_nop 1
	v_addc_co_u32_e32 v5, vcc, 0, v3, vcc
	global_store_dword v[4:5], v74, off offset:192
.LBB0_1082:
	s_or_b64 exec, exec, s[0:1]
	v_add_f32_e32 v4, v77, v78
	v_fmamk_f32 v4, v4, 0x3c000000, v241
	s_mov_b32 s0, 0xf800000
	s_waitcnt lgkmcnt(0)
	v_mul_f32_e32 v5, 0x4f800000, v4
	v_cmp_gt_f32_e32 vcc, s0, v4
	s_nop 1
	v_cndmask_b32_e32 v4, v4, v5, vcc
	v_sqrt_f32_e32 v5, v4
	s_nop 0
	v_add_u32_e32 v74, -1, v5
	v_fma_f32 v76, -v74, v5, v4
	v_add_u32_e32 v75, 1, v5
	v_cmp_ge_f32_e64 s[10:11], 0, v76
	s_nop 1
	v_cndmask_b32_e64 v74, v5, v74, s[10:11]
	v_fma_f32 v5, -v75, v5, v4
	v_cmp_lt_f32_e64 s[10:11], 0, v5
	s_nop 1
	v_cndmask_b32_e64 v5, v74, v75, s[10:11]
	v_mul_f32_e32 v74, 0x37800000, v5
	v_cndmask_b32_e32 v5, v5, v74, vcc
	v_cmp_class_f32_e32 vcc, v4, v247
	s_nop 1
	v_cndmask_b32_e32 v4, v5, v4, vcc
	v_div_scale_f32 v5, s[0:1], v4, v4, 1.0
	v_rcp_f32_e32 v74, v5
	s_nop 0
	v_fma_f32 v75, -v5, v74, 1.0
	v_fmac_f32_e32 v74, v75, v74
	v_div_scale_f32 v75, vcc, 1.0, v4, 1.0
	v_mul_f32_e32 v76, v75, v74
	v_fma_f32 v77, -v5, v76, v75
	v_fmac_f32_e32 v76, v77, v74
	v_fma_f32 v5, -v5, v76, v75
	v_div_fmas_f32 v5, v5, v74, v76
	v_div_fixup_f32 v4, v5, v4, 1.0
	v_mul_f32_e32 v5, v7, v4
	v_mul_f32_e32 v5, v73, v5
	s_nop 1
	v_mov_b32_dpp v73, v5 quad_perm:[1,0,3,2] row_mask:0xf bank_mask:0xf
	s_and_saveexec_b64 s[0:1], s[8:9]
	s_cbranch_execz .LBB0_1084
	v_add_co_u32_e32 v74, vcc, 0x9000, v2
	s_waitcnt lgkmcnt(0)
	v_cvt_pk_bf16_f32 v5, v5, v73
	s_nop 0
	v_addc_co_u32_e32 v75, vcc, 0, v3, vcc
	global_store_dword v[74:75], v5, off
.LBB0_1084:
	s_or_b64 exec, exec, s[0:1]
	v_mul_f32_e32 v5, v14, v4
	v_mul_f32_e32 v5, v72, v5
	s_nop 1
	v_mov_b32_dpp v72, v5 quad_perm:[1,0,3,2] row_mask:0xf bank_mask:0xf
	s_and_saveexec_b64 s[0:1], s[8:9]
	s_cbranch_execz .LBB0_1086
	s_waitcnt lgkmcnt(0)
	v_cvt_pk_bf16_f32 v5, v5, v72
	v_add_co_u32_e32 v72, vcc, 0x9000, v2
	s_nop 1
	v_addc_co_u32_e32 v73, vcc, 0, v3, vcc
	global_store_dword v[72:73], v5, off offset:64
.LBB0_1086:
	s_or_b64 exec, exec, s[0:1]
	v_mul_f32_e32 v5, v12, v4
	v_mul_f32_e32 v5, v69, v5
	s_nop 1
	v_mov_b32_dpp v69, v5 quad_perm:[1,0,3,2] row_mask:0xf bank_mask:0xf
	s_and_saveexec_b64 s[0:1], s[8:9]
	s_cbranch_execz .LBB0_1088
	s_waitcnt lgkmcnt(1)
	v_add_co_u32_e32 v72, vcc, 0x9000, v2
	s_waitcnt lgkmcnt(0)
	v_cvt_pk_bf16_f32 v5, v5, v69
	s_nop 0
	v_addc_co_u32_e32 v73, vcc, 0, v3, vcc
	global_store_dword v[72:73], v5, off offset:128
.LBB0_1088:
	s_or_b64 exec, exec, s[0:1]
	v_mul_f32_e32 v4, v0, v4
	v_mul_f32_e32 v4, v68, v4
	s_nop 1
	v_mov_b32_dpp v5, v4 quad_perm:[1,0,3,2] row_mask:0xf bank_mask:0xf
	s_and_saveexec_b64 s[0:1], s[8:9]
	s_cbranch_execz .LBB0_1090
	s_waitcnt lgkmcnt(0)
	v_cvt_pk_bf16_f32 v68, v4, v5
	v_add_co_u32_e32 v4, vcc, 0x9000, v2
	s_nop 1
	v_addc_co_u32_e32 v5, vcc, 0, v3, vcc
	global_store_dword v[4:5], v68, off offset:192
.LBB0_1090:
	s_or_b64 exec, exec, s[0:1]
	v_add_f32_e32 v4, v70, v71
	v_fmamk_f32 v4, v4, 0x3c000000, v241
	s_mov_b32 s0, 0xf800000
	s_waitcnt lgkmcnt(0)
	v_mul_f32_e32 v5, 0x4f800000, v4
	v_cmp_gt_f32_e32 vcc, s0, v4
	s_nop 1
	v_cndmask_b32_e32 v4, v4, v5, vcc
	v_sqrt_f32_e32 v5, v4
	s_nop 0
	v_add_u32_e32 v68, -1, v5
	v_fma_f32 v70, -v68, v5, v4
	v_add_u32_e32 v69, 1, v5
	v_cmp_ge_f32_e64 s[10:11], 0, v70
	s_nop 1
	v_cndmask_b32_e64 v68, v5, v68, s[10:11]
	v_fma_f32 v5, -v69, v5, v4
	v_cmp_lt_f32_e64 s[10:11], 0, v5
	s_nop 1
	v_cndmask_b32_e64 v5, v68, v69, s[10:11]
	v_mul_f32_e32 v68, 0x37800000, v5
	v_cndmask_b32_e32 v5, v5, v68, vcc
	v_cmp_class_f32_e32 vcc, v4, v247
	s_nop 1
	v_cndmask_b32_e32 v4, v5, v4, vcc
	v_div_scale_f32 v5, s[0:1], v4, v4, 1.0
	v_rcp_f32_e32 v68, v5
	s_nop 0
	v_fma_f32 v69, -v5, v68, 1.0
	v_fmac_f32_e32 v68, v69, v68
	v_div_scale_f32 v69, vcc, 1.0, v4, 1.0
	v_mul_f32_e32 v70, v69, v68
	v_fma_f32 v71, -v5, v70, v69
	v_fmac_f32_e32 v70, v71, v68
	v_fma_f32 v5, -v5, v70, v69
	v_div_fmas_f32 v5, v5, v68, v70
	v_div_fixup_f32 v4, v5, v4, 1.0
	v_mul_f32_e32 v5, v7, v4
	v_mul_f32_e32 v5, v65, v5
	s_nop 1
	v_mov_b32_dpp v65, v5 quad_perm:[1,0,3,2] row_mask:0xf bank_mask:0xf
	s_and_saveexec_b64 s[0:1], s[8:9]
	s_cbranch_execz .LBB0_1092
	v_add_co_u32_e32 v68, vcc, 0xa000, v2
	s_waitcnt lgkmcnt(0)
	v_cvt_pk_bf16_f32 v5, v5, v65
	s_nop 0
	v_addc_co_u32_e32 v69, vcc, 0, v3, vcc
	global_store_dword v[68:69], v5, off
.LBB0_1092:
	s_or_b64 exec, exec, s[0:1]
	v_mul_f32_e32 v5, v14, v4
	v_mul_f32_e32 v5, v64, v5
	s_nop 1
	v_mov_b32_dpp v64, v5 quad_perm:[1,0,3,2] row_mask:0xf bank_mask:0xf
	s_and_saveexec_b64 s[0:1], s[8:9]
	s_cbranch_execz .LBB0_1094
	s_waitcnt lgkmcnt(0)
	v_cvt_pk_bf16_f32 v5, v5, v64
	v_add_co_u32_e32 v64, vcc, 0xa000, v2
	s_nop 1
	v_addc_co_u32_e32 v65, vcc, 0, v3, vcc
	global_store_dword v[64:65], v5, off offset:64
; #define GAS __attribute__((address_space(1)))
; __device__ __forceinline__ unsigned cvtpk(float lo, float hi) { unsigned r; asm volatile("v_cvt_pk_bf16_f32 %0, %1, %2" : "=v"(r) : "v"(lo), "v"(hi)); return r; }
; __device__ __forceinline__ int crow(int r, int hi) { return (r & 3) + 8 * (r >> 2) + 4 * hi; }
; __device__ __forceinline__ void store_o(const f32x16 (&o)[4], bf16_t* Ow, int pitch, int r32, int hi) {
; #pragma unroll
;     for (int r = 0; r < 16; ++r) { const int orow = crow(r, hi);
; #pragma unroll
;         for (int d0 = 0; d0 < 4; ++d0) { const float v = o[d0][r]; const float vn = __shfl_xor(v, 1);
;             if ((r32 & 1) == 0) *(GAS unsigned*)(Ow + (size_t)orow * pitch + d0 * 32 + r32) = cvtpk(v, vn); } }
; __device__ __forceinline__ void ph_attn(const Args& a, char* lds, int l, int rep) {
;     ...
;             for (int r = 0; r < 16; ++r) { float ss = 0.f;
; #pragma unroll
;                 for (int d = 0; d < 4; ++d) { const unsigned pw = o1p[d][r >> 1]; const float o1v = __uint_as_float((r & 1) ? (pw & 0xffff0000u) : (pw << 16)); const float v = o1v - lam * o[d][r]; o[d][r] = v; ss += v * v; }
;                 ss += __shfl_xor(ss, 1); ss += __shfl_xor(ss, 2); ss += __shfl_xor(ss, 4); ss += __shfl_xor(ss, 8); ss += __shfl_xor(ss, 16);
;                 const float rs = 1.0f / sqrtf(ss * (1.0f / 128.0f) + EPSN);
; #pragma unroll
;                 for (int d = 0; d < 4; ++d) o[d][r] *= rs * gd[d]; }
.LBB0_1094:
	s_or_b64 exec, exec, s[0:1]
	v_mul_f32_e32 v5, v12, v4
	v_mul_f32_e32 v5, v63, v5
	s_nop 1
	v_mov_b32_dpp v63, v5 quad_perm:[1,0,3,2] row_mask:0xf bank_mask:0xf
	s_and_saveexec_b64 s[0:1], s[8:9]
	s_cbranch_execz .LBB0_1096
	s_waitcnt lgkmcnt(1)
	v_add_co_u32_e32 v64, vcc, 0xa000, v2
	s_waitcnt lgkmcnt(0)
	v_cvt_pk_bf16_f32 v5, v5, v63
	s_nop 0
	v_addc_co_u32_e32 v65, vcc, 0, v3, vcc
	global_store_dword v[64:65], v5, off offset:128
.LBB0_1096:
	s_or_b64 exec, exec, s[0:1]
	v_mul_f32_e32 v4, v0, v4
	v_mul_f32_e32 v4, v62, v4
	s_nop 1
	v_mov_b32_dpp v5, v4 quad_perm:[1,0,3,2] row_mask:0xf bank_mask:0xf
	s_and_saveexec_b64 s[0:1], s[8:9]
	s_cbranch_execz .LBB0_1098
	s_waitcnt lgkmcnt(0)
	v_cvt_pk_bf16_f32 v62, v4, v5
	v_add_co_u32_e32 v4, vcc, 0xa000, v2
	s_nop 1
	v_addc_co_u32_e32 v5, vcc, 0, v3, vcc
	global_store_dword v[4:5], v62, off offset:192
.LBB0_1098:
	s_or_b64 exec, exec, s[0:1]
	v_add_f32_e32 v4, v66, v67
	v_fmamk_f32 v4, v4, 0x3c000000, v241
	s_mov_b32 s0, 0xf800000
	s_waitcnt lgkmcnt(0)
	v_mul_f32_e32 v5, 0x4f800000, v4
	v_cmp_gt_f32_e32 vcc, s0, v4
	s_nop 1
	v_cndmask_b32_e32 v4, v4, v5, vcc
	v_sqrt_f32_e32 v5, v4
	s_nop 0
	v_add_u32_e32 v62, -1, v5
	v_fma_f32 v64, -v62, v5, v4
	v_add_u32_e32 v63, 1, v5
	v_cmp_ge_f32_e64 s[10:11], 0, v64
	s_nop 1
	v_cndmask_b32_e64 v62, v5, v62, s[10:11]
	v_fma_f32 v5, -v63, v5, v4
	v_cmp_lt_f32_e64 s[10:11], 0, v5
	s_nop 1
	v_cndmask_b32_e64 v5, v62, v63, s[10:11]
	v_mul_f32_e32 v62, 0x37800000, v5
	v_cndmask_b32_e32 v5, v5, v62, vcc
	v_cmp_class_f32_e32 vcc, v4, v247
	s_nop 1
	v_cndmask_b32_e32 v4, v5, v4, vcc
	v_div_scale_f32 v5, s[0:1], v4, v4, 1.0
	v_rcp_f32_e32 v62, v5
	s_nop 0
	v_fma_f32 v63, -v5, v62, 1.0
	v_fmac_f32_e32 v62, v63, v62
	v_div_scale_f32 v63, vcc, 1.0, v4, 1.0
	v_mul_f32_e32 v64, v63, v62
	v_fma_f32 v65, -v5, v64, v63
	v_fmac_f32_e32 v64, v65, v62
	v_fma_f32 v5, -v5, v64, v63
	v_div_fmas_f32 v5, v5, v62, v64
	v_div_fixup_f32 v4, v5, v4, 1.0
	v_mul_f32_e32 v5, v7, v4
	v_mul_f32_e32 v5, v61, v5
	s_nop 1
	v_mov_b32_dpp v61, v5 quad_perm:[1,0,3,2] row_mask:0xf bank_mask:0xf
	s_and_saveexec_b64 s[0:1], s[8:9]
	s_cbranch_execz .LBB0_1100
	v_add_co_u32_e32 v62, vcc, 0xb000, v2
	s_waitcnt lgkmcnt(0)
	v_cvt_pk_bf16_f32 v5, v5, v61
	s_nop 0
	v_addc_co_u32_e32 v63, vcc, 0, v3, vcc
	global_store_dword v[62:63], v5, off
.LBB0_1100:
	s_or_b64 exec, exec, s[0:1]
	v_mul_f32_e32 v5, v14, v4
	v_mul_f32_e32 v5, v58, v5
	s_nop 1
	v_mov_b32_dpp v58, v5 quad_perm:[1,0,3,2] row_mask:0xf bank_mask:0xf
	s_and_saveexec_b64 s[0:1], s[8:9]
	s_cbranch_execz .LBB0_1102
	v_add_co_u32_e32 v62, vcc, 0xb000, v2
	s_waitcnt lgkmcnt(0)
	v_cvt_pk_bf16_f32 v5, v5, v58
	s_nop 0
	v_addc_co_u32_e32 v63, vcc, 0, v3, vcc
	global_store_dword v[62:63], v5, off offset:64
.LBB0_1102:
	s_or_b64 exec, exec, s[0:1]
	v_mul_f32_e32 v5, v12, v4
	v_mul_f32_e32 v5, v57, v5
	s_nop 1
	v_mov_b32_dpp v57, v5 quad_perm:[1,0,3,2] row_mask:0xf bank_mask:0xf
	s_and_saveexec_b64 s[0:1], s[8:9]
	s_cbranch_execz .LBB0_1104
	v_add_co_u32_e32 v62, vcc, 0xb000, v2
	s_waitcnt lgkmcnt(0)
	v_cvt_pk_bf16_f32 v5, v5, v57
	s_nop 0
	v_addc_co_u32_e32 v63, vcc, 0, v3, vcc
	global_store_dword v[62:63], v5, off offset:128
.LBB0_1104:
	s_or_b64 exec, exec, s[0:1]
	v_mul_f32_e32 v4, v0, v4
	v_mul_f32_e32 v4, v56, v4
	s_nop 1
	v_mov_b32_dpp v5, v4 quad_perm:[1,0,3,2] row_mask:0xf bank_mask:0xf
	s_and_saveexec_b64 s[0:1], s[8:9]
	s_cbranch_execz .LBB0_1106
	s_waitcnt lgkmcnt(0)
	v_cvt_pk_bf16_f32 v56, v4, v5
	v_add_co_u32_e32 v4, vcc, 0xb000, v2
	s_nop 1
	v_addc_co_u32_e32 v5, vcc, 0, v3, vcc
	global_store_dword v[4:5], v56, off offset:192
.LBB0_1106:
	s_or_b64 exec, exec, s[0:1]
	v_add_f32_e32 v4, v59, v60
	v_fmamk_f32 v4, v4, 0x3c000000, v241
	s_mov_b32 s0, 0xf800000
	s_waitcnt lgkmcnt(0)
	v_mul_f32_e32 v5, 0x4f800000, v4
	v_cmp_gt_f32_e32 vcc, s0, v4
	s_nop 1
	v_cndmask_b32_e32 v4, v4, v5, vcc
	v_sqrt_f32_e32 v5, v4
	s_nop 0
	v_add_u32_e32 v56, -1, v5
	v_fma_f32 v58, -v56, v5, v4
	v_add_u32_e32 v57, 1, v5
	v_cmp_ge_f32_e64 s[10:11], 0, v58
	s_nop 1
	v_cndmask_b32_e64 v56, v5, v56, s[10:11]
	v_fma_f32 v5, -v57, v5, v4
	v_cmp_lt_f32_e64 s[10:11], 0, v5
	s_nop 1
	v_cndmask_b32_e64 v5, v56, v57, s[10:11]
	v_mul_f32_e32 v56, 0x37800000, v5
	v_cndmask_b32_e32 v5, v5, v56, vcc
	v_cmp_class_f32_e32 vcc, v4, v247
	s_nop 1
	v_cndmask_b32_e32 v4, v5, v4, vcc
	v_div_scale_f32 v5, s[0:1], v4, v4, 1.0
	v_rcp_f32_e32 v56, v5
	s_nop 0
	v_fma_f32 v57, -v5, v56, 1.0
	v_fmac_f32_e32 v56, v57, v56
	v_div_scale_f32 v57, vcc, 1.0, v4, 1.0
	v_mul_f32_e32 v58, v57, v56
	v_fma_f32 v59, -v5, v58, v57
	v_fmac_f32_e32 v58, v59, v56
	v_fma_f32 v5, -v5, v58, v57
	v_div_fmas_f32 v5, v5, v56, v58
	v_div_fixup_f32 v4, v5, v4, 1.0
	v_mul_f32_e32 v5, v7, v4
	v_mul_f32_e32 v5, v55, v5
	s_nop 1
	v_mov_b32_dpp v55, v5 quad_perm:[1,0,3,2] row_mask:0xf bank_mask:0xf
	s_and_saveexec_b64 s[0:1], s[8:9]
	s_cbranch_execz .LBB0_1108
	v_add_co_u32_e32 v56, vcc, 0x10000, v2
	s_waitcnt lgkmcnt(0)
	v_cvt_pk_bf16_f32 v5, v5, v55
	s_nop 0
	v_addc_co_u32_e32 v57, vcc, 0, v3, vcc
	global_store_dword v[56:57], v5, off
.LBB0_1108:
	s_or_b64 exec, exec, s[0:1]
	v_mul_f32_e32 v5, v14, v4
	v_mul_f32_e32 v5, v54, v5
	s_nop 1
	v_mov_b32_dpp v54, v5 quad_perm:[1,0,3,2] row_mask:0xf bank_mask:0xf
	s_and_saveexec_b64 s[0:1], s[8:9]
	s_cbranch_execz .LBB0_1110
	s_waitcnt lgkmcnt(0)
	v_cvt_pk_bf16_f32 v5, v5, v54
	v_add_co_u32_e32 v54, vcc, 0x10000, v2
	s_nop 1
	v_addc_co_u32_e32 v55, vcc, 0, v3, vcc
	global_store_dword v[54:55], v5, off offset:64
; #define GAS __attribute__((address_space(1)))
; __device__ __forceinline__ unsigned cvtpk(float lo, float hi) { unsigned r; asm volatile("v_cvt_pk_bf16_f32 %0, %1, %2" : "=v"(r) : "v"(lo), "v"(hi)); return r; }
; __device__ __forceinline__ int crow(int r, int hi) { return (r & 3) + 8 * (r >> 2) + 4 * hi; }
; __device__ __forceinline__ void store_o(const f32x16 (&o)[4], bf16_t* Ow, int pitch, int r32, int hi) {
; #pragma unroll
;     for (int r = 0; r < 16; ++r) { const int orow = crow(r, hi);
; #pragma unroll
;         for (int d0 = 0; d0 < 4; ++d0) { const float v = o[d0][r]; const float vn = __shfl_xor(v, 1);
;             if ((r32 & 1) == 0) *(GAS unsigned*)(Ow + (size_t)orow * pitch + d0 * 32 + r32) = cvtpk(v, vn); } }
; __device__ __forceinline__ void ph_attn(const Args& a, char* lds, int l, int rep) {
;     ...
;             for (int r = 0; r < 16; ++r) { float ss = 0.f;
; #pragma unroll
;                 for (int d = 0; d < 4; ++d) { const unsigned pw = o1p[d][r >> 1]; const float o1v = __uint_as_float((r & 1) ? (pw & 0xffff0000u) : (pw << 16)); const float v = o1v - lam * o[d][r]; o[d][r] = v; ss += v * v; }
;                 ss += __shfl_xor(ss, 1); ss += __shfl_xor(ss, 2); ss += __shfl_xor(ss, 4); ss += __shfl_xor(ss, 8); ss += __shfl_xor(ss, 16);
;                 const float rs = 1.0f / sqrtf(ss * (1.0f / 128.0f) + EPSN);
; #pragma unroll
;                 for (int d = 0; d < 4; ++d) o[d][r] *= rs * gd[d]; }
.LBB0_1110:
	s_or_b64 exec, exec, s[0:1]
	v_mul_f32_e32 v5, v12, v4
	v_mul_f32_e32 v5, v51, v5
	s_nop 1
	v_mov_b32_dpp v51, v5 quad_perm:[1,0,3,2] row_mask:0xf bank_mask:0xf
	s_and_saveexec_b64 s[0:1], s[8:9]
	s_cbranch_execz .LBB0_1112
	s_waitcnt lgkmcnt(1)
	v_add_co_u32_e32 v54, vcc, 0x10000, v2
	s_waitcnt lgkmcnt(0)
	v_cvt_pk_bf16_f32 v5, v5, v51
	s_nop 0
	v_addc_co_u32_e32 v55, vcc, 0, v3, vcc
	global_store_dword v[54:55], v5, off offset:128
.LBB0_1112:
	s_or_b64 exec, exec, s[0:1]
	v_mul_f32_e32 v4, v0, v4
	v_mul_f32_e32 v4, v50, v4
	s_nop 1
	v_mov_b32_dpp v5, v4 quad_perm:[1,0,3,2] row_mask:0xf bank_mask:0xf
	s_and_saveexec_b64 s[0:1], s[8:9]
	s_cbranch_execz .LBB0_1114
	s_waitcnt lgkmcnt(0)
	v_cvt_pk_bf16_f32 v50, v4, v5
	v_add_co_u32_e32 v4, vcc, 0x10000, v2
	s_nop 1
	v_addc_co_u32_e32 v5, vcc, 0, v3, vcc
	global_store_dword v[4:5], v50, off offset:192
.LBB0_1114:
	s_or_b64 exec, exec, s[0:1]
	v_add_f32_e32 v4, v52, v53
	v_fmamk_f32 v4, v4, 0x3c000000, v241
	s_mov_b32 s0, 0xf800000
	s_waitcnt lgkmcnt(0)
	v_mul_f32_e32 v5, 0x4f800000, v4
	v_cmp_gt_f32_e32 vcc, s0, v4
	s_nop 1
	v_cndmask_b32_e32 v4, v4, v5, vcc
	v_sqrt_f32_e32 v5, v4
	s_nop 0
	v_add_u32_e32 v50, -1, v5
	v_fma_f32 v52, -v50, v5, v4
	v_add_u32_e32 v51, 1, v5
	v_cmp_ge_f32_e64 s[10:11], 0, v52
	s_nop 1
	v_cndmask_b32_e64 v50, v5, v50, s[10:11]
	v_fma_f32 v5, -v51, v5, v4
	v_cmp_lt_f32_e64 s[10:11], 0, v5
	s_nop 1
	v_cndmask_b32_e64 v5, v50, v51, s[10:11]
	v_mul_f32_e32 v50, 0x37800000, v5
	v_cndmask_b32_e32 v5, v5, v50, vcc
	v_cmp_class_f32_e32 vcc, v4, v247
	s_nop 1
	v_cndmask_b32_e32 v4, v5, v4, vcc
	v_div_scale_f32 v5, s[0:1], v4, v4, 1.0
	v_rcp_f32_e32 v50, v5
	s_nop 0
	v_fma_f32 v51, -v5, v50, 1.0
	v_fmac_f32_e32 v50, v51, v50
	v_div_scale_f32 v51, vcc, 1.0, v4, 1.0
	v_mul_f32_e32 v52, v51, v50
	v_fma_f32 v53, -v5, v52, v51
	v_fmac_f32_e32 v52, v53, v50
	v_fma_f32 v5, -v5, v52, v51
	v_div_fmas_f32 v5, v5, v50, v52
	v_div_fixup_f32 v4, v5, v4, 1.0
	v_mul_f32_e32 v5, v7, v4
	v_mul_f32_e32 v5, v47, v5
	s_nop 1
	v_mov_b32_dpp v47, v5 quad_perm:[1,0,3,2] row_mask:0xf bank_mask:0xf
	s_and_saveexec_b64 s[0:1], s[8:9]
	s_cbranch_execz .LBB0_1116
	v_add_co_u32_e32 v50, vcc, 0x11000, v2
	s_waitcnt lgkmcnt(0)
	v_cvt_pk_bf16_f32 v5, v5, v47
	s_nop 0
	v_addc_co_u32_e32 v51, vcc, 0, v3, vcc
	global_store_dword v[50:51], v5, off
.LBB0_1116:
	s_or_b64 exec, exec, s[0:1]
	v_mul_f32_e32 v5, v14, v4
	v_mul_f32_e32 v5, v46, v5
	s_nop 1
	v_mov_b32_dpp v46, v5 quad_perm:[1,0,3,2] row_mask:0xf bank_mask:0xf
	s_and_saveexec_b64 s[0:1], s[8:9]
	s_cbranch_execz .LBB0_1118
	s_waitcnt lgkmcnt(0)
	v_cvt_pk_bf16_f32 v5, v5, v46
	v_add_co_u32_e32 v46, vcc, 0x11000, v2
	s_nop 1
	v_addc_co_u32_e32 v47, vcc, 0, v3, vcc
	global_store_dword v[46:47], v5, off offset:64
.LBB0_1118:
	s_or_b64 exec, exec, s[0:1]
	v_mul_f32_e32 v5, v12, v4
	v_mul_f32_e32 v5, v45, v5
	s_nop 1
	v_mov_b32_dpp v45, v5 quad_perm:[1,0,3,2] row_mask:0xf bank_mask:0xf
	s_and_saveexec_b64 s[0:1], s[8:9]
	s_cbranch_execz .LBB0_1120
	s_waitcnt lgkmcnt(1)
	v_add_co_u32_e32 v46, vcc, 0x11000, v2
	s_waitcnt lgkmcnt(0)
	v_cvt_pk_bf16_f32 v5, v5, v45
	s_nop 0
	v_addc_co_u32_e32 v47, vcc, 0, v3, vcc
	global_store_dword v[46:47], v5, off offset:128
.LBB0_1120:
	s_or_b64 exec, exec, s[0:1]
	v_mul_f32_e32 v4, v0, v4
	v_mul_f32_e32 v4, v44, v4
	s_nop 1
	v_mov_b32_dpp v5, v4 quad_perm:[1,0,3,2] row_mask:0xf bank_mask:0xf
	s_and_saveexec_b64 s[0:1], s[8:9]
	s_cbranch_execz .LBB0_1122
	s_waitcnt lgkmcnt(0)
	v_cvt_pk_bf16_f32 v44, v4, v5
	v_add_co_u32_e32 v4, vcc, 0x11000, v2
	s_nop 1
	v_addc_co_u32_e32 v5, vcc, 0, v3, vcc
	global_store_dword v[4:5], v44, off offset:192
.LBB0_1122:
	s_or_b64 exec, exec, s[0:1]
	v_add_f32_e32 v4, v48, v49
	v_fmamk_f32 v4, v4, 0x3c000000, v241
	s_mov_b32 s0, 0xf800000
	s_waitcnt lgkmcnt(0)
	v_mul_f32_e32 v5, 0x4f800000, v4
	v_cmp_gt_f32_e32 vcc, s0, v4
	s_nop 1
	v_cndmask_b32_e32 v4, v4, v5, vcc
	v_sqrt_f32_e32 v5, v4
	s_nop 0
	v_add_u32_e32 v44, -1, v5
	v_fma_f32 v46, -v44, v5, v4
	v_add_u32_e32 v45, 1, v5
	v_cmp_ge_f32_e64 s[10:11], 0, v46
	s_nop 1
	v_cndmask_b32_e64 v44, v5, v44, s[10:11]
	v_fma_f32 v5, -v45, v5, v4
	v_cmp_lt_f32_e64 s[10:11], 0, v5
	s_nop 1
	v_cndmask_b32_e64 v5, v44, v45, s[10:11]
	v_mul_f32_e32 v44, 0x37800000, v5
	v_cndmask_b32_e32 v5, v5, v44, vcc
	v_cmp_class_f32_e32 vcc, v4, v247
	s_nop 1
	v_cndmask_b32_e32 v4, v5, v4, vcc
	v_div_scale_f32 v5, s[0:1], v4, v4, 1.0
	v_rcp_f32_e32 v44, v5
	s_nop 0
	v_fma_f32 v45, -v5, v44, 1.0
	v_fmac_f32_e32 v44, v45, v44
	v_div_scale_f32 v45, vcc, 1.0, v4, 1.0
	v_mul_f32_e32 v46, v45, v44
	v_fma_f32 v47, -v5, v46, v45
	v_fmac_f32_e32 v46, v47, v44
	v_fma_f32 v5, -v5, v46, v45
	v_div_fmas_f32 v5, v5, v44, v46
	v_div_fixup_f32 v4, v5, v4, 1.0
	v_mul_f32_e32 v5, v7, v4
	v_mul_f32_e32 v5, v43, v5
	s_nop 1
	v_mov_b32_dpp v43, v5 quad_perm:[1,0,3,2] row_mask:0xf bank_mask:0xf
	s_and_saveexec_b64 s[0:1], s[8:9]
	s_cbranch_execz .LBB0_1124
	v_add_co_u32_e32 v44, vcc, 0x12000, v2
	s_waitcnt lgkmcnt(0)
	v_cvt_pk_bf16_f32 v5, v5, v43
	s_nop 0
	v_addc_co_u32_e32 v45, vcc, 0, v3, vcc
	global_store_dword v[44:45], v5, off
.LBB0_1124:
	s_or_b64 exec, exec, s[0:1]
	v_mul_f32_e32 v5, v14, v4
	v_mul_f32_e32 v5, v40, v5
	s_nop 1
	v_mov_b32_dpp v40, v5 quad_perm:[1,0,3,2] row_mask:0xf bank_mask:0xf
	s_and_saveexec_b64 s[0:1], s[8:9]
	s_cbranch_execz .LBB0_1126
	v_add_co_u32_e32 v44, vcc, 0x12000, v2
	s_waitcnt lgkmcnt(0)
	v_cvt_pk_bf16_f32 v5, v5, v40
	s_nop 0
	v_addc_co_u32_e32 v45, vcc, 0, v3, vcc
	global_store_dword v[44:45], v5, off offset:64
; #define GAS __attribute__((address_space(1)))
; __device__ __forceinline__ unsigned cvtpk(float lo, float hi) { unsigned r; asm volatile("v_cvt_pk_bf16_f32 %0, %1, %2" : "=v"(r) : "v"(lo), "v"(hi)); return r; }
; __device__ __forceinline__ int crow(int r, int hi) { return (r & 3) + 8 * (r >> 2) + 4 * hi; }
; __device__ __forceinline__ void store_o(const f32x16 (&o)[4], bf16_t* Ow, int pitch, int r32, int hi) {
; #pragma unroll
;     for (int r = 0; r < 16; ++r) { const int orow = crow(r, hi);
; #pragma unroll
;         for (int d0 = 0; d0 < 4; ++d0) { const float v = o[d0][r]; const float vn = __shfl_xor(v, 1);
;             if ((r32 & 1) == 0) *(GAS unsigned*)(Ow + (size_t)orow * pitch + d0 * 32 + r32) = cvtpk(v, vn); } }
; __device__ __forceinline__ void ph_attn(const Args& a, char* lds, int l, int rep) {
;     ...
;             for (int r = 0; r < 16; ++r) { float ss = 0.f;
; #pragma unroll
;                 for (int d = 0; d < 4; ++d) { const unsigned pw = o1p[d][r >> 1]; const float o1v = __uint_as_float((r & 1) ? (pw & 0xffff0000u) : (pw << 16)); const float v = o1v - lam * o[d][r]; o[d][r] = v; ss += v * v; }
;                 ss += __shfl_xor(ss, 1); ss += __shfl_xor(ss, 2); ss += __shfl_xor(ss, 4); ss += __shfl_xor(ss, 8); ss += __shfl_xor(ss, 16);
;                 const float rs = 1.0f / sqrtf(ss * (1.0f / 128.0f) + EPSN);
; #pragma unroll
;                 for (int d = 0; d < 4; ++d) o[d][r] *= rs * gd[d]; }
.LBB0_1126:
	s_or_b64 exec, exec, s[0:1]
	v_mul_f32_e32 v5, v12, v4
	v_mul_f32_e32 v5, v39, v5
	s_nop 1
	v_mov_b32_dpp v39, v5 quad_perm:[1,0,3,2] row_mask:0xf bank_mask:0xf
	s_and_saveexec_b64 s[0:1], s[8:9]
	s_cbranch_execz .LBB0_1128
	v_add_co_u32_e32 v44, vcc, 0x12000, v2
	s_waitcnt lgkmcnt(0)
	v_cvt_pk_bf16_f32 v5, v5, v39
	s_nop 0
	v_addc_co_u32_e32 v45, vcc, 0, v3, vcc
	global_store_dword v[44:45], v5, off offset:128
.LBB0_1128:
	s_or_b64 exec, exec, s[0:1]
	v_mul_f32_e32 v4, v0, v4
	v_mul_f32_e32 v4, v38, v4
	s_nop 1
	v_mov_b32_dpp v5, v4 quad_perm:[1,0,3,2] row_mask:0xf bank_mask:0xf
	s_and_saveexec_b64 s[0:1], s[8:9]
	s_cbranch_execz .LBB0_1130
	s_waitcnt lgkmcnt(0)
	v_cvt_pk_bf16_f32 v38, v4, v5
	v_add_co_u32_e32 v4, vcc, 0x12000, v2
	s_nop 1
	v_addc_co_u32_e32 v5, vcc, 0, v3, vcc
	global_store_dword v[4:5], v38, off offset:192
.LBB0_1130:
	s_or_b64 exec, exec, s[0:1]
	v_add_f32_e32 v4, v41, v42
	v_fmamk_f32 v4, v4, 0x3c000000, v241
	s_mov_b32 s0, 0xf800000
	s_waitcnt lgkmcnt(0)
	v_mul_f32_e32 v5, 0x4f800000, v4
	v_cmp_gt_f32_e32 vcc, s0, v4
	s_nop 1
	v_cndmask_b32_e32 v4, v4, v5, vcc
	v_sqrt_f32_e32 v5, v4
	s_nop 0
	v_add_u32_e32 v38, -1, v5
	v_fma_f32 v40, -v38, v5, v4
	v_add_u32_e32 v39, 1, v5
	v_cmp_ge_f32_e64 s[10:11], 0, v40
	s_nop 1
	v_cndmask_b32_e64 v38, v5, v38, s[10:11]
	v_fma_f32 v5, -v39, v5, v4
	v_cmp_lt_f32_e64 s[10:11], 0, v5
	s_nop 1
	v_cndmask_b32_e64 v5, v38, v39, s[10:11]
	v_mul_f32_e32 v38, 0x37800000, v5
	v_cndmask_b32_e32 v5, v5, v38, vcc
	v_cmp_class_f32_e32 vcc, v4, v247
	s_nop 1
	v_cndmask_b32_e32 v4, v5, v4, vcc
	v_div_scale_f32 v5, s[0:1], v4, v4, 1.0
	v_rcp_f32_e32 v38, v5
	s_nop 0
	v_fma_f32 v39, -v5, v38, 1.0
	v_fmac_f32_e32 v38, v39, v38
	v_div_scale_f32 v39, vcc, 1.0, v4, 1.0
	v_mul_f32_e32 v40, v39, v38
	v_fma_f32 v41, -v5, v40, v39
	v_fmac_f32_e32 v40, v41, v38
	v_fma_f32 v5, -v5, v40, v39
	v_div_fmas_f32 v5, v5, v38, v40
	v_div_fixup_f32 v4, v5, v4, 1.0
	v_mul_f32_e32 v5, v7, v4
	v_mul_f32_e32 v5, v37, v5
	s_nop 1
	v_mov_b32_dpp v37, v5 quad_perm:[1,0,3,2] row_mask:0xf bank_mask:0xf
	s_and_saveexec_b64 s[0:1], s[8:9]
	s_cbranch_execz .LBB0_1132
	v_add_co_u32_e32 v38, vcc, 0x13000, v2
	s_waitcnt lgkmcnt(0)
	v_cvt_pk_bf16_f32 v5, v5, v37
	s_nop 0
	v_addc_co_u32_e32 v39, vcc, 0, v3, vcc
	global_store_dword v[38:39], v5, off
.LBB0_1132:
	s_or_b64 exec, exec, s[0:1]
	v_mul_f32_e32 v5, v14, v4
	v_mul_f32_e32 v5, v36, v5
	s_nop 1
	v_mov_b32_dpp v36, v5 quad_perm:[1,0,3,2] row_mask:0xf bank_mask:0xf
	s_and_saveexec_b64 s[0:1], s[8:9]
	s_cbranch_execz .LBB0_1134
	s_waitcnt lgkmcnt(0)
	v_cvt_pk_bf16_f32 v5, v5, v36
	v_add_co_u32_e32 v36, vcc, 0x13000, v2
	s_nop 1
	v_addc_co_u32_e32 v37, vcc, 0, v3, vcc
	global_store_dword v[36:37], v5, off offset:64
.LBB0_1134:
	s_or_b64 exec, exec, s[0:1]
	v_mul_f32_e32 v5, v12, v4
	v_mul_f32_e32 v5, v33, v5
	s_nop 1
	v_mov_b32_dpp v33, v5 quad_perm:[1,0,3,2] row_mask:0xf bank_mask:0xf
	s_and_saveexec_b64 s[0:1], s[8:9]
	s_cbranch_execz .LBB0_1136
	s_waitcnt lgkmcnt(1)
	v_add_co_u32_e32 v36, vcc, 0x13000, v2
	s_waitcnt lgkmcnt(0)
	v_cvt_pk_bf16_f32 v5, v5, v33
	s_nop 0
	v_addc_co_u32_e32 v37, vcc, 0, v3, vcc
	global_store_dword v[36:37], v5, off offset:128
.LBB0_1136:
	s_or_b64 exec, exec, s[0:1]
	v_mul_f32_e32 v4, v0, v4
	v_mul_f32_e32 v4, v32, v4
	s_nop 1
	v_mov_b32_dpp v5, v4 quad_perm:[1,0,3,2] row_mask:0xf bank_mask:0xf
	s_and_saveexec_b64 s[0:1], s[8:9]
	s_cbranch_execz .LBB0_1138
	s_waitcnt lgkmcnt(0)
	v_cvt_pk_bf16_f32 v32, v4, v5
	v_add_co_u32_e32 v4, vcc, 0x13000, v2
	s_nop 1
	v_addc_co_u32_e32 v5, vcc, 0, v3, vcc
	global_store_dword v[4:5], v32, off offset:192
.LBB0_1138:
	s_or_b64 exec, exec, s[0:1]
	v_add_f32_e32 v4, v34, v35
	v_fmamk_f32 v4, v4, 0x3c000000, v241
	s_mov_b32 s0, 0xf800000
	s_waitcnt lgkmcnt(0)
	v_mul_f32_e32 v5, 0x4f800000, v4
	v_cmp_gt_f32_e32 vcc, s0, v4
	s_nop 1
	v_cndmask_b32_e32 v4, v4, v5, vcc
	v_sqrt_f32_e32 v5, v4
	s_nop 0
	v_add_u32_e32 v32, -1, v5
	v_fma_f32 v34, -v32, v5, v4
	v_add_u32_e32 v33, 1, v5
	v_cmp_ge_f32_e64 s[10:11], 0, v34
	s_nop 1
	v_cndmask_b32_e64 v32, v5, v32, s[10:11]
	v_fma_f32 v5, -v33, v5, v4
	v_cmp_lt_f32_e64 s[10:11], 0, v5
	s_nop 1
	v_cndmask_b32_e64 v5, v32, v33, s[10:11]
	v_mul_f32_e32 v32, 0x37800000, v5
	v_cndmask_b32_e32 v5, v5, v32, vcc
	v_cmp_class_f32_e32 vcc, v4, v247
	s_nop 1
	v_cndmask_b32_e32 v4, v5, v4, vcc
	v_div_scale_f32 v5, s[0:1], v4, v4, 1.0
	v_rcp_f32_e32 v32, v5
	s_nop 0
	v_fma_f32 v33, -v5, v32, 1.0
	v_fmac_f32_e32 v32, v33, v32
	v_div_scale_f32 v33, vcc, 1.0, v4, 1.0
	v_mul_f32_e32 v34, v33, v32
	v_fma_f32 v35, -v5, v34, v33
	v_fmac_f32_e32 v34, v35, v32
	v_fma_f32 v5, -v5, v34, v33
	v_div_fmas_f32 v5, v5, v32, v34
	v_div_fixup_f32 v4, v5, v4, 1.0
	v_mul_f32_e32 v5, v7, v4
	v_mul_f32_e32 v5, v29, v5
	s_nop 1
	v_mov_b32_dpp v29, v5 quad_perm:[1,0,3,2] row_mask:0xf bank_mask:0xf
	s_and_saveexec_b64 s[0:1], s[8:9]
	s_cbranch_execz .LBB0_1140
	v_add_co_u32_e32 v32, vcc, 0x18000, v2
	s_waitcnt lgkmcnt(0)
	v_cvt_pk_bf16_f32 v5, v5, v29
	s_nop 0
	v_addc_co_u32_e32 v33, vcc, 0, v3, vcc
	global_store_dword v[32:33], v5, off
.LBB0_1140:
	s_or_b64 exec, exec, s[0:1]
	v_mul_f32_e32 v5, v14, v4
	v_mul_f32_e32 v5, v28, v5
	s_nop 1
	v_mov_b32_dpp v28, v5 quad_perm:[1,0,3,2] row_mask:0xf bank_mask:0xf
	s_and_saveexec_b64 s[0:1], s[8:9]
	s_cbranch_execz .LBB0_1142
	s_waitcnt lgkmcnt(0)
	v_cvt_pk_bf16_f32 v5, v5, v28
	v_add_co_u32_e32 v28, vcc, 0x18000, v2
	s_nop 1
	v_addc_co_u32_e32 v29, vcc, 0, v3, vcc
	global_store_dword v[28:29], v5, off offset:64
; #define GAS __attribute__((address_space(1)))
; __device__ __forceinline__ unsigned cvtpk(float lo, float hi) { unsigned r; asm volatile("v_cvt_pk_bf16_f32 %0, %1, %2" : "=v"(r) : "v"(lo), "v"(hi)); return r; }
; __device__ __forceinline__ int crow(int r, int hi) { return (r & 3) + 8 * (r >> 2) + 4 * hi; }
; __device__ __forceinline__ void store_o(const f32x16 (&o)[4], bf16_t* Ow, int pitch, int r32, int hi) {
; #pragma unroll
;     for (int r = 0; r < 16; ++r) { const int orow = crow(r, hi);
; #pragma unroll
;         for (int d0 = 0; d0 < 4; ++d0) { const float v = o[d0][r]; const float vn = __shfl_xor(v, 1);
;             if ((r32 & 1) == 0) *(GAS unsigned*)(Ow + (size_t)orow * pitch + d0 * 32 + r32) = cvtpk(v, vn); } }
; __device__ __forceinline__ void ph_attn(const Args& a, char* lds, int l, int rep) {
;     ...
;             for (int r = 0; r < 16; ++r) { float ss = 0.f;
; #pragma unroll
;                 for (int d = 0; d < 4; ++d) { const unsigned pw = o1p[d][r >> 1]; const float o1v = __uint_as_float((r & 1) ? (pw & 0xffff0000u) : (pw << 16)); const float v = o1v - lam * o[d][r]; o[d][r] = v; ss += v * v; }
;                 ss += __shfl_xor(ss, 1); ss += __shfl_xor(ss, 2); ss += __shfl_xor(ss, 4); ss += __shfl_xor(ss, 8); ss += __shfl_xor(ss, 16);
;                 const float rs = 1.0f / sqrtf(ss * (1.0f / 128.0f) + EPSN);
; #pragma unroll
;                 for (int d = 0; d < 4; ++d) o[d][r] *= rs * gd[d]; }
.LBB0_1142:
	s_or_b64 exec, exec, s[0:1]
	v_mul_f32_e32 v5, v12, v4
	v_mul_f32_e32 v5, v27, v5
	s_nop 1
	v_mov_b32_dpp v27, v5 quad_perm:[1,0,3,2] row_mask:0xf bank_mask:0xf
	s_and_saveexec_b64 s[0:1], s[8:9]
	s_cbranch_execz .LBB0_1144
	s_waitcnt lgkmcnt(1)
	v_add_co_u32_e32 v28, vcc, 0x18000, v2
	s_waitcnt lgkmcnt(0)
	v_cvt_pk_bf16_f32 v5, v5, v27
	s_nop 0
	v_addc_co_u32_e32 v29, vcc, 0, v3, vcc
	global_store_dword v[28:29], v5, off offset:128
.LBB0_1144:
	s_or_b64 exec, exec, s[0:1]
	v_mul_f32_e32 v4, v0, v4
	v_mul_f32_e32 v4, v26, v4
	s_nop 1
	v_mov_b32_dpp v5, v4 quad_perm:[1,0,3,2] row_mask:0xf bank_mask:0xf
	s_and_saveexec_b64 s[0:1], s[8:9]
	s_cbranch_execz .LBB0_1146
	s_waitcnt lgkmcnt(0)
	v_cvt_pk_bf16_f32 v26, v4, v5
	v_add_co_u32_e32 v4, vcc, 0x18000, v2
	s_nop 1
	v_addc_co_u32_e32 v5, vcc, 0, v3, vcc
	global_store_dword v[4:5], v26, off offset:192
.LBB0_1146:
	s_or_b64 exec, exec, s[0:1]
	v_add_f32_e32 v4, v30, v31
	v_fmamk_f32 v4, v4, 0x3c000000, v241
	s_mov_b32 s0, 0xf800000
	s_waitcnt lgkmcnt(0)
	v_mul_f32_e32 v5, 0x4f800000, v4
	v_cmp_gt_f32_e32 vcc, s0, v4
	s_nop 1
	v_cndmask_b32_e32 v4, v4, v5, vcc
	v_sqrt_f32_e32 v5, v4
	s_nop 0
	v_add_u32_e32 v26, -1, v5
	v_fma_f32 v28, -v26, v5, v4
	v_add_u32_e32 v27, 1, v5
	v_cmp_ge_f32_e64 s[10:11], 0, v28
	s_nop 1
	v_cndmask_b32_e64 v26, v5, v26, s[10:11]
	v_fma_f32 v5, -v27, v5, v4
	v_cmp_lt_f32_e64 s[10:11], 0, v5
	s_nop 1
	v_cndmask_b32_e64 v5, v26, v27, s[10:11]
	v_mul_f32_e32 v26, 0x37800000, v5
	v_cndmask_b32_e32 v5, v5, v26, vcc
	v_cmp_class_f32_e32 vcc, v4, v247
	s_nop 1
	v_cndmask_b32_e32 v4, v5, v4, vcc
	v_div_scale_f32 v5, s[0:1], v4, v4, 1.0
	v_rcp_f32_e32 v26, v5
	s_nop 0
	v_fma_f32 v27, -v5, v26, 1.0
	v_fmac_f32_e32 v26, v27, v26
	v_div_scale_f32 v27, vcc, 1.0, v4, 1.0
	v_mul_f32_e32 v28, v27, v26
	v_fma_f32 v29, -v5, v28, v27
	v_fmac_f32_e32 v28, v29, v26
	v_fma_f32 v5, -v5, v28, v27
	v_div_fmas_f32 v5, v5, v26, v28
	v_div_fixup_f32 v4, v5, v4, 1.0
	v_mul_f32_e32 v5, v7, v4
	v_mul_f32_e32 v5, v25, v5
	s_nop 1
	v_mov_b32_dpp v25, v5 quad_perm:[1,0,3,2] row_mask:0xf bank_mask:0xf
	s_and_saveexec_b64 s[0:1], s[8:9]
	s_cbranch_execz .LBB0_1148
	v_add_co_u32_e32 v26, vcc, 0x19000, v2
	s_waitcnt lgkmcnt(0)
	v_cvt_pk_bf16_f32 v5, v5, v25
	s_nop 0
	v_addc_co_u32_e32 v27, vcc, 0, v3, vcc
	global_store_dword v[26:27], v5, off
.LBB0_1148:
	s_or_b64 exec, exec, s[0:1]
	v_mul_f32_e32 v5, v14, v4
	v_mul_f32_e32 v5, v22, v5
	s_nop 1
	v_mov_b32_dpp v22, v5 quad_perm:[1,0,3,2] row_mask:0xf bank_mask:0xf
	s_and_saveexec_b64 s[0:1], s[8:9]
	s_cbranch_execz .LBB0_1150
	v_add_co_u32_e32 v26, vcc, 0x19000, v2
	s_waitcnt lgkmcnt(0)
	v_cvt_pk_bf16_f32 v5, v5, v22
	s_nop 0
	v_addc_co_u32_e32 v27, vcc, 0, v3, vcc
	global_store_dword v[26:27], v5, off offset:64
.LBB0_1150:
	s_or_b64 exec, exec, s[0:1]
	v_mul_f32_e32 v5, v12, v4
	v_mul_f32_e32 v5, v21, v5
	s_nop 1
	v_mov_b32_dpp v21, v5 quad_perm:[1,0,3,2] row_mask:0xf bank_mask:0xf
	s_and_saveexec_b64 s[0:1], s[8:9]
	s_cbranch_execz .LBB0_1152
	v_add_co_u32_e32 v26, vcc, 0x19000, v2
	s_waitcnt lgkmcnt(0)
	v_cvt_pk_bf16_f32 v5, v5, v21
	s_nop 0
	v_addc_co_u32_e32 v27, vcc, 0, v3, vcc
	global_store_dword v[26:27], v5, off offset:128
.LBB0_1152:
	s_or_b64 exec, exec, s[0:1]
	v_mul_f32_e32 v4, v0, v4
	v_mul_f32_e32 v4, v20, v4
	s_nop 1
	v_mov_b32_dpp v5, v4 quad_perm:[1,0,3,2] row_mask:0xf bank_mask:0xf
	s_and_saveexec_b64 s[0:1], s[8:9]
	s_cbranch_execz .LBB0_1154
	s_waitcnt lgkmcnt(0)
	v_cvt_pk_bf16_f32 v20, v4, v5
	v_add_co_u32_e32 v4, vcc, 0x19000, v2
	s_nop 1
	v_addc_co_u32_e32 v5, vcc, 0, v3, vcc
	global_store_dword v[4:5], v20, off offset:192
.LBB0_1154:
	s_or_b64 exec, exec, s[0:1]
	v_add_f32_e32 v4, v23, v24
	v_fmamk_f32 v4, v4, 0x3c000000, v241
	s_mov_b32 s0, 0xf800000
	s_waitcnt lgkmcnt(0)
	v_mul_f32_e32 v5, 0x4f800000, v4
	v_cmp_gt_f32_e32 vcc, s0, v4
	s_nop 1
	v_cndmask_b32_e32 v4, v4, v5, vcc
	v_sqrt_f32_e32 v5, v4
	s_nop 0
	v_add_u32_e32 v20, -1, v5
	v_fma_f32 v22, -v20, v5, v4
	v_add_u32_e32 v21, 1, v5
	v_cmp_ge_f32_e64 s[10:11], 0, v22
	s_nop 1
	v_cndmask_b32_e64 v20, v5, v20, s[10:11]
	v_fma_f32 v5, -v21, v5, v4
	v_cmp_lt_f32_e64 s[10:11], 0, v5
	s_nop 1
	v_cndmask_b32_e64 v5, v20, v21, s[10:11]
	v_mul_f32_e32 v20, 0x37800000, v5
	v_cndmask_b32_e32 v5, v5, v20, vcc
	v_cmp_class_f32_e32 vcc, v4, v247
	s_nop 1
	v_cndmask_b32_e32 v4, v5, v4, vcc
	v_div_scale_f32 v5, s[0:1], v4, v4, 1.0
	v_rcp_f32_e32 v20, v5
	s_nop 0
	v_fma_f32 v21, -v5, v20, 1.0
	v_fmac_f32_e32 v20, v21, v20
	v_div_scale_f32 v21, vcc, 1.0, v4, 1.0
	v_mul_f32_e32 v22, v21, v20
	v_fma_f32 v23, -v5, v22, v21
	v_fmac_f32_e32 v22, v23, v20
	v_fma_f32 v5, -v5, v22, v21
	v_div_fmas_f32 v5, v5, v20, v22
	v_div_fixup_f32 v4, v5, v4, 1.0
	v_mul_f32_e32 v5, v7, v4
	v_mul_f32_e32 v5, v19, v5
	s_nop 1
	v_mov_b32_dpp v19, v5 quad_perm:[1,0,3,2] row_mask:0xf bank_mask:0xf
	s_and_saveexec_b64 s[0:1], s[8:9]
	s_cbranch_execz .LBB0_1156
	v_add_co_u32_e32 v20, vcc, 0x1a000, v2
	s_waitcnt lgkmcnt(0)
	v_cvt_pk_bf16_f32 v5, v5, v19
	s_nop 0
	v_addc_co_u32_e32 v21, vcc, 0, v3, vcc
	global_store_dword v[20:21], v5, off
; #define GAS __attribute__((address_space(1)))
; __device__ __forceinline__ unsigned cvtpk(float lo, float hi) { unsigned r; asm volatile("v_cvt_pk_bf16_f32 %0, %1, %2" : "=v"(r) : "v"(lo), "v"(hi)); return r; }
; __device__ __forceinline__ int crow(int r, int hi) { return (r & 3) + 8 * (r >> 2) + 4 * hi; }
; __device__ __forceinline__ void store_o(const f32x16 (&o)[4], bf16_t* Ow, int pitch, int r32, int hi) {
; #pragma unroll
;     for (int r = 0; r < 16; ++r) { const int orow = crow(r, hi);
; #pragma unroll
;         for (int d0 = 0; d0 < 4; ++d0) { const float v = o[d0][r]; const float vn = __shfl_xor(v, 1);
;             if ((r32 & 1) == 0) *(GAS unsigned*)(Ow + (size_t)orow * pitch + d0 * 32 + r32) = cvtpk(v, vn); } }
; __device__ __forceinline__ void ph_attn(const Args& a, char* lds, int l, int rep) {
;     ...
;             for (int r = 0; r < 16; ++r) { float ss = 0.f;
; #pragma unroll
;                 for (int d = 0; d < 4; ++d) { const unsigned pw = o1p[d][r >> 1]; const float o1v = __uint_as_float((r & 1) ? (pw & 0xffff0000u) : (pw << 16)); const float v = o1v - lam * o[d][r]; o[d][r] = v; ss += v * v; }
;                 ss += __shfl_xor(ss, 1); ss += __shfl_xor(ss, 2); ss += __shfl_xor(ss, 4); ss += __shfl_xor(ss, 8); ss += __shfl_xor(ss, 16);
;                 const float rs = 1.0f / sqrtf(ss * (1.0f / 128.0f) + EPSN);
; #pragma unroll
;                 for (int d = 0; d < 4; ++d) o[d][r] *= rs * gd[d]; }
.LBB0_1156:
	s_or_b64 exec, exec, s[0:1]
	v_mul_f32_e32 v5, v14, v4
	v_mul_f32_e32 v5, v18, v5
	s_nop 1
	v_mov_b32_dpp v18, v5 quad_perm:[1,0,3,2] row_mask:0xf bank_mask:0xf
	s_and_saveexec_b64 s[0:1], s[8:9]
	s_cbranch_execz .LBB0_1158
	s_waitcnt lgkmcnt(0)
	v_cvt_pk_bf16_f32 v5, v5, v18
	v_add_co_u32_e32 v18, vcc, 0x1a000, v2
	s_nop 1
	v_addc_co_u32_e32 v19, vcc, 0, v3, vcc
	global_store_dword v[18:19], v5, off offset:64
.LBB0_1158:
	s_or_b64 exec, exec, s[0:1]
	v_mul_f32_e32 v5, v12, v4
	v_mul_f32_e32 v5, v15, v5
	s_nop 1
	v_mov_b32_dpp v15, v5 quad_perm:[1,0,3,2] row_mask:0xf bank_mask:0xf
	s_and_saveexec_b64 s[0:1], s[8:9]
	s_cbranch_execz .LBB0_1160
	s_waitcnt lgkmcnt(1)
	v_add_co_u32_e32 v18, vcc, 0x1a000, v2
	s_waitcnt lgkmcnt(0)
	v_cvt_pk_bf16_f32 v5, v5, v15
	s_nop 0
	v_addc_co_u32_e32 v19, vcc, 0, v3, vcc
	global_store_dword v[18:19], v5, off offset:128
.LBB0_1160:
	s_or_b64 exec, exec, s[0:1]
	v_mul_f32_e32 v4, v0, v4
	v_mul_f32_e32 v4, v13, v4
	s_nop 1
	v_mov_b32_dpp v5, v4 quad_perm:[1,0,3,2] row_mask:0xf bank_mask:0xf
	s_and_saveexec_b64 s[0:1], s[8:9]
	s_cbranch_execz .LBB0_1162
	s_waitcnt lgkmcnt(0)
	v_cvt_pk_bf16_f32 v13, v4, v5
	v_add_co_u32_e32 v4, vcc, 0x1a000, v2
	s_nop 1
	v_addc_co_u32_e32 v5, vcc, 0, v3, vcc
	global_store_dword v[4:5], v13, off offset:192
.LBB0_1162:
	s_or_b64 exec, exec, s[0:1]
	v_add_f32_e32 v4, v16, v17
	v_fmamk_f32 v4, v4, 0x3c000000, v241
	s_mov_b32 s0, 0xf800000
	s_waitcnt lgkmcnt(0)
	v_mul_f32_e32 v5, 0x4f800000, v4
	v_cmp_gt_f32_e32 vcc, s0, v4
	s_nop 1
	v_cndmask_b32_e32 v4, v4, v5, vcc
	v_sqrt_f32_e32 v5, v4
	s_nop 0
	v_add_u32_e32 v13, -1, v5
	v_fma_f32 v16, -v13, v5, v4
	v_add_u32_e32 v15, 1, v5
	v_cmp_ge_f32_e64 s[10:11], 0, v16
	s_nop 1
	v_cndmask_b32_e64 v13, v5, v13, s[10:11]
	v_fma_f32 v5, -v15, v5, v4
	v_cmp_lt_f32_e64 s[10:11], 0, v5
	s_nop 1
	v_cndmask_b32_e64 v5, v13, v15, s[10:11]
	v_mul_f32_e32 v13, 0x37800000, v5
	v_cndmask_b32_e32 v5, v5, v13, vcc
	v_cmp_class_f32_e32 vcc, v4, v247
	s_nop 1
	v_cndmask_b32_e32 v4, v5, v4, vcc
	v_div_scale_f32 v5, s[0:1], v4, v4, 1.0
	v_rcp_f32_e32 v13, v5
	s_nop 0
	v_fma_f32 v15, -v5, v13, 1.0
	v_fmac_f32_e32 v13, v15, v13
	v_div_scale_f32 v15, vcc, 1.0, v4, 1.0
	v_mul_f32_e32 v16, v15, v13
	v_fma_f32 v17, -v5, v16, v15
	v_fmac_f32_e32 v16, v17, v13
	v_fma_f32 v5, -v5, v16, v15
	v_div_fmas_f32 v5, v5, v13, v16
	v_div_fixup_f32 v4, v5, v4, 1.0
	v_mul_f32_e32 v5, v7, v4
	v_mul_f32_e32 v5, v11, v5
	s_nop 1
	v_mov_b32_dpp v7, v5 quad_perm:[1,0,3,2] row_mask:0xf bank_mask:0xf
	s_and_saveexec_b64 s[0:1], s[8:9]
	s_cbranch_execz .LBB0_1164
	v_add_co_u32_e32 v16, vcc, 0x1b000, v2
	s_waitcnt lgkmcnt(0)
	v_cvt_pk_bf16_f32 v5, v5, v7
	s_nop 0
	v_addc_co_u32_e32 v17, vcc, 0, v3, vcc
	global_store_dword v[16:17], v5, off
.LBB0_1164:
	s_or_b64 exec, exec, s[0:1]
	v_mul_f32_e32 v5, v14, v4
	v_mul_f32_e32 v5, v10, v5
	s_waitcnt lgkmcnt(0)
	s_nop 1
	v_mov_b32_dpp v7, v5 quad_perm:[1,0,3,2] row_mask:0xf bank_mask:0xf
	s_and_saveexec_b64 s[0:1], s[8:9]
	s_cbranch_execz .LBB0_1166
	v_add_co_u32_e32 v10, vcc, 0x1b000, v2
	s_waitcnt lgkmcnt(0)
	v_cvt_pk_bf16_f32 v5, v5, v7
	s_nop 0
	v_addc_co_u32_e32 v11, vcc, 0, v3, vcc
	global_store_dword v[10:11], v5, off offset:64
.LBB0_1166:
	s_or_b64 exec, exec, s[0:1]
	v_mul_f32_e32 v5, v12, v4
	v_mul_f32_e32 v5, v9, v5
	s_waitcnt lgkmcnt(0)
	s_nop 1
	v_mov_b32_dpp v7, v5 quad_perm:[1,0,3,2] row_mask:0xf bank_mask:0xf
	s_and_saveexec_b64 s[0:1], s[8:9]
	s_cbranch_execz .LBB0_1168
	v_add_co_u32_e32 v10, vcc, 0x1b000, v2
	s_waitcnt lgkmcnt(0)
	v_cvt_pk_bf16_f32 v5, v5, v7
	s_nop 0
	v_addc_co_u32_e32 v11, vcc, 0, v3, vcc
	global_store_dword v[10:11], v5, off offset:128
.LBB0_1168:
	s_or_b64 exec, exec, s[0:1]
	v_mul_f32_e32 v0, v0, v4
	v_mul_f32_e32 v0, v8, v0
	s_nop 1
	v_mov_b32_dpp v4, v0 quad_perm:[1,0,3,2] row_mask:0xf bank_mask:0xf
	s_and_saveexec_b64 s[0:1], s[8:9]
	s_xor_b64 s[0:1], exec, s[0:1]
	s_cbranch_execz .LBB0_1170
	v_add_co_u32_e32 v2, vcc, 0x1b000, v2
	s_waitcnt lgkmcnt(0)
	v_cvt_pk_bf16_f32 v0, v0, v4
	s_nop 0
	v_addc_co_u32_e32 v3, vcc, 0, v3, vcc
	global_store_dword v[2:3], v0, off offset:192

; #define GAS __attribute__((address_space(1)))
; __device__ __forceinline__ unsigned cvtpk(float lo, float hi) { unsigned r; asm volatile("v_cvt_pk_bf16_f32 %0, %1, %2" : "=v"(r) : "v"(lo), "v"(hi)); return r; }
; __device__ __forceinline__ int crow(int r, int hi) { return (r & 3) + 8 * (r >> 2) + 4 * hi; }
; template <int DK, int MODE> ...
;     ...
;     if (hi == 0) ws[32 + r32] = l_reg; asm volatile("s_waitcnt lgkmcnt(0)" ::: "memory");
; #pragma unroll
;     for (int r = 0; r < 16; ++r) { const float rl = __builtin_amdgcn_rcpf(ws[32 + crow(r, hi)]);
; #pragma unroll
;         for (int d = 0; d < 4; ++d) o[d][r] *= rl; }
; __device__ __forceinline__ void store_o(const f32x16 (&o)[4], bf16_t* Ow, int pitch, int r32, int hi) {
; #pragma unroll
;     for (int r = 0; r < 16; ++r) { const int orow = crow(r, hi);
; #pragma unroll
;         for (int d0 = 0; d0 < 4; ++d0) { const float v = o[d0][r]; const float vn = __shfl_xor(v, 1);
;             if ((r32 & 1) == 0) *(GAS unsigned*)(Ow + (size_t)orow * pitch + d0 * 32 + r32) = cvtpk(v, vn); } }
.LBB0_1197:
	s_and_saveexec_b64 s[0:1], s[10:11]
	ds_write_b32 v153, v181 offset:128
	s_or_b64 exec, exec, s[0:1]
	s_waitcnt lgkmcnt(0)
	v_add_u32_e32 v0, s4, v152
	ds_read_b128 v[78:81], v0 offset:128
	ds_read_b128 v[74:77], v0 offset:160
	s_lshl_b64 s[0:1], s[76:77], 12
	v_readlane_b32 s2, v255, 38
	ds_read_b128 v[70:73], v0 offset:192
	ds_read_b128 v[66:69], v0 offset:224
	s_waitcnt lgkmcnt(0)
	v_rcp_f32_e32 v78, v78
	s_add_u32 s0, s2, s0
	v_readlane_b32 s2, v255, 39
	v_xor_b32_e32 v0, 1, v243
	v_mul_f32_e32 v86, v34, v78
	v_and_b32_e32 v34, 64, v243
	v_add_u32_e32 v34, 64, v34
	s_addc_u32 s1, s2, s1
	s_lshl_b32 s2, s86, 8
	v_cmp_lt_i32_e32 vcc, v0, v34
	s_add_u32 s0, s0, s2
	s_addc_u32 s1, s1, 0
	v_cndmask_b32_e32 v0, v243, v0, vcc
	v_lshlrev_b32_e32 v34, 2, v0
	v_lshlrev_b32_e32 v0, 1, v146
	v_lshl_add_u64 v[82:83], s[0:1], 0, v[0:1]
	v_lshlrev_b32_e32 v0, 1, v148
	v_lshl_add_u64 v[84:85], v[82:83], 0, v[0:1]
	s_nop 1
	v_mov_b32_dpp v0, v86 quad_perm:[1,0,3,2] row_mask:0xf bank_mask:0xf
	s_waitcnt lgkmcnt(0)
	s_mov_b64 s[0:1], 0x400
	v_lshl_add_u64 v[82:83], v[84:85], 0, s[0:1]
	s_and_saveexec_b64 s[0:1], s[8:9]
	s_cbranch_execz .LBB0_1201
	s_waitcnt lgkmcnt(0)
	v_cvt_pk_bf16_f32 v0, v86, v0
	global_store_dword v[82:83], v0, off
.LBB0_1201:
	s_or_b64 exec, exec, s[0:1]
	s_waitcnt lgkmcnt(0)
	v_mul_f32_e32 v0, v50, v78
	s_nop 1
	v_mov_b32_dpp v50, v0 quad_perm:[1,0,3,2] row_mask:0xf bank_mask:0xf
	s_and_saveexec_b64 s[0:1], s[8:9]
	s_cbranch_execz .LBB0_1203
	s_waitcnt lgkmcnt(0)
	v_cvt_pk_bf16_f32 v0, v0, v50
	global_store_dword v[84:85], v0, off offset:1088
.LBB0_1203:
	s_or_b64 exec, exec, s[0:1]
	v_mul_f32_e32 v0, v18, v78
	s_nop 1
	v_mov_b32_dpp v18, v0 quad_perm:[1,0,3,2] row_mask:0xf bank_mask:0xf
	s_and_saveexec_b64 s[0:1], s[8:9]
	s_cbranch_execz .LBB0_1205
	s_waitcnt lgkmcnt(0)
	v_cvt_pk_bf16_f32 v0, v0, v18
	global_store_dword v[84:85], v0, off offset:1152
.LBB0_1205:
	s_or_b64 exec, exec, s[0:1]
	v_mul_f32_e32 v0, v2, v78
	s_nop 1
	v_mov_b32_dpp v2, v0 quad_perm:[1,0,3,2] row_mask:0xf bank_mask:0xf
	s_and_saveexec_b64 s[0:1], s[8:9]
	s_cbranch_execz .LBB0_1207
	s_waitcnt lgkmcnt(0)
	v_cvt_pk_bf16_f32 v0, v0, v2
	global_store_dword v[84:85], v0, off offset:1216

; #define GAS __attribute__((address_space(1)))
; __device__ __forceinline__ unsigned cvtpk(float lo, float hi) { unsigned r; asm volatile("v_cvt_pk_bf16_f32 %0, %1, %2" : "=v"(r) : "v"(lo), "v"(hi)); return r; }
; __device__ __forceinline__ int crow(int r, int hi) { return (r & 3) + 8 * (r >> 2) + 4 * hi; }
; __device__ __forceinline__ void store_o(const f32x16 (&o)[4], bf16_t* Ow, int pitch, int r32, int hi) {
; #pragma unroll
;     for (int r = 0; r < 16; ++r) { const int orow = crow(r, hi);
; #pragma unroll
;         for (int d0 = 0; d0 < 4; ++d0) { const float v = o[d0][r]; const float vn = __shfl_xor(v, 1);
;             if ((r32 & 1) == 0) *(GAS unsigned*)(Ow + (size_t)orow * pitch + d0 * 32 + r32) = cvtpk(v, vn); } }
.LBB0_1325:
	s_or_b64 exec, exec, s[0:1]
	v_mul_f32_e32 v0, v17, v0
	s_nop 1
	v_mov_b32_dpp v2, v0 quad_perm:[1,0,3,2] row_mask:0xf bank_mask:0xf
	s_and_saveexec_b64 s[0:1], s[8:9]
	s_xor_b64 s[0:1], exec, s[0:1]
	s_cbranch_execz .LBB0_859
	s_waitcnt lgkmcnt(0)
	v_cvt_pk_bf16_f32 v0, v0, v2
	v_add_co_u32_e32 v2, vcc, 0x1b000, v82
	s_nop 1
	v_addc_co_u32_e32 v3, vcc, 0, v83, vcc
	global_store_dword v[2:3], v0, off offset:192
	s_branch .LBB0_859

; #define GAS __attribute__((address_space(1)))
; __device__ __forceinline__ unsigned cvtpk(float lo, float hi) { unsigned r; asm volatile("v_cvt_pk_bf16_f32 %0, %1, %2" : "=v"(r) : "v"(lo), "v"(hi)); return r; }
; __device__ __forceinline__ int crow(int r, int hi) { return (r & 3) + 8 * (r >> 2) + 4 * hi; }
; template <int DK, int MODE> ...
;     ...
;     for (int r = 0; r < 16; ++r) { const float rl = __builtin_amdgcn_rcpf(ws[32 + crow(r, hi)]);
; #pragma unroll
;         for (int d = 0; d < 4; ++d) o[d][r] *= rl; }
; __device__ __forceinline__ void store_o(const f32x16 (&o)[4], bf16_t* Ow, int pitch, int r32, int hi) {
; #pragma unroll
;     for (int r = 0; r < 16; ++r) { const int orow = crow(r, hi);
; #pragma unroll
;         for (int d0 = 0; d0 < 4; ++d0) { const float v = o[d0][r]; const float vn = __shfl_xor(v, 1);
;             if ((r32 & 1) == 0) *(GAS unsigned*)(Ow + (size_t)orow * pitch + d0 * 32 + r32) = cvtpk(v, vn); } }
.LBB0_1626:
	s_or_b64 exec, exec, s[0:1]
	v_mul_f32_e32 v48, v48, v80
	s_nop 1
	v_mov_b32_dpp v64, v48 quad_perm:[1,0,3,2] row_mask:0xf bank_mask:0xf
	s_and_saveexec_b64 s[0:1], s[4:5]
	s_cbranch_execz .LBB0_1628
	s_waitcnt lgkmcnt(0)
	v_cvt_pk_bf16_f32 v48, v48, v64
	global_store_dword v[14:15], v48, off offset:64
.LBB0_1628:
	s_or_b64 exec, exec, s[0:1]
	v_mul_f32_e32 v32, v32, v80
	s_nop 1
	v_mov_b32_dpp v48, v32 quad_perm:[1,0,3,2] row_mask:0xf bank_mask:0xf
	s_and_saveexec_b64 s[0:1], s[4:5]
	s_cbranch_execz .LBB0_1630
	s_waitcnt lgkmcnt(0)
	v_cvt_pk_bf16_f32 v32, v32, v48
	global_store_dword v[14:15], v32, off offset:128
.LBB0_1630:
	s_or_b64 exec, exec, s[0:1]
	v_mul_f32_e32 v16, v16, v80
	s_nop 1
	v_mov_b32_dpp v32, v16 quad_perm:[1,0,3,2] row_mask:0xf bank_mask:0xf
	s_and_saveexec_b64 s[0:1], s[4:5]
	s_cbranch_execz .LBB0_1632
	s_waitcnt lgkmcnt(0)
	v_cvt_pk_bf16_f32 v16, v16, v32
	global_store_dword v[14:15], v16, off offset:192
.LBB0_1632:
	s_or_b64 exec, exec, s[0:1]
	v_rcp_f32_e32 v16, v81
	s_waitcnt lgkmcnt(0)
	v_mul_f32_e32 v32, v65, v16
	s_nop 1
	v_mov_b32_dpp v48, v32 quad_perm:[1,0,3,2] row_mask:0xf bank_mask:0xf
	s_and_saveexec_b64 s[0:1], s[4:5]
	s_cbranch_execz .LBB0_1634
	s_waitcnt lgkmcnt(0)
	v_cvt_pk_bf16_f32 v32, v32, v48
	global_store_dword v[14:15], v32, off offset:1024
.LBB0_1634:
	s_or_b64 exec, exec, s[0:1]
	v_mul_f32_e32 v32, v49, v16
	s_waitcnt lgkmcnt(0)
	s_nop 1
	v_mov_b32_dpp v48, v32 quad_perm:[1,0,3,2] row_mask:0xf bank_mask:0xf
	s_and_saveexec_b64 s[0:1], s[4:5]
	s_cbranch_execz .LBB0_1636
	s_waitcnt lgkmcnt(0)
	v_cvt_pk_bf16_f32 v32, v32, v48
	global_store_dword v[14:15], v32, off offset:1088
.LBB0_1636:
	s_or_b64 exec, exec, s[0:1]
	v_mul_f32_e32 v32, v33, v16
	s_nop 1
	v_mov_b32_dpp v33, v32 quad_perm:[1,0,3,2] row_mask:0xf bank_mask:0xf
	s_and_saveexec_b64 s[0:1], s[4:5]
	s_cbranch_execz .LBB0_1638
	s_waitcnt lgkmcnt(0)
	v_cvt_pk_bf16_f32 v32, v32, v33
	global_store_dword v[14:15], v32, off offset:1152
.LBB0_1638:
	s_or_b64 exec, exec, s[0:1]
	v_mul_f32_e32 v16, v17, v16
	s_nop 1
	v_mov_b32_dpp v17, v16 quad_perm:[1,0,3,2] row_mask:0xf bank_mask:0xf
	s_and_saveexec_b64 s[0:1], s[4:5]
	s_cbranch_execz .LBB0_1640
	s_waitcnt lgkmcnt(0)
	v_cvt_pk_bf16_f32 v16, v16, v17
	global_store_dword v[14:15], v16, off offset:1216
.LBB0_1640:
	s_or_b64 exec, exec, s[0:1]
	v_rcp_f32_e32 v16, v82
	s_waitcnt lgkmcnt(0)
	v_mul_f32_e32 v17, v66, v16
	s_nop 1
	v_mov_b32_dpp v32, v17 quad_perm:[1,0,3,2] row_mask:0xf bank_mask:0xf
	s_and_saveexec_b64 s[0:1], s[4:5]
	s_cbranch_execz .LBB0_1642
	s_waitcnt lgkmcnt(0)
	v_cvt_pk_bf16_f32 v17, v17, v32
	global_store_dword v[14:15], v17, off offset:2048
.LBB0_1642:
	s_or_b64 exec, exec, s[0:1]
	v_mul_f32_e32 v17, v50, v16
	s_waitcnt lgkmcnt(0)
	s_nop 1
	v_mov_b32_dpp v32, v17 quad_perm:[1,0,3,2] row_mask:0xf bank_mask:0xf
	s_and_saveexec_b64 s[0:1], s[4:5]
	s_cbranch_execz .LBB0_1644
	s_waitcnt lgkmcnt(0)
	v_cvt_pk_bf16_f32 v17, v17, v32
	global_store_dword v[14:15], v17, off offset:2112
.LBB0_1644:
	s_or_b64 exec, exec, s[0:1]
	v_mul_f32_e32 v17, v34, v16
	s_waitcnt lgkmcnt(0)
	s_nop 1
	v_mov_b32_dpp v32, v17 quad_perm:[1,0,3,2] row_mask:0xf bank_mask:0xf
	s_and_saveexec_b64 s[0:1], s[4:5]
	s_cbranch_execz .LBB0_1646
	s_waitcnt lgkmcnt(0)
	v_cvt_pk_bf16_f32 v17, v17, v32
	global_store_dword v[14:15], v17, off offset:2176
.LBB0_1646:
	s_or_b64 exec, exec, s[0:1]
	v_mul_f32_e32 v16, v18, v16
	s_nop 1
	v_mov_b32_dpp v17, v16 quad_perm:[1,0,3,2] row_mask:0xf bank_mask:0xf
	s_and_saveexec_b64 s[0:1], s[4:5]
	s_cbranch_execz .LBB0_1648
	s_waitcnt lgkmcnt(0)
	v_cvt_pk_bf16_f32 v16, v16, v17
	global_store_dword v[14:15], v16, off offset:2240
.LBB0_1648:
	s_or_b64 exec, exec, s[0:1]
	v_rcp_f32_e32 v16, v83
	s_waitcnt lgkmcnt(0)
	v_mul_f32_e32 v17, v67, v16
	s_nop 1
	v_mov_b32_dpp v18, v17 quad_perm:[1,0,3,2] row_mask:0xf bank_mask:0xf
	s_and_saveexec_b64 s[0:1], s[4:5]
	s_cbranch_execz .LBB0_1650
	s_waitcnt lgkmcnt(0)
	v_cvt_pk_bf16_f32 v17, v17, v18
	global_store_dword v[14:15], v17, off offset:3072
.LBB0_1650:
	s_or_b64 exec, exec, s[0:1]
	v_mul_f32_e32 v17, v51, v16
	s_waitcnt lgkmcnt(0)
	s_nop 1
	v_mov_b32_dpp v18, v17 quad_perm:[1,0,3,2] row_mask:0xf bank_mask:0xf
	s_and_saveexec_b64 s[0:1], s[4:5]
	s_cbranch_execz .LBB0_1652
	s_waitcnt lgkmcnt(0)
	v_cvt_pk_bf16_f32 v17, v17, v18
	global_store_dword v[14:15], v17, off offset:3136
.LBB0_1652:
	s_or_b64 exec, exec, s[0:1]
	v_mul_f32_e32 v17, v35, v16
	s_waitcnt lgkmcnt(0)
	s_nop 1
	v_mov_b32_dpp v18, v17 quad_perm:[1,0,3,2] row_mask:0xf bank_mask:0xf
	s_and_saveexec_b64 s[0:1], s[4:5]
	s_cbranch_execz .LBB0_1654
	s_waitcnt lgkmcnt(0)
	v_cvt_pk_bf16_f32 v17, v17, v18
	global_store_dword v[14:15], v17, off offset:3200
.LBB0_1654:
	s_or_b64 exec, exec, s[0:1]
	v_mul_f32_e32 v16, v19, v16
	s_nop 1
	v_mov_b32_dpp v17, v16 quad_perm:[1,0,3,2] row_mask:0xf bank_mask:0xf
	s_and_saveexec_b64 s[0:1], s[4:5]
	s_cbranch_execz .LBB0_1656
	s_waitcnt lgkmcnt(0)
	v_cvt_pk_bf16_f32 v16, v16, v17
	global_store_dword v[14:15], v16, off offset:3264
.LBB0_1656:
	s_or_b64 exec, exec, s[0:1]
	v_rcp_f32_e32 v10, v10
	s_nop 0
	v_mul_f32_e32 v16, v68, v10
	s_waitcnt lgkmcnt(0)
	s_nop 1
	v_mov_b32_dpp v17, v16 quad_perm:[1,0,3,2] row_mask:0xf bank_mask:0xf
	s_and_saveexec_b64 s[0:1], s[4:5]
	s_cbranch_execz .LBB0_1658
	s_waitcnt lgkmcnt(0)
	v_cvt_pk_bf16_f32 v18, v16, v17
	v_add_co_u32_e32 v16, vcc, 0x2000, v14
	s_nop 1
	v_addc_co_u32_e32 v17, vcc, 0, v15, vcc
	global_store_dword v[16:17], v18, off
; #define GAS __attribute__((address_space(1)))
; __device__ __forceinline__ unsigned cvtpk(float lo, float hi) { unsigned r; asm volatile("v_cvt_pk_bf16_f32 %0, %1, %2" : "=v"(r) : "v"(lo), "v"(hi)); return r; }
; __device__ __forceinline__ int crow(int r, int hi) { return (r & 3) + 8 * (r >> 2) + 4 * hi; }
; template <int DK, int MODE> ...
;     ...
;     for (int r = 0; r < 16; ++r) { const float rl = __builtin_amdgcn_rcpf(ws[32 + crow(r, hi)]);
; #pragma unroll
;         for (int d = 0; d < 4; ++d) o[d][r] *= rl; }
; __device__ __forceinline__ void store_o(const f32x16 (&o)[4], bf16_t* Ow, int pitch, int r32, int hi) {
; #pragma unroll
;     for (int r = 0; r < 16; ++r) { const int orow = crow(r, hi);
; #pragma unroll
;         for (int d0 = 0; d0 < 4; ++d0) { const float v = o[d0][r]; const float vn = __shfl_xor(v, 1);
;             if ((r32 & 1) == 0) *(GAS unsigned*)(Ow + (size_t)orow * pitch + d0 * 32 + r32) = cvtpk(v, vn); } }
.LBB0_1658:
	s_or_b64 exec, exec, s[0:1]
	v_mul_f32_e32 v16, v52, v10
	s_waitcnt lgkmcnt(0)
	s_nop 1
	v_mov_b32_dpp v17, v16 quad_perm:[1,0,3,2] row_mask:0xf bank_mask:0xf
	s_and_saveexec_b64 s[0:1], s[4:5]
	s_cbranch_execz .LBB0_1660
	s_waitcnt lgkmcnt(0)
	v_cvt_pk_bf16_f32 v18, v16, v17
	v_add_co_u32_e32 v16, vcc, 0x2000, v14
	s_nop 1
	v_addc_co_u32_e32 v17, vcc, 0, v15, vcc
	global_store_dword v[16:17], v18, off offset:64
.LBB0_1660:
	s_or_b64 exec, exec, s[0:1]
	v_mul_f32_e32 v16, v36, v10
	s_waitcnt lgkmcnt(0)
	s_nop 1
	v_mov_b32_dpp v17, v16 quad_perm:[1,0,3,2] row_mask:0xf bank_mask:0xf
	s_and_saveexec_b64 s[0:1], s[4:5]
	s_cbranch_execz .LBB0_1662
	s_waitcnt lgkmcnt(0)
	v_cvt_pk_bf16_f32 v18, v16, v17
	v_add_co_u32_e32 v16, vcc, 0x2000, v14
	s_nop 1
	v_addc_co_u32_e32 v17, vcc, 0, v15, vcc
	global_store_dword v[16:17], v18, off offset:128
.LBB0_1662:
	s_or_b64 exec, exec, s[0:1]
	v_mul_f32_e32 v10, v20, v10
	s_nop 1
	v_mov_b32_dpp v16, v10 quad_perm:[1,0,3,2] row_mask:0xf bank_mask:0xf
	s_and_saveexec_b64 s[0:1], s[4:5]
	s_cbranch_execz .LBB0_1664
	s_waitcnt lgkmcnt(0)
	v_cvt_pk_bf16_f32 v10, v10, v16
	v_add_co_u32_e32 v16, vcc, 0x2000, v14
	s_nop 1
	v_addc_co_u32_e32 v17, vcc, 0, v15, vcc
	global_store_dword v[16:17], v10, off offset:192
.LBB0_1664:
	s_or_b64 exec, exec, s[0:1]
	v_rcp_f32_e32 v10, v11
	s_nop 0
	v_mul_f32_e32 v11, v69, v10
	s_waitcnt lgkmcnt(0)
	s_nop 1
	v_mov_b32_dpp v16, v11 quad_perm:[1,0,3,2] row_mask:0xf bank_mask:0xf
	s_and_saveexec_b64 s[0:1], s[4:5]
	s_cbranch_execz .LBB0_1666
	s_waitcnt lgkmcnt(0)
	v_cvt_pk_bf16_f32 v11, v11, v16
	v_add_co_u32_e32 v16, vcc, 0x2000, v14
	s_nop 1
	v_addc_co_u32_e32 v17, vcc, 0, v15, vcc
	global_store_dword v[16:17], v11, off offset:1024
.LBB0_1666:
	s_or_b64 exec, exec, s[0:1]
	v_mul_f32_e32 v11, v53, v10
	s_waitcnt lgkmcnt(0)
	s_nop 1
	v_mov_b32_dpp v16, v11 quad_perm:[1,0,3,2] row_mask:0xf bank_mask:0xf
	s_and_saveexec_b64 s[0:1], s[4:5]
	s_cbranch_execz .LBB0_1668
	s_waitcnt lgkmcnt(0)
	v_cvt_pk_bf16_f32 v11, v11, v16
	v_add_co_u32_e32 v16, vcc, 0x2000, v14
	s_nop 1
	v_addc_co_u32_e32 v17, vcc, 0, v15, vcc
	global_store_dword v[16:17], v11, off offset:1088
.LBB0_1668:
	s_or_b64 exec, exec, s[0:1]
	v_mul_f32_e32 v11, v37, v10
	s_waitcnt lgkmcnt(0)
	s_nop 1
	v_mov_b32_dpp v16, v11 quad_perm:[1,0,3,2] row_mask:0xf bank_mask:0xf
	s_and_saveexec_b64 s[0:1], s[4:5]
	s_cbranch_execz .LBB0_1670
	s_waitcnt lgkmcnt(0)
	v_cvt_pk_bf16_f32 v11, v11, v16
	v_add_co_u32_e32 v16, vcc, 0x2000, v14
	s_nop 1
	v_addc_co_u32_e32 v17, vcc, 0, v15, vcc
	global_store_dword v[16:17], v11, off offset:1152
.LBB0_1670:
	s_or_b64 exec, exec, s[0:1]
	v_mul_f32_e32 v10, v21, v10
	s_nop 1
	v_mov_b32_dpp v11, v10 quad_perm:[1,0,3,2] row_mask:0xf bank_mask:0xf
	s_and_saveexec_b64 s[0:1], s[4:5]
	s_cbranch_execz .LBB0_1672
	s_waitcnt lgkmcnt(0)
	v_cvt_pk_bf16_f32 v16, v10, v11
	v_add_co_u32_e32 v10, vcc, 0x2000, v14
	s_nop 1
	v_addc_co_u32_e32 v11, vcc, 0, v15, vcc
	global_store_dword v[10:11], v16, off offset:1216
.LBB0_1672:
	s_or_b64 exec, exec, s[0:1]
	v_rcp_f32_e32 v10, v12
	s_waitcnt lgkmcnt(0)
	v_mul_f32_e32 v11, v70, v10
	s_nop 1
	v_mov_b32_dpp v12, v11 quad_perm:[1,0,3,2] row_mask:0xf bank_mask:0xf
	s_and_saveexec_b64 s[0:1], s[4:5]
	s_cbranch_execz .LBB0_1674
	v_add_co_u32_e32 v16, vcc, 0x2000, v14
	s_waitcnt lgkmcnt(0)
	v_cvt_pk_bf16_f32 v11, v11, v12
	s_nop 0
	v_addc_co_u32_e32 v17, vcc, 0, v15, vcc
	global_store_dword v[16:17], v11, off offset:2048
.LBB0_1674:
	s_or_b64 exec, exec, s[0:1]
	v_mul_f32_e32 v11, v54, v10
	s_waitcnt lgkmcnt(0)
	s_nop 1
	v_mov_b32_dpp v12, v11 quad_perm:[1,0,3,2] row_mask:0xf bank_mask:0xf
	s_and_saveexec_b64 s[0:1], s[4:5]
	s_cbranch_execz .LBB0_1676
	v_add_co_u32_e32 v16, vcc, 0x2000, v14
	s_waitcnt lgkmcnt(0)
	v_cvt_pk_bf16_f32 v11, v11, v12
	s_nop 0
	v_addc_co_u32_e32 v17, vcc, 0, v15, vcc
	global_store_dword v[16:17], v11, off offset:2112
.LBB0_1676:
	s_or_b64 exec, exec, s[0:1]
	v_mul_f32_e32 v11, v38, v10
	s_waitcnt lgkmcnt(0)
	s_nop 1
	v_mov_b32_dpp v12, v11 quad_perm:[1,0,3,2] row_mask:0xf bank_mask:0xf
	s_and_saveexec_b64 s[0:1], s[4:5]
	s_cbranch_execz .LBB0_1678
	v_add_co_u32_e32 v16, vcc, 0x2000, v14
	s_waitcnt lgkmcnt(0)
	v_cvt_pk_bf16_f32 v11, v11, v12
	s_nop 0
	v_addc_co_u32_e32 v17, vcc, 0, v15, vcc
	global_store_dword v[16:17], v11, off offset:2176
.LBB0_1678:
	s_or_b64 exec, exec, s[0:1]
	v_mul_f32_e32 v10, v22, v10
	s_nop 1
	v_mov_b32_dpp v11, v10 quad_perm:[1,0,3,2] row_mask:0xf bank_mask:0xf
	s_and_saveexec_b64 s[0:1], s[4:5]
	s_cbranch_execz .LBB0_1680
	s_waitcnt lgkmcnt(0)
	v_cvt_pk_bf16_f32 v12, v10, v11
	v_add_co_u32_e32 v10, vcc, 0x2000, v14
	s_nop 1
	v_addc_co_u32_e32 v11, vcc, 0, v15, vcc
	global_store_dword v[10:11], v12, off offset:2240
.LBB0_1680:
	s_or_b64 exec, exec, s[0:1]
	v_rcp_f32_e32 v10, v13
	s_waitcnt lgkmcnt(0)
	v_mul_f32_e32 v11, v71, v10
	s_nop 1
	v_mov_b32_dpp v12, v11 quad_perm:[1,0,3,2] row_mask:0xf bank_mask:0xf
	s_and_saveexec_b64 s[0:1], s[4:5]
	s_cbranch_execz .LBB0_1682
	s_waitcnt lgkmcnt(0)
	v_cvt_pk_bf16_f32 v11, v11, v12
	v_add_co_u32_e32 v12, vcc, 0x2000, v14
	s_nop 1
	v_addc_co_u32_e32 v13, vcc, 0, v15, vcc
	global_store_dword v[12:13], v11, off offset:3072
.LBB0_1682:
	s_or_b64 exec, exec, s[0:1]
	v_mul_f32_e32 v11, v55, v10
	s_waitcnt lgkmcnt(0)
	s_nop 1
	v_mov_b32_dpp v12, v11 quad_perm:[1,0,3,2] row_mask:0xf bank_mask:0xf
	s_and_saveexec_b64 s[0:1], s[4:5]
	s_cbranch_execz .LBB0_1684
	s_waitcnt lgkmcnt(0)
	v_cvt_pk_bf16_f32 v11, v11, v12
	v_add_co_u32_e32 v12, vcc, 0x2000, v14
	s_nop 1
	v_addc_co_u32_e32 v13, vcc, 0, v15, vcc
	global_store_dword v[12:13], v11, off offset:3136
; #define GAS __attribute__((address_space(1)))
; __device__ __forceinline__ unsigned cvtpk(float lo, float hi) { unsigned r; asm volatile("v_cvt_pk_bf16_f32 %0, %1, %2" : "=v"(r) : "v"(lo), "v"(hi)); return r; }
; __device__ __forceinline__ int crow(int r, int hi) { return (r & 3) + 8 * (r >> 2) + 4 * hi; }
; template <int DK, int MODE> ...
;     ...
;     for (int r = 0; r < 16; ++r) { const float rl = __builtin_amdgcn_rcpf(ws[32 + crow(r, hi)]);
; #pragma unroll
;         for (int d = 0; d < 4; ++d) o[d][r] *= rl; }
; __device__ __forceinline__ void store_o(const f32x16 (&o)[4], bf16_t* Ow, int pitch, int r32, int hi) {
; #pragma unroll
;     for (int r = 0; r < 16; ++r) { const int orow = crow(r, hi);
; #pragma unroll
;         for (int d0 = 0; d0 < 4; ++d0) { const float v = o[d0][r]; const float vn = __shfl_xor(v, 1);
;             if ((r32 & 1) == 0) *(GAS unsigned*)(Ow + (size_t)orow * pitch + d0 * 32 + r32) = cvtpk(v, vn); } }
.LBB0_1684:
	s_or_b64 exec, exec, s[0:1]
	v_mul_f32_e32 v11, v39, v10
	s_waitcnt lgkmcnt(0)
	s_nop 1
	v_mov_b32_dpp v12, v11 quad_perm:[1,0,3,2] row_mask:0xf bank_mask:0xf
	s_and_saveexec_b64 s[0:1], s[4:5]
	s_cbranch_execz .LBB0_1686
	s_waitcnt lgkmcnt(0)
	v_cvt_pk_bf16_f32 v11, v11, v12
	v_add_co_u32_e32 v12, vcc, 0x2000, v14
	s_nop 1
	v_addc_co_u32_e32 v13, vcc, 0, v15, vcc
	global_store_dword v[12:13], v11, off offset:3200
.LBB0_1686:
	s_or_b64 exec, exec, s[0:1]
	v_mul_f32_e32 v10, v23, v10
	s_nop 1
	v_mov_b32_dpp v11, v10 quad_perm:[1,0,3,2] row_mask:0xf bank_mask:0xf
	s_and_saveexec_b64 s[0:1], s[4:5]
	s_cbranch_execz .LBB0_1688
	s_waitcnt lgkmcnt(0)
	v_cvt_pk_bf16_f32 v12, v10, v11
	v_add_co_u32_e32 v10, vcc, 0x2000, v14
	s_nop 1
	v_addc_co_u32_e32 v11, vcc, 0, v15, vcc
	global_store_dword v[10:11], v12, off offset:3264
.LBB0_1688:
	s_or_b64 exec, exec, s[0:1]
	v_rcp_f32_e32 v6, v6
	s_nop 0
	v_mul_f32_e32 v10, v72, v6
	s_waitcnt lgkmcnt(0)
	s_nop 1
	v_mov_b32_dpp v11, v10 quad_perm:[1,0,3,2] row_mask:0xf bank_mask:0xf
	s_and_saveexec_b64 s[0:1], s[4:5]
	s_cbranch_execz .LBB0_1690
	s_waitcnt lgkmcnt(0)
	v_cvt_pk_bf16_f32 v12, v10, v11
	v_add_co_u32_e32 v10, vcc, 0x4000, v14
	s_nop 1
	v_addc_co_u32_e32 v11, vcc, 0, v15, vcc
	global_store_dword v[10:11], v12, off
.LBB0_1690:
	s_or_b64 exec, exec, s[0:1]
	v_mul_f32_e32 v10, v56, v6
	s_waitcnt lgkmcnt(0)
	s_nop 1
	v_mov_b32_dpp v11, v10 quad_perm:[1,0,3,2] row_mask:0xf bank_mask:0xf
	s_and_saveexec_b64 s[0:1], s[4:5]
	s_cbranch_execz .LBB0_1692
	s_waitcnt lgkmcnt(0)
	v_cvt_pk_bf16_f32 v12, v10, v11
	v_add_co_u32_e32 v10, vcc, 0x4000, v14
	s_nop 1
	v_addc_co_u32_e32 v11, vcc, 0, v15, vcc
	global_store_dword v[10:11], v12, off offset:64
.LBB0_1692:
	s_or_b64 exec, exec, s[0:1]
	v_mul_f32_e32 v10, v40, v6
	s_waitcnt lgkmcnt(0)
	s_nop 1
	v_mov_b32_dpp v11, v10 quad_perm:[1,0,3,2] row_mask:0xf bank_mask:0xf
	s_and_saveexec_b64 s[0:1], s[4:5]
	s_cbranch_execz .LBB0_1694
	s_waitcnt lgkmcnt(0)
	v_cvt_pk_bf16_f32 v12, v10, v11
	v_add_co_u32_e32 v10, vcc, 0x4000, v14
	s_nop 1
	v_addc_co_u32_e32 v11, vcc, 0, v15, vcc
	global_store_dword v[10:11], v12, off offset:128
.LBB0_1694:
	s_or_b64 exec, exec, s[0:1]
	v_mul_f32_e32 v6, v24, v6
	s_nop 1
	v_mov_b32_dpp v10, v6 quad_perm:[1,0,3,2] row_mask:0xf bank_mask:0xf
	s_and_saveexec_b64 s[0:1], s[4:5]
	s_cbranch_execz .LBB0_1696
	s_waitcnt lgkmcnt(0)
	v_cvt_pk_bf16_f32 v6, v6, v10
	v_add_co_u32_e32 v10, vcc, 0x4000, v14
	s_nop 1
	v_addc_co_u32_e32 v11, vcc, 0, v15, vcc
	global_store_dword v[10:11], v6, off offset:192
.LBB0_1696:
	s_or_b64 exec, exec, s[0:1]
	v_rcp_f32_e32 v6, v7
	s_nop 0
	v_mul_f32_e32 v7, v73, v6
	s_waitcnt lgkmcnt(0)
	s_nop 1
	v_mov_b32_dpp v10, v7 quad_perm:[1,0,3,2] row_mask:0xf bank_mask:0xf
	s_and_saveexec_b64 s[0:1], s[4:5]
	s_cbranch_execz .LBB0_1698
	s_waitcnt lgkmcnt(0)
	v_cvt_pk_bf16_f32 v7, v7, v10
	v_add_co_u32_e32 v10, vcc, 0x4000, v14
	s_nop 1
	v_addc_co_u32_e32 v11, vcc, 0, v15, vcc
	global_store_dword v[10:11], v7, off offset:1024
.LBB0_1698:
	s_or_b64 exec, exec, s[0:1]
	v_mul_f32_e32 v7, v57, v6
	s_waitcnt lgkmcnt(0)
	s_nop 1
	v_mov_b32_dpp v10, v7 quad_perm:[1,0,3,2] row_mask:0xf bank_mask:0xf
	s_and_saveexec_b64 s[0:1], s[4:5]
	s_cbranch_execz .LBB0_1700
	s_waitcnt lgkmcnt(0)
	v_cvt_pk_bf16_f32 v7, v7, v10
	v_add_co_u32_e32 v10, vcc, 0x4000, v14
	s_nop 1
	v_addc_co_u32_e32 v11, vcc, 0, v15, vcc
	global_store_dword v[10:11], v7, off offset:1088
.LBB0_1700:
	s_or_b64 exec, exec, s[0:1]
	v_mul_f32_e32 v7, v41, v6
	s_waitcnt lgkmcnt(0)
	s_nop 1
	v_mov_b32_dpp v10, v7 quad_perm:[1,0,3,2] row_mask:0xf bank_mask:0xf
	s_and_saveexec_b64 s[0:1], s[4:5]
	s_cbranch_execz .LBB0_1702
	s_waitcnt lgkmcnt(0)
	v_cvt_pk_bf16_f32 v7, v7, v10
	v_add_co_u32_e32 v10, vcc, 0x4000, v14
	s_nop 1
	v_addc_co_u32_e32 v11, vcc, 0, v15, vcc
	global_store_dword v[10:11], v7, off offset:1152
.LBB0_1702:
	s_or_b64 exec, exec, s[0:1]
	v_mul_f32_e32 v6, v25, v6
	s_nop 1
	v_mov_b32_dpp v7, v6 quad_perm:[1,0,3,2] row_mask:0xf bank_mask:0xf
	s_and_saveexec_b64 s[0:1], s[4:5]
	s_cbranch_execz .LBB0_1704
	s_waitcnt lgkmcnt(0)
	v_cvt_pk_bf16_f32 v10, v6, v7
	v_add_co_u32_e32 v6, vcc, 0x4000, v14
	s_nop 1
	v_addc_co_u32_e32 v7, vcc, 0, v15, vcc
	global_store_dword v[6:7], v10, off offset:1216
.LBB0_1704:
	s_or_b64 exec, exec, s[0:1]
	v_rcp_f32_e32 v6, v8
	s_waitcnt lgkmcnt(0)
	v_mul_f32_e32 v7, v74, v6
	s_nop 1
	v_mov_b32_dpp v8, v7 quad_perm:[1,0,3,2] row_mask:0xf bank_mask:0xf
	s_and_saveexec_b64 s[0:1], s[4:5]
	s_cbranch_execz .LBB0_1706
	v_add_co_u32_e32 v10, vcc, 0x4000, v14
	s_waitcnt lgkmcnt(0)
	v_cvt_pk_bf16_f32 v7, v7, v8
	s_nop 0
	v_addc_co_u32_e32 v11, vcc, 0, v15, vcc
	global_store_dword v[10:11], v7, off offset:2048
.LBB0_1706:
	s_or_b64 exec, exec, s[0:1]
	v_mul_f32_e32 v7, v58, v6
	s_waitcnt lgkmcnt(0)
	s_nop 1
	v_mov_b32_dpp v8, v7 quad_perm:[1,0,3,2] row_mask:0xf bank_mask:0xf
	s_and_saveexec_b64 s[0:1], s[4:5]
	s_cbranch_execz .LBB0_1708
	v_add_co_u32_e32 v10, vcc, 0x4000, v14
	s_waitcnt lgkmcnt(0)
	v_cvt_pk_bf16_f32 v7, v7, v8
	s_nop 0
	v_addc_co_u32_e32 v11, vcc, 0, v15, vcc
	global_store_dword v[10:11], v7, off offset:2112
.LBB0_1708:
	s_or_b64 exec, exec, s[0:1]
	v_mul_f32_e32 v7, v42, v6
	s_waitcnt lgkmcnt(0)
	s_nop 1
	v_mov_b32_dpp v8, v7 quad_perm:[1,0,3,2] row_mask:0xf bank_mask:0xf
	s_and_saveexec_b64 s[0:1], s[4:5]
	s_cbranch_execz .LBB0_1710
	v_add_co_u32_e32 v10, vcc, 0x4000, v14
	s_waitcnt lgkmcnt(0)
	v_cvt_pk_bf16_f32 v7, v7, v8
	s_nop 0
	v_addc_co_u32_e32 v11, vcc, 0, v15, vcc
	global_store_dword v[10:11], v7, off offset:2176
; #define GAS __attribute__((address_space(1)))
; __device__ __forceinline__ unsigned cvtpk(float lo, float hi) { unsigned r; asm volatile("v_cvt_pk_bf16_f32 %0, %1, %2" : "=v"(r) : "v"(lo), "v"(hi)); return r; }
; __device__ __forceinline__ int crow(int r, int hi) { return (r & 3) + 8 * (r >> 2) + 4 * hi; }
; template <int DK, int MODE> ...
;     ...
;     for (int r = 0; r < 16; ++r) { const float rl = __builtin_amdgcn_rcpf(ws[32 + crow(r, hi)]);
; #pragma unroll
;         for (int d = 0; d < 4; ++d) o[d][r] *= rl; }
; __device__ __forceinline__ void store_o(const f32x16 (&o)[4], bf16_t* Ow, int pitch, int r32, int hi) {
; #pragma unroll
;     for (int r = 0; r < 16; ++r) { const int orow = crow(r, hi);
; #pragma unroll
;         for (int d0 = 0; d0 < 4; ++d0) { const float v = o[d0][r]; const float vn = __shfl_xor(v, 1);
;             if ((r32 & 1) == 0) *(GAS unsigned*)(Ow + (size_t)orow * pitch + d0 * 32 + r32) = cvtpk(v, vn); } }
.LBB0_1710:
	s_or_b64 exec, exec, s[0:1]
	v_mul_f32_e32 v6, v26, v6
	s_nop 1
	v_mov_b32_dpp v7, v6 quad_perm:[1,0,3,2] row_mask:0xf bank_mask:0xf
	s_and_saveexec_b64 s[0:1], s[4:5]
	s_cbranch_execz .LBB0_1712
	s_waitcnt lgkmcnt(0)
	v_cvt_pk_bf16_f32 v8, v6, v7
	v_add_co_u32_e32 v6, vcc, 0x4000, v14
	s_nop 1
	v_addc_co_u32_e32 v7, vcc, 0, v15, vcc
	global_store_dword v[6:7], v8, off offset:2240
.LBB0_1712:
	s_or_b64 exec, exec, s[0:1]
	v_rcp_f32_e32 v6, v9
	s_waitcnt lgkmcnt(0)
	v_mul_f32_e32 v7, v75, v6
	s_nop 1
	v_mov_b32_dpp v8, v7 quad_perm:[1,0,3,2] row_mask:0xf bank_mask:0xf
	s_and_saveexec_b64 s[0:1], s[4:5]
	s_cbranch_execz .LBB0_1714
	s_waitcnt lgkmcnt(0)
	v_cvt_pk_bf16_f32 v7, v7, v8
	v_add_co_u32_e32 v8, vcc, 0x4000, v14
	s_nop 1
	v_addc_co_u32_e32 v9, vcc, 0, v15, vcc
	global_store_dword v[8:9], v7, off offset:3072
.LBB0_1714:
	s_or_b64 exec, exec, s[0:1]
	v_mul_f32_e32 v7, v59, v6
	s_waitcnt lgkmcnt(0)
	s_nop 1
	v_mov_b32_dpp v8, v7 quad_perm:[1,0,3,2] row_mask:0xf bank_mask:0xf
	s_and_saveexec_b64 s[0:1], s[4:5]
	s_cbranch_execz .LBB0_1716
	s_waitcnt lgkmcnt(0)
	v_cvt_pk_bf16_f32 v7, v7, v8
	v_add_co_u32_e32 v8, vcc, 0x4000, v14
	s_nop 1
	v_addc_co_u32_e32 v9, vcc, 0, v15, vcc
	global_store_dword v[8:9], v7, off offset:3136
.LBB0_1716:
	s_or_b64 exec, exec, s[0:1]
	v_mul_f32_e32 v7, v43, v6
	s_waitcnt lgkmcnt(0)
	s_nop 1
	v_mov_b32_dpp v8, v7 quad_perm:[1,0,3,2] row_mask:0xf bank_mask:0xf
	s_and_saveexec_b64 s[0:1], s[4:5]
	s_cbranch_execz .LBB0_1718
	s_waitcnt lgkmcnt(0)
	v_cvt_pk_bf16_f32 v7, v7, v8
	v_add_co_u32_e32 v8, vcc, 0x4000, v14
	s_nop 1
	v_addc_co_u32_e32 v9, vcc, 0, v15, vcc
	global_store_dword v[8:9], v7, off offset:3200
.LBB0_1718:
	s_or_b64 exec, exec, s[0:1]
	v_mul_f32_e32 v6, v27, v6
	s_nop 1
	v_mov_b32_dpp v7, v6 quad_perm:[1,0,3,2] row_mask:0xf bank_mask:0xf
	s_and_saveexec_b64 s[0:1], s[4:5]
	s_cbranch_execz .LBB0_1720
	s_waitcnt lgkmcnt(0)
	v_cvt_pk_bf16_f32 v8, v6, v7
	v_add_co_u32_e32 v6, vcc, 0x4000, v14
	s_nop 1
	v_addc_co_u32_e32 v7, vcc, 0, v15, vcc
	global_store_dword v[6:7], v8, off offset:3264
.LBB0_1720:
	s_or_b64 exec, exec, s[0:1]
	v_rcp_f32_e32 v2, v2
	s_nop 0
	v_mul_f32_e32 v6, v76, v2
	s_waitcnt lgkmcnt(0)
	s_nop 1
	v_mov_b32_dpp v7, v6 quad_perm:[1,0,3,2] row_mask:0xf bank_mask:0xf
	s_and_saveexec_b64 s[0:1], s[4:5]
	s_cbranch_execz .LBB0_1722
	s_waitcnt lgkmcnt(0)
	v_cvt_pk_bf16_f32 v8, v6, v7
	v_add_co_u32_e32 v6, vcc, 0x6000, v14
	s_nop 1
	v_addc_co_u32_e32 v7, vcc, 0, v15, vcc
	global_store_dword v[6:7], v8, off
.LBB0_1722:
	s_or_b64 exec, exec, s[0:1]
	v_mul_f32_e32 v6, v60, v2
	s_waitcnt lgkmcnt(0)
	s_nop 1
	v_mov_b32_dpp v7, v6 quad_perm:[1,0,3,2] row_mask:0xf bank_mask:0xf
	s_and_saveexec_b64 s[0:1], s[4:5]
	s_cbranch_execz .LBB0_1724
	s_waitcnt lgkmcnt(0)
	v_cvt_pk_bf16_f32 v8, v6, v7
	v_add_co_u32_e32 v6, vcc, 0x6000, v14
	s_nop 1
	v_addc_co_u32_e32 v7, vcc, 0, v15, vcc
	global_store_dword v[6:7], v8, off offset:64
.LBB0_1724:
	s_or_b64 exec, exec, s[0:1]
	v_mul_f32_e32 v6, v44, v2
	s_waitcnt lgkmcnt(0)
	s_nop 1
	v_mov_b32_dpp v7, v6 quad_perm:[1,0,3,2] row_mask:0xf bank_mask:0xf
	s_and_saveexec_b64 s[0:1], s[4:5]
	s_cbranch_execz .LBB0_1726
	s_waitcnt lgkmcnt(0)
	v_cvt_pk_bf16_f32 v8, v6, v7
	v_add_co_u32_e32 v6, vcc, 0x6000, v14
	s_nop 1
	v_addc_co_u32_e32 v7, vcc, 0, v15, vcc
	global_store_dword v[6:7], v8, off offset:128
.LBB0_1726:
	s_or_b64 exec, exec, s[0:1]
	v_mul_f32_e32 v2, v28, v2
	s_nop 1
	v_mov_b32_dpp v6, v2 quad_perm:[1,0,3,2] row_mask:0xf bank_mask:0xf
	s_and_saveexec_b64 s[0:1], s[4:5]
	s_cbranch_execz .LBB0_1728
	s_waitcnt lgkmcnt(0)
	v_cvt_pk_bf16_f32 v2, v2, v6
	v_add_co_u32_e32 v6, vcc, 0x6000, v14
	s_nop 1
	v_addc_co_u32_e32 v7, vcc, 0, v15, vcc
	global_store_dword v[6:7], v2, off offset:192
.LBB0_1728:
	s_or_b64 exec, exec, s[0:1]
	v_rcp_f32_e32 v2, v3
	s_nop 0
	v_mul_f32_e32 v3, v77, v2
	s_waitcnt lgkmcnt(0)
	s_nop 1
	v_mov_b32_dpp v6, v3 quad_perm:[1,0,3,2] row_mask:0xf bank_mask:0xf
	s_and_saveexec_b64 s[0:1], s[4:5]
	s_cbranch_execz .LBB0_1730
	s_waitcnt lgkmcnt(0)
	v_cvt_pk_bf16_f32 v3, v3, v6
	v_add_co_u32_e32 v6, vcc, 0x6000, v14
	s_nop 1
	v_addc_co_u32_e32 v7, vcc, 0, v15, vcc
	global_store_dword v[6:7], v3, off offset:1024
; #define GAS __attribute__((address_space(1)))
; __device__ __forceinline__ unsigned cvtpk(float lo, float hi) { unsigned r; asm volatile("v_cvt_pk_bf16_f32 %0, %1, %2" : "=v"(r) : "v"(lo), "v"(hi)); return r; }
; __device__ __forceinline__ int crow(int r, int hi) { return (r & 3) + 8 * (r >> 2) + 4 * hi; }
; template <int DK, int MODE> ...
;     ...
;     for (int r = 0; r < 16; ++r) { const float rl = __builtin_amdgcn_rcpf(ws[32 + crow(r, hi)]);
; #pragma unroll
;         for (int d = 0; d < 4; ++d) o[d][r] *= rl; }
; __device__ __forceinline__ void store_o(const f32x16 (&o)[4], bf16_t* Ow, int pitch, int r32, int hi) {
; #pragma unroll
;     for (int r = 0; r < 16; ++r) { const int orow = crow(r, hi);
; #pragma unroll
;         for (int d0 = 0; d0 < 4; ++d0) { const float v = o[d0][r]; const float vn = __shfl_xor(v, 1);
;             if ((r32 & 1) == 0) *(GAS unsigned*)(Ow + (size_t)orow * pitch + d0 * 32 + r32) = cvtpk(v, vn); } }
.LBB0_1730:
	s_or_b64 exec, exec, s[0:1]
	v_mul_f32_e32 v3, v61, v2
	s_waitcnt lgkmcnt(0)
	s_nop 1
	v_mov_b32_dpp v6, v3 quad_perm:[1,0,3,2] row_mask:0xf bank_mask:0xf
	s_and_saveexec_b64 s[0:1], s[4:5]
	s_cbranch_execz .LBB0_1732
	s_waitcnt lgkmcnt(0)
	v_cvt_pk_bf16_f32 v3, v3, v6
	v_add_co_u32_e32 v6, vcc, 0x6000, v14
	s_nop 1
	v_addc_co_u32_e32 v7, vcc, 0, v15, vcc
	global_store_dword v[6:7], v3, off offset:1088
.LBB0_1732:
	s_or_b64 exec, exec, s[0:1]
	v_mul_f32_e32 v3, v45, v2
	s_waitcnt lgkmcnt(0)
	s_nop 1
	v_mov_b32_dpp v6, v3 quad_perm:[1,0,3,2] row_mask:0xf bank_mask:0xf
	s_and_saveexec_b64 s[0:1], s[4:5]
	s_cbranch_execz .LBB0_1734
	s_waitcnt lgkmcnt(0)
	v_cvt_pk_bf16_f32 v3, v3, v6
	v_add_co_u32_e32 v6, vcc, 0x6000, v14
	s_nop 1
	v_addc_co_u32_e32 v7, vcc, 0, v15, vcc
	global_store_dword v[6:7], v3, off offset:1152
.LBB0_1734:
	s_or_b64 exec, exec, s[0:1]
	v_mul_f32_e32 v2, v29, v2
	s_nop 1
	v_mov_b32_dpp v3, v2 quad_perm:[1,0,3,2] row_mask:0xf bank_mask:0xf
	s_and_saveexec_b64 s[0:1], s[4:5]
	s_cbranch_execz .LBB0_1736
	s_waitcnt lgkmcnt(0)
	v_cvt_pk_bf16_f32 v6, v2, v3
	v_add_co_u32_e32 v2, vcc, 0x6000, v14
	s_nop 1
	v_addc_co_u32_e32 v3, vcc, 0, v15, vcc
	global_store_dword v[2:3], v6, off offset:1216
.LBB0_1736:
	s_or_b64 exec, exec, s[0:1]
	v_rcp_f32_e32 v2, v4
	s_waitcnt lgkmcnt(0)
	v_mul_f32_e32 v3, v78, v2
	s_nop 1
	v_mov_b32_dpp v4, v3 quad_perm:[1,0,3,2] row_mask:0xf bank_mask:0xf
	s_and_saveexec_b64 s[0:1], s[4:5]
	s_cbranch_execz .LBB0_1738
	v_add_co_u32_e32 v6, vcc, 0x6000, v14
	s_waitcnt lgkmcnt(0)
	v_cvt_pk_bf16_f32 v3, v3, v4
	s_nop 0
	v_addc_co_u32_e32 v7, vcc, 0, v15, vcc
	global_store_dword v[6:7], v3, off offset:2048
.LBB0_1738:
	s_or_b64 exec, exec, s[0:1]
	v_mul_f32_e32 v3, v62, v2
	s_waitcnt lgkmcnt(0)
	s_nop 1
	v_mov_b32_dpp v4, v3 quad_perm:[1,0,3,2] row_mask:0xf bank_mask:0xf
	s_and_saveexec_b64 s[0:1], s[4:5]
	s_cbranch_execz .LBB0_1740
	v_add_co_u32_e32 v6, vcc, 0x6000, v14
	s_waitcnt lgkmcnt(0)
	v_cvt_pk_bf16_f32 v3, v3, v4
	s_nop 0
	v_addc_co_u32_e32 v7, vcc, 0, v15, vcc
	global_store_dword v[6:7], v3, off offset:2112
.LBB0_1740:
	s_or_b64 exec, exec, s[0:1]
	v_mul_f32_e32 v3, v46, v2
	s_waitcnt lgkmcnt(0)
	s_nop 1
	v_mov_b32_dpp v4, v3 quad_perm:[1,0,3,2] row_mask:0xf bank_mask:0xf
	s_and_saveexec_b64 s[0:1], s[4:5]
	s_cbranch_execz .LBB0_1742
	v_add_co_u32_e32 v6, vcc, 0x6000, v14
	s_waitcnt lgkmcnt(0)
	v_cvt_pk_bf16_f32 v3, v3, v4
	s_nop 0
	v_addc_co_u32_e32 v7, vcc, 0, v15, vcc
	global_store_dword v[6:7], v3, off offset:2176
.LBB0_1742:
	s_or_b64 exec, exec, s[0:1]
	v_mul_f32_e32 v2, v30, v2
	s_nop 1
	v_mov_b32_dpp v3, v2 quad_perm:[1,0,3,2] row_mask:0xf bank_mask:0xf
	s_and_saveexec_b64 s[0:1], s[4:5]
	s_cbranch_execz .LBB0_1744
	s_waitcnt lgkmcnt(0)
	v_cvt_pk_bf16_f32 v4, v2, v3
	v_add_co_u32_e32 v2, vcc, 0x6000, v14
	s_nop 1
	v_addc_co_u32_e32 v3, vcc, 0, v15, vcc
	global_store_dword v[2:3], v4, off offset:2240
.LBB0_1744:
	s_or_b64 exec, exec, s[0:1]
	v_rcp_f32_e32 v2, v5
	s_waitcnt lgkmcnt(0)
	v_mul_f32_e32 v3, v79, v2
	s_nop 1
	v_mov_b32_dpp v4, v3 quad_perm:[1,0,3,2] row_mask:0xf bank_mask:0xf
	s_and_saveexec_b64 s[0:1], s[4:5]
	s_cbranch_execz .LBB0_1746
	s_waitcnt lgkmcnt(0)
	v_cvt_pk_bf16_f32 v3, v3, v4
	v_add_co_u32_e32 v4, vcc, 0x6000, v14
	s_nop 1
	v_addc_co_u32_e32 v5, vcc, 0, v15, vcc
	global_store_dword v[4:5], v3, off offset:3072
.LBB0_1746:
	s_or_b64 exec, exec, s[0:1]
	v_mul_f32_e32 v3, v63, v2
	s_waitcnt lgkmcnt(0)
	s_nop 1
	v_mov_b32_dpp v4, v3 quad_perm:[1,0,3,2] row_mask:0xf bank_mask:0xf
	s_and_saveexec_b64 s[0:1], s[4:5]
	s_cbranch_execz .LBB0_1748
	s_waitcnt lgkmcnt(0)
	v_cvt_pk_bf16_f32 v3, v3, v4
	v_add_co_u32_e32 v4, vcc, 0x6000, v14
	s_nop 1
	v_addc_co_u32_e32 v5, vcc, 0, v15, vcc
	global_store_dword v[4:5], v3, off offset:3136
.LBB0_1748:
	s_or_b64 exec, exec, s[0:1]
	v_mul_f32_e32 v3, v47, v2
	s_waitcnt lgkmcnt(0)
	s_nop 1
	v_mov_b32_dpp v4, v3 quad_perm:[1,0,3,2] row_mask:0xf bank_mask:0xf
	s_and_saveexec_b64 s[0:1], s[4:5]
	s_cbranch_execz .LBB0_1750
	s_waitcnt lgkmcnt(0)
	v_cvt_pk_bf16_f32 v3, v3, v4
	v_add_co_u32_e32 v4, vcc, 0x6000, v14
	s_nop 1
	v_addc_co_u32_e32 v5, vcc, 0, v15, vcc
	global_store_dword v[4:5], v3, off offset:3200
.LBB0_1750:
	s_or_b64 exec, exec, s[0:1]
	v_mul_f32_e32 v2, v31, v2
	s_nop 1
	v_mov_b32_dpp v0, v2 quad_perm:[1,0,3,2] row_mask:0xf bank_mask:0xf
	s_and_saveexec_b64 s[0:1], s[4:5]
	s_cbranch_execz .LBB0_1610
	s_waitcnt lgkmcnt(0)
	v_cvt_pk_bf16_f32 v0, v2, v0
	v_add_co_u32_e32 v2, vcc, 0x6000, v14
	s_nop 1
	v_addc_co_u32_e32 v3, vcc, 0, v15, vcc
	global_store_dword v[2:3], v0, off offset:3264
	s_branch .LBB0_1610
